# adds: A-pass near tiles use an extended bias table in LDS (one ds_read_b32 + add per score); sub-LN gains staged in LDS for the A epilogue (stores no longer wait per chunk); gate epilogue exp2 scale f
# speedup vs baseline: 1.0186x; 1.0095x over previous
; __device__ __forceinline__ unsigned pk2(float lo, float hi) { f32x2_t v = {lo, hi}; bf16x2_t b = __builtin_convertvector(v, bf16x2_t); return __builtin_bit_cast(unsigned, b); }
; __device__ __forceinline__ float sigmoidf_(float x) { return __builtin_amdgcn_rcpf(1.0f + fexp2(-x * LOG2E)); }
;     __device__ __forceinline__ void operator()(AccRef acc, const pg8::Unit& u, int wr, int wc, int fr, int fq) const {
;     ...
;                     v[0] = sigmoidf_(acc[ai][bj][m][0][0] * rs + bv0[0]) * bflo(pw.x); v[1] = sigmoidf_(acc[ai][bj][m][0][1] * rs + bv0[1]) * bfhi(pw.x);
;                     v[2] = sigmoidf_(acc[ai][bj][m][0][2] * rs + bv0[2]) * bflo(pw.y); v[3] = sigmoidf_(acc[ai][bj][m][0][3] * rs + bv0[3]) * bfhi(pw.y);
;                     v[4] = sigmoidf_(acc[ai][bj][m][1][0] * rs + bv1[0]) * bflo(pw.z); v[5] = sigmoidf_(acc[ai][bj][m][1][1] * rs + bv1[1]) * bfhi(pw.z);
;                     v[6] = sigmoidf_(acc[ai][bj][m][1][2] * rs + bv1[2]) * bflo(pw.w); v[7] = sigmoidf_(acc[ai][bj][m][1][3] * rs + bv1[3]) * bfhi(pw.w);
;                     v[0] += bflo(tw.x); v[1] += bfhi(tw.x); v[2] += bflo(tw.y); v[3] += bfhi(tw.y);
;                     v[4] += bflo(tw.z); v[5] += bfhi(tw.z); v[6] += bflo(tw.w); v[7] += bfhi(tw.w);
;                     v4u w; w.x = pk2(v[0], v[1]); w.y = pk2(v[2], v[3]); w.z = pk2(v[4], v[5]); w.w = pk2(v[6], v[7]);
.Lgate_f:
	v_mov_b32_e32 v62, 0
	v_mov_b32_e32 v63, 0
	global_load_dwordx4 v[2:5], v224, s[6:7]
	s_add_u32 s6, s6, 0x2000
	s_addc_u32 s7, s7, 0
	global_load_dwordx4 v[10:13], v224, s[6:7]
	s_add_u32 s6, s6, 0x2000
	s_addc_u32 s7, s7, 0
	global_load_dwordx4 v[18:21], v224, s[6:7]
	s_add_u32 s6, s6, 0x2000
	s_addc_u32 s7, s7, 0
	global_load_dwordx4 v[26:29], v224, s[6:7]
	s_add_u32 s6, s6, 0x2000
	s_addc_u32 s7, s7, 0
	global_load_dwordx4 v[34:37], v224, s[6:7]
	s_add_u32 s6, s6, 0x2000
	s_addc_u32 s7, s7, 0
	global_load_dwordx4 v[42:45], v224, s[6:7]
	s_add_u32 s6, s6, 0x2000
	s_addc_u32 s7, s7, 0
	ds_read_b32 v210, v227 offset:0
	ds_read_b32 v211, v227 offset:64
	ds_read_b32 v212, v227 offset:128
	ds_read_b32 v213, v227 offset:192
	ds_read_b32 v228, v227 offset:512
	ds_read_b32 v229, v227 offset:576
	ds_read_b32 v230, v227 offset:640
	ds_read_b32 v231, v227 offset:704
	s_waitcnt lgkmcnt(0)
	v_mul_f32_e32 v210, 0xbfb8aa3b, v210
	v_mul_f32_e32 v211, 0xbfb8aa3b, v211
	v_mul_f32_e32 v212, 0xbfb8aa3b, v212
	v_mul_f32_e32 v213, 0xbfb8aa3b, v213
	v_mul_f32_e32 v228, 0xbfb8aa3b, v228
	v_mul_f32_e32 v229, 0xbfb8aa3b, v229
	v_mul_f32_e32 v230, 0xbfb8aa3b, v230
	v_mul_f32_e32 v231, 0xbfb8aa3b, v231
	s_waitcnt vmcnt(6)
	v_mul_f32_e32 v194, 0xbfb8aa3b, v194
	v_mul_f32_e32 v195, 0xbfb8aa3b, v195
	v_mul_f32_e32 v196, 0xbfb8aa3b, v196
	v_mul_f32_e32 v197, 0xbfb8aa3b, v197
	v_mul_f32_e32 v198, 0xbfb8aa3b, v198
	v_mul_f32_e32 v199, 0xbfb8aa3b, v199
	v_mul_f32_e32 v200, 0xbfb8aa3b, v200
	v_mul_f32_e32 v201, 0xbfb8aa3b, v201
	v_mul_f32_e32 v202, 0xbfb8aa3b, v202
	v_mul_f32_e32 v203, 0xbfb8aa3b, v203
	v_mul_f32_e32 v204, 0xbfb8aa3b, v204
	v_mul_f32_e32 v205, 0xbfb8aa3b, v205
	v_mul_f32_e32 v206, 0xbfb8aa3b, v206
	v_mul_f32_e32 v207, 0xbfb8aa3b, v207
	v_mul_f32_e32 v208, 0xbfb8aa3b, v208
	v_mul_f32_e32 v209, 0xbfb8aa3b, v209
	s_waitcnt vmcnt(5)
	v_fma_f32 v50, v190, v210, v194
	v_fma_f32 v51, v191, v210, v195
	v_fma_f32 v52, v192, v210, v196
	v_fma_f32 v53, v193, v210, v197
	v_fma_f32 v54, v186, v210, v198
	v_fma_f32 v55, v187, v210, v199
	v_fma_f32 v56, v188, v210, v200
	v_fma_f32 v57, v189, v210, v201
	v_exp_f32_e32 v50, v50
	v_exp_f32_e32 v51, v51
	v_exp_f32_e32 v52, v52
	v_exp_f32_e32 v53, v53
	v_exp_f32_e32 v54, v54
	v_exp_f32_e32 v55, v55
	v_exp_f32_e32 v56, v56
	v_exp_f32_e32 v57, v57
	v_add_f32_e32 v50, 1.0, v50
	v_add_f32_e32 v51, 1.0, v51
	v_add_f32_e32 v52, 1.0, v52
	v_add_f32_e32 v53, 1.0, v53
	v_add_f32_e32 v54, 1.0, v54
	v_add_f32_e32 v55, 1.0, v55
	v_add_f32_e32 v56, 1.0, v56
	v_add_f32_e32 v57, 1.0, v57
	v_rcp_f32_e32 v50, v50
	v_rcp_f32_e32 v51, v51
	v_rcp_f32_e32 v52, v52
	v_rcp_f32_e32 v53, v53
	v_rcp_f32_e32 v54, v54
	v_rcp_f32_e32 v55, v55
	v_rcp_f32_e32 v56, v56
	v_rcp_f32_e32 v57, v57
	v_lshlrev_b32_e32 v58, 16, v2
	v_and_b32_e32 v59, 0xffff0000, v2
	v_pk_fma_f32 v[50:51], v[50:51], v[58:59], v[62:63]
	v_lshlrev_b32_e32 v58, 16, v3
	v_and_b32_e32 v59, 0xffff0000, v3
	v_pk_fma_f32 v[52:53], v[52:53], v[58:59], v[62:63]
	v_lshlrev_b32_e32 v58, 16, v4
	v_and_b32_e32 v59, 0xffff0000, v4
	v_pk_fma_f32 v[54:55], v[54:55], v[58:59], v[62:63]
	v_lshlrev_b32_e32 v58, 16, v5
	v_and_b32_e32 v59, 0xffff0000, v5
	v_pk_fma_f32 v[56:57], v[56:57], v[58:59], v[62:63]
	v_cvt_pk_bf16_f32 v2, v50, v51
	v_cvt_pk_bf16_f32 v3, v52, v53
	v_cvt_pk_bf16_f32 v4, v54, v55
	v_cvt_pk_bf16_f32 v5, v56, v57
	s_cbranch_vccz .Lgate_f_m0
	global_store_dwordx4 v225, v[2:5], s[8:9]
	s_add_u32 s8, s8, 0x2000
	s_addc_u32 s9, s9, 0
	s_branch .Lgate_f_j0

; __device__ __forceinline__ unsigned pk2(float lo, float hi) { f32x2_t v = {lo, hi}; bf16x2_t b = __builtin_convertvector(v, bf16x2_t); return __builtin_bit_cast(unsigned, b); }
; __device__ __forceinline__ float sigmoidf_(float x) { return __builtin_amdgcn_rcpf(1.0f + fexp2(-x * LOG2E)); }
;     __device__ __forceinline__ void operator()(AccRef acc, const pg8::Unit& u, int wr, int wc, int fr, int fq) const {
;     ...
;                     v[0] = sigmoidf_(acc[ai][bj][m][0][0] * rs + bv0[0]) * bflo(pw.x); v[1] = sigmoidf_(acc[ai][bj][m][0][1] * rs + bv0[1]) * bfhi(pw.x);
;                     v[2] = sigmoidf_(acc[ai][bj][m][0][2] * rs + bv0[2]) * bflo(pw.y); v[3] = sigmoidf_(acc[ai][bj][m][0][3] * rs + bv0[3]) * bfhi(pw.y);
;                     v[4] = sigmoidf_(acc[ai][bj][m][1][0] * rs + bv1[0]) * bflo(pw.z); v[5] = sigmoidf_(acc[ai][bj][m][1][1] * rs + bv1[1]) * bfhi(pw.z);
;                     v[6] = sigmoidf_(acc[ai][bj][m][1][2] * rs + bv1[2]) * bflo(pw.w); v[7] = sigmoidf_(acc[ai][bj][m][1][3] * rs + bv1[3]) * bfhi(pw.w);
;                     v[0] += bflo(tw.x); v[1] += bfhi(tw.x); v[2] += bflo(tw.y); v[3] += bfhi(tw.y);
;                     v[4] += bflo(tw.z); v[5] += bfhi(tw.z); v[6] += bflo(tw.w); v[7] += bfhi(tw.w);
;                     v4u w; w.x = pk2(v[0], v[1]); w.y = pk2(v[2], v[3]); w.z = pk2(v[4], v[5]); w.w = pk2(v[6], v[7]);
.Lgate_f_j0:
	global_load_dwordx4 v[2:5], v224, s[6:7]
	s_add_u32 s6, s6, 0x2000
	s_addc_u32 s7, s7, 0
	s_waitcnt vmcnt(6)
	v_fma_f32 v50, v174, v211, v194
	v_fma_f32 v51, v175, v211, v195
	v_fma_f32 v52, v176, v211, v196
	v_fma_f32 v53, v177, v211, v197
	v_fma_f32 v54, v170, v211, v198
	v_fma_f32 v55, v171, v211, v199
	v_fma_f32 v56, v172, v211, v200
	v_fma_f32 v57, v173, v211, v201
	v_exp_f32_e32 v50, v50
	v_exp_f32_e32 v51, v51
	v_exp_f32_e32 v52, v52
	v_exp_f32_e32 v53, v53
	v_exp_f32_e32 v54, v54
	v_exp_f32_e32 v55, v55
	v_exp_f32_e32 v56, v56
	v_exp_f32_e32 v57, v57
	v_add_f32_e32 v50, 1.0, v50
	v_add_f32_e32 v51, 1.0, v51
	v_add_f32_e32 v52, 1.0, v52
	v_add_f32_e32 v53, 1.0, v53
	v_add_f32_e32 v54, 1.0, v54
	v_add_f32_e32 v55, 1.0, v55
	v_add_f32_e32 v56, 1.0, v56
	v_add_f32_e32 v57, 1.0, v57
	v_rcp_f32_e32 v50, v50
	v_rcp_f32_e32 v51, v51
	v_rcp_f32_e32 v52, v52
	v_rcp_f32_e32 v53, v53
	v_rcp_f32_e32 v54, v54
	v_rcp_f32_e32 v55, v55
	v_rcp_f32_e32 v56, v56
	v_rcp_f32_e32 v57, v57
	v_lshlrev_b32_e32 v58, 16, v10
	v_and_b32_e32 v59, 0xffff0000, v10
	v_pk_fma_f32 v[50:51], v[50:51], v[58:59], v[62:63]
	v_lshlrev_b32_e32 v58, 16, v11
	v_and_b32_e32 v59, 0xffff0000, v11
	v_pk_fma_f32 v[52:53], v[52:53], v[58:59], v[62:63]
	v_lshlrev_b32_e32 v58, 16, v12
	v_and_b32_e32 v59, 0xffff0000, v12
	v_pk_fma_f32 v[54:55], v[54:55], v[58:59], v[62:63]
	v_lshlrev_b32_e32 v58, 16, v13
	v_and_b32_e32 v59, 0xffff0000, v13
	v_pk_fma_f32 v[56:57], v[56:57], v[58:59], v[62:63]
	v_cvt_pk_bf16_f32 v10, v50, v51
	v_cvt_pk_bf16_f32 v11, v52, v53
	v_cvt_pk_bf16_f32 v12, v54, v55
	v_cvt_pk_bf16_f32 v13, v56, v57
	s_cbranch_vccz .Lgate_f_m1
	global_store_dwordx4 v225, v[10:13], s[8:9]
	s_add_u32 s8, s8, 0x2000
	s_addc_u32 s9, s9, 0
	s_branch .Lgate_f_j1

; __device__ __forceinline__ unsigned pk2(float lo, float hi) { f32x2_t v = {lo, hi}; bf16x2_t b = __builtin_convertvector(v, bf16x2_t); return __builtin_bit_cast(unsigned, b); }
; __device__ __forceinline__ float sigmoidf_(float x) { return __builtin_amdgcn_rcpf(1.0f + fexp2(-x * LOG2E)); }
;     __device__ __forceinline__ void operator()(AccRef acc, const pg8::Unit& u, int wr, int wc, int fr, int fq) const {
;     ...
;                     v[0] = sigmoidf_(acc[ai][bj][m][0][0] * rs + bv0[0]) * bflo(pw.x); v[1] = sigmoidf_(acc[ai][bj][m][0][1] * rs + bv0[1]) * bfhi(pw.x);
;                     v[2] = sigmoidf_(acc[ai][bj][m][0][2] * rs + bv0[2]) * bflo(pw.y); v[3] = sigmoidf_(acc[ai][bj][m][0][3] * rs + bv0[3]) * bfhi(pw.y);
;                     v[4] = sigmoidf_(acc[ai][bj][m][1][0] * rs + bv1[0]) * bflo(pw.z); v[5] = sigmoidf_(acc[ai][bj][m][1][1] * rs + bv1[1]) * bfhi(pw.z);
;                     v[6] = sigmoidf_(acc[ai][bj][m][1][2] * rs + bv1[2]) * bflo(pw.w); v[7] = sigmoidf_(acc[ai][bj][m][1][3] * rs + bv1[3]) * bfhi(pw.w);
;                     v[0] += bflo(tw.x); v[1] += bfhi(tw.x); v[2] += bflo(tw.y); v[3] += bfhi(tw.y);
;                     v[4] += bflo(tw.z); v[5] += bfhi(tw.z); v[6] += bflo(tw.w); v[7] += bfhi(tw.w);
;                     v4u w; w.x = pk2(v[0], v[1]); w.y = pk2(v[2], v[3]); w.z = pk2(v[4], v[5]); w.w = pk2(v[6], v[7]);
.Lgate_f_j1:
	global_load_dwordx4 v[10:13], v224, s[6:7]
	s_add_u32 s6, s6, 0x2000
	s_addc_u32 s7, s7, 0
	s_waitcnt vmcnt(7)
	v_fma_f32 v50, v158, v212, v194
	v_fma_f32 v51, v159, v212, v195
	v_fma_f32 v52, v160, v212, v196
	v_fma_f32 v53, v161, v212, v197
	v_fma_f32 v54, v154, v212, v198
	v_fma_f32 v55, v155, v212, v199
	v_fma_f32 v56, v156, v212, v200
	v_fma_f32 v57, v157, v212, v201
	v_exp_f32_e32 v50, v50
	v_exp_f32_e32 v51, v51
	v_exp_f32_e32 v52, v52
	v_exp_f32_e32 v53, v53
	v_exp_f32_e32 v54, v54
	v_exp_f32_e32 v55, v55
	v_exp_f32_e32 v56, v56
	v_exp_f32_e32 v57, v57
	v_add_f32_e32 v50, 1.0, v50
	v_add_f32_e32 v51, 1.0, v51
	v_add_f32_e32 v52, 1.0, v52
	v_add_f32_e32 v53, 1.0, v53
	v_add_f32_e32 v54, 1.0, v54
	v_add_f32_e32 v55, 1.0, v55
	v_add_f32_e32 v56, 1.0, v56
	v_add_f32_e32 v57, 1.0, v57
	v_rcp_f32_e32 v50, v50
	v_rcp_f32_e32 v51, v51
	v_rcp_f32_e32 v52, v52
	v_rcp_f32_e32 v53, v53
	v_rcp_f32_e32 v54, v54
	v_rcp_f32_e32 v55, v55
	v_rcp_f32_e32 v56, v56
	v_rcp_f32_e32 v57, v57
	v_lshlrev_b32_e32 v58, 16, v18
	v_and_b32_e32 v59, 0xffff0000, v18
	v_pk_fma_f32 v[50:51], v[50:51], v[58:59], v[62:63]
	v_lshlrev_b32_e32 v58, 16, v19
	v_and_b32_e32 v59, 0xffff0000, v19
	v_pk_fma_f32 v[52:53], v[52:53], v[58:59], v[62:63]
	v_lshlrev_b32_e32 v58, 16, v20
	v_and_b32_e32 v59, 0xffff0000, v20
	v_pk_fma_f32 v[54:55], v[54:55], v[58:59], v[62:63]
	v_lshlrev_b32_e32 v58, 16, v21
	v_and_b32_e32 v59, 0xffff0000, v21
	v_pk_fma_f32 v[56:57], v[56:57], v[58:59], v[62:63]
	v_cvt_pk_bf16_f32 v18, v50, v51
	v_cvt_pk_bf16_f32 v19, v52, v53
	v_cvt_pk_bf16_f32 v20, v54, v55
	v_cvt_pk_bf16_f32 v21, v56, v57
	s_cbranch_vccz .Lgate_f_m2
	global_store_dwordx4 v225, v[18:21], s[8:9]
	s_add_u32 s8, s8, 0x2000
	s_addc_u32 s9, s9, 0
	s_branch .Lgate_f_j2

; __device__ __forceinline__ unsigned pk2(float lo, float hi) { f32x2_t v = {lo, hi}; bf16x2_t b = __builtin_convertvector(v, bf16x2_t); return __builtin_bit_cast(unsigned, b); }
; __device__ __forceinline__ float sigmoidf_(float x) { return __builtin_amdgcn_rcpf(1.0f + fexp2(-x * LOG2E)); }
;     __device__ __forceinline__ void operator()(AccRef acc, const pg8::Unit& u, int wr, int wc, int fr, int fq) const {
;     ...
;                     v[0] = sigmoidf_(acc[ai][bj][m][0][0] * rs + bv0[0]) * bflo(pw.x); v[1] = sigmoidf_(acc[ai][bj][m][0][1] * rs + bv0[1]) * bfhi(pw.x);
;                     v[2] = sigmoidf_(acc[ai][bj][m][0][2] * rs + bv0[2]) * bflo(pw.y); v[3] = sigmoidf_(acc[ai][bj][m][0][3] * rs + bv0[3]) * bfhi(pw.y);
;                     v[4] = sigmoidf_(acc[ai][bj][m][1][0] * rs + bv1[0]) * bflo(pw.z); v[5] = sigmoidf_(acc[ai][bj][m][1][1] * rs + bv1[1]) * bfhi(pw.z);
;                     v[6] = sigmoidf_(acc[ai][bj][m][1][2] * rs + bv1[2]) * bflo(pw.w); v[7] = sigmoidf_(acc[ai][bj][m][1][3] * rs + bv1[3]) * bfhi(pw.w);
;                     v[0] += bflo(tw.x); v[1] += bfhi(tw.x); v[2] += bflo(tw.y); v[3] += bfhi(tw.y);
;                     v[4] += bflo(tw.z); v[5] += bfhi(tw.z); v[6] += bflo(tw.w); v[7] += bfhi(tw.w);
;                     v4u w; w.x = pk2(v[0], v[1]); w.y = pk2(v[2], v[3]); w.z = pk2(v[4], v[5]); w.w = pk2(v[6], v[7]);
.Lgate_f_j2:
	global_load_dwordx4 v[18:21], v224, s[6:7]
	s_add_u32 s6, s6, 0x2000
	s_addc_u32 s7, s7, 0
	s_waitcnt vmcnt(8)
	v_fma_f32 v50, v142, v213, v194
	v_fma_f32 v51, v143, v213, v195
	v_fma_f32 v52, v144, v213, v196
	v_fma_f32 v53, v145, v213, v197
	v_fma_f32 v54, v138, v213, v198
	v_fma_f32 v55, v139, v213, v199
	v_fma_f32 v56, v140, v213, v200
	v_fma_f32 v57, v141, v213, v201
	v_exp_f32_e32 v50, v50
	v_exp_f32_e32 v51, v51
	v_exp_f32_e32 v52, v52
	v_exp_f32_e32 v53, v53
	v_exp_f32_e32 v54, v54
	v_exp_f32_e32 v55, v55
	v_exp_f32_e32 v56, v56
	v_exp_f32_e32 v57, v57
	v_add_f32_e32 v50, 1.0, v50
	v_add_f32_e32 v51, 1.0, v51
	v_add_f32_e32 v52, 1.0, v52
	v_add_f32_e32 v53, 1.0, v53
	v_add_f32_e32 v54, 1.0, v54
	v_add_f32_e32 v55, 1.0, v55
	v_add_f32_e32 v56, 1.0, v56
	v_add_f32_e32 v57, 1.0, v57
	v_rcp_f32_e32 v50, v50
	v_rcp_f32_e32 v51, v51
	v_rcp_f32_e32 v52, v52
	v_rcp_f32_e32 v53, v53
	v_rcp_f32_e32 v54, v54
	v_rcp_f32_e32 v55, v55
	v_rcp_f32_e32 v56, v56
	v_rcp_f32_e32 v57, v57
	v_lshlrev_b32_e32 v58, 16, v26
	v_and_b32_e32 v59, 0xffff0000, v26
	v_pk_fma_f32 v[50:51], v[50:51], v[58:59], v[62:63]
	v_lshlrev_b32_e32 v58, 16, v27
	v_and_b32_e32 v59, 0xffff0000, v27
	v_pk_fma_f32 v[52:53], v[52:53], v[58:59], v[62:63]
	v_lshlrev_b32_e32 v58, 16, v28
	v_and_b32_e32 v59, 0xffff0000, v28
	v_pk_fma_f32 v[54:55], v[54:55], v[58:59], v[62:63]
	v_lshlrev_b32_e32 v58, 16, v29
	v_and_b32_e32 v59, 0xffff0000, v29
	v_pk_fma_f32 v[56:57], v[56:57], v[58:59], v[62:63]
	v_cvt_pk_bf16_f32 v26, v50, v51
	v_cvt_pk_bf16_f32 v27, v52, v53
	v_cvt_pk_bf16_f32 v28, v54, v55
	v_cvt_pk_bf16_f32 v29, v56, v57
	s_cbranch_vccz .Lgate_f_m3
	global_store_dwordx4 v225, v[26:29], s[8:9]
	s_add_u32 s8, s8, 0x2000
	s_addc_u32 s9, s9, 0
	s_branch .Lgate_f_j3

; __device__ __forceinline__ unsigned pk2(float lo, float hi) { f32x2_t v = {lo, hi}; bf16x2_t b = __builtin_convertvector(v, bf16x2_t); return __builtin_bit_cast(unsigned, b); }
; __device__ __forceinline__ float sigmoidf_(float x) { return __builtin_amdgcn_rcpf(1.0f + fexp2(-x * LOG2E)); }
;     __device__ __forceinline__ void operator()(AccRef acc, const pg8::Unit& u, int wr, int wc, int fr, int fq) const {
;     ...
;                     v[0] = sigmoidf_(acc[ai][bj][m][0][0] * rs + bv0[0]) * bflo(pw.x); v[1] = sigmoidf_(acc[ai][bj][m][0][1] * rs + bv0[1]) * bfhi(pw.x);
;                     v[2] = sigmoidf_(acc[ai][bj][m][0][2] * rs + bv0[2]) * bflo(pw.y); v[3] = sigmoidf_(acc[ai][bj][m][0][3] * rs + bv0[3]) * bfhi(pw.y);
;                     v[4] = sigmoidf_(acc[ai][bj][m][1][0] * rs + bv1[0]) * bflo(pw.z); v[5] = sigmoidf_(acc[ai][bj][m][1][1] * rs + bv1[1]) * bfhi(pw.z);
;                     v[6] = sigmoidf_(acc[ai][bj][m][1][2] * rs + bv1[2]) * bflo(pw.w); v[7] = sigmoidf_(acc[ai][bj][m][1][3] * rs + bv1[3]) * bfhi(pw.w);
;                     v[0] += bflo(tw.x); v[1] += bfhi(tw.x); v[2] += bflo(tw.y); v[3] += bfhi(tw.y);
;                     v[4] += bflo(tw.z); v[5] += bfhi(tw.z); v[6] += bflo(tw.w); v[7] += bfhi(tw.w);
;                     v4u w; w.x = pk2(v[0], v[1]); w.y = pk2(v[2], v[3]); w.z = pk2(v[4], v[5]); w.w = pk2(v[6], v[7]);
.Lgate_f_j3:
	global_load_dwordx4 v[26:29], v224, s[6:7]
	s_add_u32 s6, s6, 0x2000
	s_addc_u32 s7, s7, 0
	s_waitcnt vmcnt(9)
	v_fma_f32 v50, v182, v210, v202
	v_fma_f32 v51, v183, v210, v203
	v_fma_f32 v52, v184, v210, v204
	v_fma_f32 v53, v185, v210, v205
	v_fma_f32 v54, v178, v210, v206
	v_fma_f32 v55, v179, v210, v207
	v_fma_f32 v56, v180, v210, v208
	v_fma_f32 v57, v181, v210, v209
	v_exp_f32_e32 v50, v50
	v_exp_f32_e32 v51, v51
	v_exp_f32_e32 v52, v52
	v_exp_f32_e32 v53, v53
	v_exp_f32_e32 v54, v54
	v_exp_f32_e32 v55, v55
	v_exp_f32_e32 v56, v56
	v_exp_f32_e32 v57, v57
	v_add_f32_e32 v50, 1.0, v50
	v_add_f32_e32 v51, 1.0, v51
	v_add_f32_e32 v52, 1.0, v52
	v_add_f32_e32 v53, 1.0, v53
	v_add_f32_e32 v54, 1.0, v54
	v_add_f32_e32 v55, 1.0, v55
	v_add_f32_e32 v56, 1.0, v56
	v_add_f32_e32 v57, 1.0, v57
	v_rcp_f32_e32 v50, v50
	v_rcp_f32_e32 v51, v51
	v_rcp_f32_e32 v52, v52
	v_rcp_f32_e32 v53, v53
	v_rcp_f32_e32 v54, v54
	v_rcp_f32_e32 v55, v55
	v_rcp_f32_e32 v56, v56
	v_rcp_f32_e32 v57, v57
	v_lshlrev_b32_e32 v58, 16, v34
	v_and_b32_e32 v59, 0xffff0000, v34
	v_pk_fma_f32 v[50:51], v[50:51], v[58:59], v[62:63]
	v_lshlrev_b32_e32 v58, 16, v35
	v_and_b32_e32 v59, 0xffff0000, v35
	v_pk_fma_f32 v[52:53], v[52:53], v[58:59], v[62:63]
	v_lshlrev_b32_e32 v58, 16, v36
	v_and_b32_e32 v59, 0xffff0000, v36
	v_pk_fma_f32 v[54:55], v[54:55], v[58:59], v[62:63]
	v_lshlrev_b32_e32 v58, 16, v37
	v_and_b32_e32 v59, 0xffff0000, v37
	v_pk_fma_f32 v[56:57], v[56:57], v[58:59], v[62:63]
	v_cvt_pk_bf16_f32 v34, v50, v51
	v_cvt_pk_bf16_f32 v35, v52, v53
	v_cvt_pk_bf16_f32 v36, v54, v55
	v_cvt_pk_bf16_f32 v37, v56, v57
	s_cbranch_vccz .Lgate_f_m4
	global_store_dwordx4 v225, v[34:37], s[8:9]
	s_add_u32 s8, s8, 0x2000
	s_addc_u32 s9, s9, 0
	s_branch .Lgate_f_j4

; __device__ __forceinline__ unsigned pk2(float lo, float hi) { f32x2_t v = {lo, hi}; bf16x2_t b = __builtin_convertvector(v, bf16x2_t); return __builtin_bit_cast(unsigned, b); }
; __device__ __forceinline__ float sigmoidf_(float x) { return __builtin_amdgcn_rcpf(1.0f + fexp2(-x * LOG2E)); }
;     __device__ __forceinline__ void operator()(AccRef acc, const pg8::Unit& u, int wr, int wc, int fr, int fq) const {
;     ...
;                     v[0] = sigmoidf_(acc[ai][bj][m][0][0] * rs + bv0[0]) * bflo(pw.x); v[1] = sigmoidf_(acc[ai][bj][m][0][1] * rs + bv0[1]) * bfhi(pw.x);
;                     v[2] = sigmoidf_(acc[ai][bj][m][0][2] * rs + bv0[2]) * bflo(pw.y); v[3] = sigmoidf_(acc[ai][bj][m][0][3] * rs + bv0[3]) * bfhi(pw.y);
;                     v[4] = sigmoidf_(acc[ai][bj][m][1][0] * rs + bv1[0]) * bflo(pw.z); v[5] = sigmoidf_(acc[ai][bj][m][1][1] * rs + bv1[1]) * bfhi(pw.z);
;                     v[6] = sigmoidf_(acc[ai][bj][m][1][2] * rs + bv1[2]) * bflo(pw.w); v[7] = sigmoidf_(acc[ai][bj][m][1][3] * rs + bv1[3]) * bfhi(pw.w);
;                     v[0] += bflo(tw.x); v[1] += bfhi(tw.x); v[2] += bflo(tw.y); v[3] += bfhi(tw.y);
;                     v[4] += bflo(tw.z); v[5] += bfhi(tw.z); v[6] += bflo(tw.w); v[7] += bfhi(tw.w);
;                     v4u w; w.x = pk2(v[0], v[1]); w.y = pk2(v[2], v[3]); w.z = pk2(v[4], v[5]); w.w = pk2(v[6], v[7]);
.Lgate_f_j4:
	global_load_dwordx4 v[34:37], v224, s[6:7]
	s_add_u32 s6, s6, 0x2000
	s_addc_u32 s7, s7, 0
	s_waitcnt vmcnt(10)
	v_fma_f32 v50, v166, v211, v202
	v_fma_f32 v51, v167, v211, v203
	v_fma_f32 v52, v168, v211, v204
	v_fma_f32 v53, v169, v211, v205
	v_fma_f32 v54, v162, v211, v206
	v_fma_f32 v55, v163, v211, v207
	v_fma_f32 v56, v164, v211, v208
	v_fma_f32 v57, v165, v211, v209
	v_exp_f32_e32 v50, v50
	v_exp_f32_e32 v51, v51
	v_exp_f32_e32 v52, v52
	v_exp_f32_e32 v53, v53
	v_exp_f32_e32 v54, v54
	v_exp_f32_e32 v55, v55
	v_exp_f32_e32 v56, v56
	v_exp_f32_e32 v57, v57
	v_add_f32_e32 v50, 1.0, v50
	v_add_f32_e32 v51, 1.0, v51
	v_add_f32_e32 v52, 1.0, v52
	v_add_f32_e32 v53, 1.0, v53
	v_add_f32_e32 v54, 1.0, v54
	v_add_f32_e32 v55, 1.0, v55
	v_add_f32_e32 v56, 1.0, v56
	v_add_f32_e32 v57, 1.0, v57
	v_rcp_f32_e32 v50, v50
	v_rcp_f32_e32 v51, v51
	v_rcp_f32_e32 v52, v52
	v_rcp_f32_e32 v53, v53
	v_rcp_f32_e32 v54, v54
	v_rcp_f32_e32 v55, v55
	v_rcp_f32_e32 v56, v56
	v_rcp_f32_e32 v57, v57
	v_lshlrev_b32_e32 v58, 16, v42
	v_and_b32_e32 v59, 0xffff0000, v42
	v_pk_fma_f32 v[50:51], v[50:51], v[58:59], v[62:63]
	v_lshlrev_b32_e32 v58, 16, v43
	v_and_b32_e32 v59, 0xffff0000, v43
	v_pk_fma_f32 v[52:53], v[52:53], v[58:59], v[62:63]
	v_lshlrev_b32_e32 v58, 16, v44
	v_and_b32_e32 v59, 0xffff0000, v44
	v_pk_fma_f32 v[54:55], v[54:55], v[58:59], v[62:63]
	v_lshlrev_b32_e32 v58, 16, v45
	v_and_b32_e32 v59, 0xffff0000, v45
	v_pk_fma_f32 v[56:57], v[56:57], v[58:59], v[62:63]
	v_cvt_pk_bf16_f32 v42, v50, v51
	v_cvt_pk_bf16_f32 v43, v52, v53
	v_cvt_pk_bf16_f32 v44, v54, v55
	v_cvt_pk_bf16_f32 v45, v56, v57
	s_cbranch_vccz .Lgate_f_m5
	global_store_dwordx4 v225, v[42:45], s[8:9]
	s_add_u32 s8, s8, 0x2000
	s_addc_u32 s9, s9, 0
	s_branch .Lgate_f_j5

; __device__ __forceinline__ unsigned pk2(float lo, float hi) { f32x2_t v = {lo, hi}; bf16x2_t b = __builtin_convertvector(v, bf16x2_t); return __builtin_bit_cast(unsigned, b); }
; __device__ __forceinline__ float sigmoidf_(float x) { return __builtin_amdgcn_rcpf(1.0f + fexp2(-x * LOG2E)); }
;     __device__ __forceinline__ void operator()(AccRef acc, const pg8::Unit& u, int wr, int wc, int fr, int fq) const {
;     ...
;                     v[0] = sigmoidf_(acc[ai][bj][m][0][0] * rs + bv0[0]) * bflo(pw.x); v[1] = sigmoidf_(acc[ai][bj][m][0][1] * rs + bv0[1]) * bfhi(pw.x);
;                     v[2] = sigmoidf_(acc[ai][bj][m][0][2] * rs + bv0[2]) * bflo(pw.y); v[3] = sigmoidf_(acc[ai][bj][m][0][3] * rs + bv0[3]) * bfhi(pw.y);
;                     v[4] = sigmoidf_(acc[ai][bj][m][1][0] * rs + bv1[0]) * bflo(pw.z); v[5] = sigmoidf_(acc[ai][bj][m][1][1] * rs + bv1[1]) * bfhi(pw.z);
;                     v[6] = sigmoidf_(acc[ai][bj][m][1][2] * rs + bv1[2]) * bflo(pw.w); v[7] = sigmoidf_(acc[ai][bj][m][1][3] * rs + bv1[3]) * bfhi(pw.w);
;                     v[0] += bflo(tw.x); v[1] += bfhi(tw.x); v[2] += bflo(tw.y); v[3] += bfhi(tw.y);
;                     v[4] += bflo(tw.z); v[5] += bfhi(tw.z); v[6] += bflo(tw.w); v[7] += bfhi(tw.w);
;                     v4u w; w.x = pk2(v[0], v[1]); w.y = pk2(v[2], v[3]); w.z = pk2(v[4], v[5]); w.w = pk2(v[6], v[7]);
.Lgate_f_j5:
	global_load_dwordx4 v[42:45], v224, s[6:7]
	s_add_u32 s6, s6, 0x2000
	s_addc_u32 s7, s7, 0
	s_waitcnt vmcnt(10)
	v_fma_f32 v50, v150, v212, v202
	v_fma_f32 v51, v151, v212, v203
	v_fma_f32 v52, v152, v212, v204
	v_fma_f32 v53, v153, v212, v205
	v_fma_f32 v54, v146, v212, v206
	v_fma_f32 v55, v147, v212, v207
	v_fma_f32 v56, v148, v212, v208
	v_fma_f32 v57, v149, v212, v209
	v_exp_f32_e32 v50, v50
	v_exp_f32_e32 v51, v51
	v_exp_f32_e32 v52, v52
	v_exp_f32_e32 v53, v53
	v_exp_f32_e32 v54, v54
	v_exp_f32_e32 v55, v55
	v_exp_f32_e32 v56, v56
	v_exp_f32_e32 v57, v57
	v_add_f32_e32 v50, 1.0, v50
	v_add_f32_e32 v51, 1.0, v51
	v_add_f32_e32 v52, 1.0, v52
	v_add_f32_e32 v53, 1.0, v53
	v_add_f32_e32 v54, 1.0, v54
	v_add_f32_e32 v55, 1.0, v55
	v_add_f32_e32 v56, 1.0, v56
	v_add_f32_e32 v57, 1.0, v57
	v_rcp_f32_e32 v50, v50
	v_rcp_f32_e32 v51, v51
	v_rcp_f32_e32 v52, v52
	v_rcp_f32_e32 v53, v53
	v_rcp_f32_e32 v54, v54
	v_rcp_f32_e32 v55, v55
	v_rcp_f32_e32 v56, v56
	v_rcp_f32_e32 v57, v57
	v_lshlrev_b32_e32 v58, 16, v2
	v_and_b32_e32 v59, 0xffff0000, v2
	v_pk_fma_f32 v[50:51], v[50:51], v[58:59], v[62:63]
	v_lshlrev_b32_e32 v58, 16, v3
	v_and_b32_e32 v59, 0xffff0000, v3
	v_pk_fma_f32 v[52:53], v[52:53], v[58:59], v[62:63]
	v_lshlrev_b32_e32 v58, 16, v4
	v_and_b32_e32 v59, 0xffff0000, v4
	v_pk_fma_f32 v[54:55], v[54:55], v[58:59], v[62:63]
	v_lshlrev_b32_e32 v58, 16, v5
	v_and_b32_e32 v59, 0xffff0000, v5
	v_pk_fma_f32 v[56:57], v[56:57], v[58:59], v[62:63]
	v_cvt_pk_bf16_f32 v2, v50, v51
	v_cvt_pk_bf16_f32 v3, v52, v53
	v_cvt_pk_bf16_f32 v4, v54, v55
	v_cvt_pk_bf16_f32 v5, v56, v57
	s_cbranch_vccz .Lgate_f_m6
	global_store_dwordx4 v225, v[2:5], s[8:9]
	s_add_u32 s8, s8, 0x2000
	s_addc_u32 s9, s9, 0
	s_branch .Lgate_f_j6

; __device__ __forceinline__ unsigned pk2(float lo, float hi) { f32x2_t v = {lo, hi}; bf16x2_t b = __builtin_convertvector(v, bf16x2_t); return __builtin_bit_cast(unsigned, b); }
; __device__ __forceinline__ float sigmoidf_(float x) { return __builtin_amdgcn_rcpf(1.0f + fexp2(-x * LOG2E)); }
;     __device__ __forceinline__ void operator()(AccRef acc, const pg8::Unit& u, int wr, int wc, int fr, int fq) const {
;     ...
;                 for (int m = 0; m < 4; ++m) {
;                     const size_t ci = ub + (size_t)((ai * 2 + bj) * 4 + m) * NTHREADS;
;                     const v4u pw = pw4[m], tw = tw4[m];
;                     const float rs = rst[(row0 + ai * 128 + m * 16) & 255];
;                     float v[8];
;                     v[0] = sigmoidf_(acc[ai][bj][m][0][0] * rs + bv0[0]) * bflo(pw.x); v[1] = sigmoidf_(acc[ai][bj][m][0][1] * rs + bv0[1]) * bfhi(pw.x);
;                     v[2] = sigmoidf_(acc[ai][bj][m][0][2] * rs + bv0[2]) * bflo(pw.y); v[3] = sigmoidf_(acc[ai][bj][m][0][3] * rs + bv0[3]) * bfhi(pw.y);
;                     v[4] = sigmoidf_(acc[ai][bj][m][1][0] * rs + bv1[0]) * bflo(pw.z); v[5] = sigmoidf_(acc[ai][bj][m][1][1] * rs + bv1[1]) * bfhi(pw.z);
;                     v[6] = sigmoidf_(acc[ai][bj][m][1][2] * rs + bv1[2]) * bflo(pw.w); v[7] = sigmoidf_(acc[ai][bj][m][1][3] * rs + bv1[3]) * bfhi(pw.w);
;                     v[0] += bflo(tw.x); v[1] += bfhi(tw.x); v[2] += bflo(tw.y); v[3] += bfhi(tw.y);
;                     v[4] += bflo(tw.z); v[5] += bfhi(tw.z); v[6] += bflo(tw.w); v[7] += bfhi(tw.w);
;                     v4u w; w.x = pk2(v[0], v[1]); w.y = pk2(v[2], v[3]); w.z = pk2(v[4], v[5]); w.w = pk2(v[6], v[7]);
;                     if (!last) TMP[ci] = w;
;                     else *(v4u*)(MRG + (size_t)(row0 + ai * 128 + m * 16) * D + col0 + bj * 128) = w;
.Lgate_f_j6:
	global_load_dwordx4 v[2:5], v224, s[6:7]
	s_add_u32 s6, s6, 0x2000
	s_addc_u32 s7, s7, 0
	s_waitcnt vmcnt(10)
	v_fma_f32 v50, v134, v213, v202
	v_fma_f32 v51, v135, v213, v203
	v_fma_f32 v52, v136, v213, v204
	v_fma_f32 v53, v137, v213, v205
	v_fma_f32 v54, v130, v213, v206
	v_fma_f32 v55, v131, v213, v207
	v_fma_f32 v56, v132, v213, v208
	v_fma_f32 v57, v133, v213, v209
	v_exp_f32_e32 v50, v50
	v_exp_f32_e32 v51, v51
	v_exp_f32_e32 v52, v52
	v_exp_f32_e32 v53, v53
	v_exp_f32_e32 v54, v54
	v_exp_f32_e32 v55, v55
	v_exp_f32_e32 v56, v56
	v_exp_f32_e32 v57, v57
	v_add_f32_e32 v50, 1.0, v50
	v_add_f32_e32 v51, 1.0, v51
	v_add_f32_e32 v52, 1.0, v52
	v_add_f32_e32 v53, 1.0, v53
	v_add_f32_e32 v54, 1.0, v54
	v_add_f32_e32 v55, 1.0, v55
	v_add_f32_e32 v56, 1.0, v56
	v_add_f32_e32 v57, 1.0, v57
	v_rcp_f32_e32 v50, v50
	v_rcp_f32_e32 v51, v51
	v_rcp_f32_e32 v52, v52
	v_rcp_f32_e32 v53, v53
	v_rcp_f32_e32 v54, v54
	v_rcp_f32_e32 v55, v55
	v_rcp_f32_e32 v56, v56
	v_rcp_f32_e32 v57, v57
	v_lshlrev_b32_e32 v58, 16, v10
	v_and_b32_e32 v59, 0xffff0000, v10
	v_pk_fma_f32 v[50:51], v[50:51], v[58:59], v[62:63]
	v_lshlrev_b32_e32 v58, 16, v11
	v_and_b32_e32 v59, 0xffff0000, v11
	v_pk_fma_f32 v[52:53], v[52:53], v[58:59], v[62:63]
	v_lshlrev_b32_e32 v58, 16, v12
	v_and_b32_e32 v59, 0xffff0000, v12
	v_pk_fma_f32 v[54:55], v[54:55], v[58:59], v[62:63]
	v_lshlrev_b32_e32 v58, 16, v13
	v_and_b32_e32 v59, 0xffff0000, v13
	v_pk_fma_f32 v[56:57], v[56:57], v[58:59], v[62:63]
	v_cvt_pk_bf16_f32 v10, v50, v51
	v_cvt_pk_bf16_f32 v11, v52, v53
	v_cvt_pk_bf16_f32 v12, v54, v55
	v_cvt_pk_bf16_f32 v13, v56, v57
	s_cbranch_vccz .Lgate_f_m7
	global_store_dwordx4 v225, v[10:13], s[8:9]
	s_add_u32 s8, s8, 0x2000
	s_addc_u32 s9, s9, 0
	s_branch .Lgate_f_j7

; __device__ __forceinline__ unsigned pk2(float lo, float hi) { f32x2_t v = {lo, hi}; bf16x2_t b = __builtin_convertvector(v, bf16x2_t); return __builtin_bit_cast(unsigned, b); }
; __device__ __forceinline__ float sigmoidf_(float x) { return __builtin_amdgcn_rcpf(1.0f + fexp2(-x * LOG2E)); }
;     __device__ __forceinline__ void operator()(AccRef acc, const pg8::Unit& u, int wr, int wc, int fr, int fq) const {
;     ...
;                 for (int m = 0; m < 4; ++m) {
;                     const size_t ci = ub + (size_t)((ai * 2 + bj) * 4 + m) * NTHREADS;
;                     const v4u pw = pw4[m], tw = tw4[m];
;                     const float rs = rst[(row0 + ai * 128 + m * 16) & 255];
;                     float v[8];
;                     v[0] = sigmoidf_(acc[ai][bj][m][0][0] * rs + bv0[0]) * bflo(pw.x); v[1] = sigmoidf_(acc[ai][bj][m][0][1] * rs + bv0[1]) * bfhi(pw.x);
;                     v[2] = sigmoidf_(acc[ai][bj][m][0][2] * rs + bv0[2]) * bflo(pw.y); v[3] = sigmoidf_(acc[ai][bj][m][0][3] * rs + bv0[3]) * bfhi(pw.y);
;                     v[4] = sigmoidf_(acc[ai][bj][m][1][0] * rs + bv1[0]) * bflo(pw.z); v[5] = sigmoidf_(acc[ai][bj][m][1][1] * rs + bv1[1]) * bfhi(pw.z);
;                     v[6] = sigmoidf_(acc[ai][bj][m][1][2] * rs + bv1[2]) * bflo(pw.w); v[7] = sigmoidf_(acc[ai][bj][m][1][3] * rs + bv1[3]) * bfhi(pw.w);
;                     v[0] += bflo(tw.x); v[1] += bfhi(tw.x); v[2] += bflo(tw.y); v[3] += bfhi(tw.y);
;                     v[4] += bflo(tw.z); v[5] += bfhi(tw.z); v[6] += bflo(tw.w); v[7] += bfhi(tw.w);
;                     v4u w; w.x = pk2(v[0], v[1]); w.y = pk2(v[2], v[3]); w.z = pk2(v[4], v[5]); w.w = pk2(v[6], v[7]);
;                     if (!last) TMP[ci] = w;
;                     else *(v4u*)(MRG + (size_t)(row0 + ai * 128 + m * 16) * D + col0 + bj * 128) = w;
.Lgate_f_j7:
	global_load_dwordx4 v[10:13], v224, s[6:7]
	s_add_u32 s6, s6, 0x2000
	s_addc_u32 s7, s7, 0
	s_waitcnt vmcnt(10)
	v_fma_f32 v50, v126, v228, v194
	v_fma_f32 v51, v127, v228, v195
	v_fma_f32 v52, v128, v228, v196
	v_fma_f32 v53, v129, v228, v197
	v_fma_f32 v54, v122, v228, v198
	v_fma_f32 v55, v123, v228, v199
	v_fma_f32 v56, v124, v228, v200
	v_fma_f32 v57, v125, v228, v201
	v_exp_f32_e32 v50, v50
	v_exp_f32_e32 v51, v51
	v_exp_f32_e32 v52, v52
	v_exp_f32_e32 v53, v53
	v_exp_f32_e32 v54, v54
	v_exp_f32_e32 v55, v55
	v_exp_f32_e32 v56, v56
	v_exp_f32_e32 v57, v57
	v_add_f32_e32 v50, 1.0, v50
	v_add_f32_e32 v51, 1.0, v51
	v_add_f32_e32 v52, 1.0, v52
	v_add_f32_e32 v53, 1.0, v53
	v_add_f32_e32 v54, 1.0, v54
	v_add_f32_e32 v55, 1.0, v55
	v_add_f32_e32 v56, 1.0, v56
	v_add_f32_e32 v57, 1.0, v57
	v_rcp_f32_e32 v50, v50
	v_rcp_f32_e32 v51, v51
	v_rcp_f32_e32 v52, v52
	v_rcp_f32_e32 v53, v53
	v_rcp_f32_e32 v54, v54
	v_rcp_f32_e32 v55, v55
	v_rcp_f32_e32 v56, v56
	v_rcp_f32_e32 v57, v57
	v_lshlrev_b32_e32 v58, 16, v18
	v_and_b32_e32 v59, 0xffff0000, v18
	v_pk_fma_f32 v[50:51], v[50:51], v[58:59], v[62:63]
	v_lshlrev_b32_e32 v58, 16, v19
	v_and_b32_e32 v59, 0xffff0000, v19
	v_pk_fma_f32 v[52:53], v[52:53], v[58:59], v[62:63]
	v_lshlrev_b32_e32 v58, 16, v20
	v_and_b32_e32 v59, 0xffff0000, v20
	v_pk_fma_f32 v[54:55], v[54:55], v[58:59], v[62:63]
	v_lshlrev_b32_e32 v58, 16, v21
	v_and_b32_e32 v59, 0xffff0000, v21
	v_pk_fma_f32 v[56:57], v[56:57], v[58:59], v[62:63]
	v_cvt_pk_bf16_f32 v18, v50, v51
	v_cvt_pk_bf16_f32 v19, v52, v53
	v_cvt_pk_bf16_f32 v20, v54, v55
	v_cvt_pk_bf16_f32 v21, v56, v57
	s_cbranch_vccz .Lgate_f_m8
	global_store_dwordx4 v225, v[18:21], s[8:9]
	s_add_u32 s8, s8, 0x2000
	s_addc_u32 s9, s9, 0
	s_branch .Lgate_f_j8

; __device__ __forceinline__ unsigned pk2(float lo, float hi) { f32x2_t v = {lo, hi}; bf16x2_t b = __builtin_convertvector(v, bf16x2_t); return __builtin_bit_cast(unsigned, b); }
; __device__ __forceinline__ float sigmoidf_(float x) { return __builtin_amdgcn_rcpf(1.0f + fexp2(-x * LOG2E)); }
;     __device__ __forceinline__ void operator()(AccRef acc, const pg8::Unit& u, int wr, int wc, int fr, int fq) const {
;     ...
;                 for (int m = 0; m < 4; ++m) {
;                     const size_t ci = ub + (size_t)((ai * 2 + bj) * 4 + m) * NTHREADS;
;                     const v4u pw = pw4[m], tw = tw4[m];
;                     const float rs = rst[(row0 + ai * 128 + m * 16) & 255];
;                     float v[8];
;                     v[0] = sigmoidf_(acc[ai][bj][m][0][0] * rs + bv0[0]) * bflo(pw.x); v[1] = sigmoidf_(acc[ai][bj][m][0][1] * rs + bv0[1]) * bfhi(pw.x);
;                     v[2] = sigmoidf_(acc[ai][bj][m][0][2] * rs + bv0[2]) * bflo(pw.y); v[3] = sigmoidf_(acc[ai][bj][m][0][3] * rs + bv0[3]) * bfhi(pw.y);
;                     v[4] = sigmoidf_(acc[ai][bj][m][1][0] * rs + bv1[0]) * bflo(pw.z); v[5] = sigmoidf_(acc[ai][bj][m][1][1] * rs + bv1[1]) * bfhi(pw.z);
;                     v[6] = sigmoidf_(acc[ai][bj][m][1][2] * rs + bv1[2]) * bflo(pw.w); v[7] = sigmoidf_(acc[ai][bj][m][1][3] * rs + bv1[3]) * bfhi(pw.w);
;                     v[0] += bflo(tw.x); v[1] += bfhi(tw.x); v[2] += bflo(tw.y); v[3] += bfhi(tw.y);
;                     v[4] += bflo(tw.z); v[5] += bfhi(tw.z); v[6] += bflo(tw.w); v[7] += bfhi(tw.w);
;                     v4u w; w.x = pk2(v[0], v[1]); w.y = pk2(v[2], v[3]); w.z = pk2(v[4], v[5]); w.w = pk2(v[6], v[7]);
;                     if (!last) TMP[ci] = w;
;                     else *(v4u*)(MRG + (size_t)(row0 + ai * 128 + m * 16) * D + col0 + bj * 128) = w;
.Lgate_f_j8:
	global_load_dwordx4 v[18:21], v224, s[6:7]
	s_add_u32 s6, s6, 0x2000
	s_addc_u32 s7, s7, 0
	s_waitcnt vmcnt(10)
	v_fma_f32 v50, v110, v229, v194
	v_fma_f32 v51, v111, v229, v195
	v_fma_f32 v52, v112, v229, v196
	v_fma_f32 v53, v113, v229, v197
	v_fma_f32 v54, v106, v229, v198
	v_fma_f32 v55, v107, v229, v199
	v_fma_f32 v56, v108, v229, v200
	v_fma_f32 v57, v109, v229, v201
	v_exp_f32_e32 v50, v50
	v_exp_f32_e32 v51, v51
	v_exp_f32_e32 v52, v52
	v_exp_f32_e32 v53, v53
	v_exp_f32_e32 v54, v54
	v_exp_f32_e32 v55, v55
	v_exp_f32_e32 v56, v56
	v_exp_f32_e32 v57, v57
	v_add_f32_e32 v50, 1.0, v50
	v_add_f32_e32 v51, 1.0, v51
	v_add_f32_e32 v52, 1.0, v52
	v_add_f32_e32 v53, 1.0, v53
	v_add_f32_e32 v54, 1.0, v54
	v_add_f32_e32 v55, 1.0, v55
	v_add_f32_e32 v56, 1.0, v56
	v_add_f32_e32 v57, 1.0, v57
	v_rcp_f32_e32 v50, v50
	v_rcp_f32_e32 v51, v51
	v_rcp_f32_e32 v52, v52
	v_rcp_f32_e32 v53, v53
	v_rcp_f32_e32 v54, v54
	v_rcp_f32_e32 v55, v55
	v_rcp_f32_e32 v56, v56
	v_rcp_f32_e32 v57, v57
	v_lshlrev_b32_e32 v58, 16, v26
	v_and_b32_e32 v59, 0xffff0000, v26
	v_pk_fma_f32 v[50:51], v[50:51], v[58:59], v[62:63]
	v_lshlrev_b32_e32 v58, 16, v27
	v_and_b32_e32 v59, 0xffff0000, v27
	v_pk_fma_f32 v[52:53], v[52:53], v[58:59], v[62:63]
	v_lshlrev_b32_e32 v58, 16, v28
	v_and_b32_e32 v59, 0xffff0000, v28
	v_pk_fma_f32 v[54:55], v[54:55], v[58:59], v[62:63]
	v_lshlrev_b32_e32 v58, 16, v29
	v_and_b32_e32 v59, 0xffff0000, v29
	v_pk_fma_f32 v[56:57], v[56:57], v[58:59], v[62:63]
	v_cvt_pk_bf16_f32 v26, v50, v51
	v_cvt_pk_bf16_f32 v27, v52, v53
	v_cvt_pk_bf16_f32 v28, v54, v55
	v_cvt_pk_bf16_f32 v29, v56, v57
	s_cbranch_vccz .Lgate_f_m9
	global_store_dwordx4 v225, v[26:29], s[8:9]
	s_add_u32 s8, s8, 0x2000
	s_addc_u32 s9, s9, 0
	s_branch .Lgate_f_j9

; __device__ __forceinline__ unsigned pk2(float lo, float hi) { f32x2_t v = {lo, hi}; bf16x2_t b = __builtin_convertvector(v, bf16x2_t); return __builtin_bit_cast(unsigned, b); }
; __device__ __forceinline__ float sigmoidf_(float x) { return __builtin_amdgcn_rcpf(1.0f + fexp2(-x * LOG2E)); }
;     __device__ __forceinline__ void operator()(AccRef acc, const pg8::Unit& u, int wr, int wc, int fr, int fq) const {
;     ...
;                 for (int m = 0; m < 4; ++m) {
;                     const size_t ci = ub + (size_t)((ai * 2 + bj) * 4 + m) * NTHREADS;
;                     const v4u pw = pw4[m], tw = tw4[m];
;                     const float rs = rst[(row0 + ai * 128 + m * 16) & 255];
;                     float v[8];
;                     v[0] = sigmoidf_(acc[ai][bj][m][0][0] * rs + bv0[0]) * bflo(pw.x); v[1] = sigmoidf_(acc[ai][bj][m][0][1] * rs + bv0[1]) * bfhi(pw.x);
;                     v[2] = sigmoidf_(acc[ai][bj][m][0][2] * rs + bv0[2]) * bflo(pw.y); v[3] = sigmoidf_(acc[ai][bj][m][0][3] * rs + bv0[3]) * bfhi(pw.y);
;                     v[4] = sigmoidf_(acc[ai][bj][m][1][0] * rs + bv1[0]) * bflo(pw.z); v[5] = sigmoidf_(acc[ai][bj][m][1][1] * rs + bv1[1]) * bfhi(pw.z);
;                     v[6] = sigmoidf_(acc[ai][bj][m][1][2] * rs + bv1[2]) * bflo(pw.w); v[7] = sigmoidf_(acc[ai][bj][m][1][3] * rs + bv1[3]) * bfhi(pw.w);
;                     v[0] += bflo(tw.x); v[1] += bfhi(tw.x); v[2] += bflo(tw.y); v[3] += bfhi(tw.y);
;                     v[4] += bflo(tw.z); v[5] += bfhi(tw.z); v[6] += bflo(tw.w); v[7] += bfhi(tw.w);
;                     v4u w; w.x = pk2(v[0], v[1]); w.y = pk2(v[2], v[3]); w.z = pk2(v[4], v[5]); w.w = pk2(v[6], v[7]);
;                     if (!last) TMP[ci] = w;
;                     else *(v4u*)(MRG + (size_t)(row0 + ai * 128 + m * 16) * D + col0 + bj * 128) = w;
.Lgate_f_j9:
	global_load_dwordx4 v[26:29], v224, s[6:7]
	s_add_u32 s6, s6, 0x2000
	s_addc_u32 s7, s7, 0
	s_waitcnt vmcnt(10)
	v_fma_f32 v50, v94, v230, v194
	v_fma_f32 v51, v95, v230, v195
	v_fma_f32 v52, v96, v230, v196
	v_fma_f32 v53, v97, v230, v197
	v_fma_f32 v54, v90, v230, v198
	v_fma_f32 v55, v91, v230, v199
	v_fma_f32 v56, v92, v230, v200
	v_fma_f32 v57, v93, v230, v201
	v_exp_f32_e32 v50, v50
	v_exp_f32_e32 v51, v51
	v_exp_f32_e32 v52, v52
	v_exp_f32_e32 v53, v53
	v_exp_f32_e32 v54, v54
	v_exp_f32_e32 v55, v55
	v_exp_f32_e32 v56, v56
	v_exp_f32_e32 v57, v57
	v_add_f32_e32 v50, 1.0, v50
	v_add_f32_e32 v51, 1.0, v51
	v_add_f32_e32 v52, 1.0, v52
	v_add_f32_e32 v53, 1.0, v53
	v_add_f32_e32 v54, 1.0, v54
	v_add_f32_e32 v55, 1.0, v55
	v_add_f32_e32 v56, 1.0, v56
	v_add_f32_e32 v57, 1.0, v57
	v_rcp_f32_e32 v50, v50
	v_rcp_f32_e32 v51, v51
	v_rcp_f32_e32 v52, v52
	v_rcp_f32_e32 v53, v53
	v_rcp_f32_e32 v54, v54
	v_rcp_f32_e32 v55, v55
	v_rcp_f32_e32 v56, v56
	v_rcp_f32_e32 v57, v57
	v_lshlrev_b32_e32 v58, 16, v34
	v_and_b32_e32 v59, 0xffff0000, v34
	v_pk_fma_f32 v[50:51], v[50:51], v[58:59], v[62:63]
	v_lshlrev_b32_e32 v58, 16, v35
	v_and_b32_e32 v59, 0xffff0000, v35
	v_pk_fma_f32 v[52:53], v[52:53], v[58:59], v[62:63]
	v_lshlrev_b32_e32 v58, 16, v36
	v_and_b32_e32 v59, 0xffff0000, v36
	v_pk_fma_f32 v[54:55], v[54:55], v[58:59], v[62:63]
	v_lshlrev_b32_e32 v58, 16, v37
	v_and_b32_e32 v59, 0xffff0000, v37
	v_pk_fma_f32 v[56:57], v[56:57], v[58:59], v[62:63]
	v_cvt_pk_bf16_f32 v34, v50, v51
	v_cvt_pk_bf16_f32 v35, v52, v53
	v_cvt_pk_bf16_f32 v36, v54, v55
	v_cvt_pk_bf16_f32 v37, v56, v57
	s_cbranch_vccz .Lgate_f_m10
	global_store_dwordx4 v225, v[34:37], s[8:9]
	s_add_u32 s8, s8, 0x2000
	s_addc_u32 s9, s9, 0
	s_branch .Lgate_f_j10

; __device__ __forceinline__ unsigned pk2(float lo, float hi) { f32x2_t v = {lo, hi}; bf16x2_t b = __builtin_convertvector(v, bf16x2_t); return __builtin_bit_cast(unsigned, b); }
; __device__ __forceinline__ float sigmoidf_(float x) { return __builtin_amdgcn_rcpf(1.0f + fexp2(-x * LOG2E)); }
;     __device__ __forceinline__ void operator()(AccRef acc, const pg8::Unit& u, int wr, int wc, int fr, int fq) const {
;     ...
;                 for (int m = 0; m < 4; ++m) {
;                     const size_t ci = ub + (size_t)((ai * 2 + bj) * 4 + m) * NTHREADS;
;                     const v4u pw = pw4[m], tw = tw4[m];
;                     const float rs = rst[(row0 + ai * 128 + m * 16) & 255];
;                     float v[8];
;                     v[0] = sigmoidf_(acc[ai][bj][m][0][0] * rs + bv0[0]) * bflo(pw.x); v[1] = sigmoidf_(acc[ai][bj][m][0][1] * rs + bv0[1]) * bfhi(pw.x);
;                     v[2] = sigmoidf_(acc[ai][bj][m][0][2] * rs + bv0[2]) * bflo(pw.y); v[3] = sigmoidf_(acc[ai][bj][m][0][3] * rs + bv0[3]) * bfhi(pw.y);
;                     v[4] = sigmoidf_(acc[ai][bj][m][1][0] * rs + bv1[0]) * bflo(pw.z); v[5] = sigmoidf_(acc[ai][bj][m][1][1] * rs + bv1[1]) * bfhi(pw.z);
;                     v[6] = sigmoidf_(acc[ai][bj][m][1][2] * rs + bv1[2]) * bflo(pw.w); v[7] = sigmoidf_(acc[ai][bj][m][1][3] * rs + bv1[3]) * bfhi(pw.w);
;                     v[0] += bflo(tw.x); v[1] += bfhi(tw.x); v[2] += bflo(tw.y); v[3] += bfhi(tw.y);
;                     v[4] += bflo(tw.z); v[5] += bfhi(tw.z); v[6] += bflo(tw.w); v[7] += bfhi(tw.w);
;                     v4u w; w.x = pk2(v[0], v[1]); w.y = pk2(v[2], v[3]); w.z = pk2(v[4], v[5]); w.w = pk2(v[6], v[7]);
;                     if (!last) TMP[ci] = w;
;                     else *(v4u*)(MRG + (size_t)(row0 + ai * 128 + m * 16) * D + col0 + bj * 128) = w;
.Lgate_f_j10:
	s_waitcnt vmcnt(9)
	v_fma_f32 v50, v78, v231, v194
	v_fma_f32 v51, v79, v231, v195
	v_fma_f32 v52, v80, v231, v196
	v_fma_f32 v53, v81, v231, v197
	v_fma_f32 v54, v74, v231, v198
	v_fma_f32 v55, v75, v231, v199
	v_fma_f32 v56, v76, v231, v200
	v_fma_f32 v57, v77, v231, v201
	v_exp_f32_e32 v50, v50
	v_exp_f32_e32 v51, v51
	v_exp_f32_e32 v52, v52
	v_exp_f32_e32 v53, v53
	v_exp_f32_e32 v54, v54
	v_exp_f32_e32 v55, v55
	v_exp_f32_e32 v56, v56
	v_exp_f32_e32 v57, v57
	v_add_f32_e32 v50, 1.0, v50
	v_add_f32_e32 v51, 1.0, v51
	v_add_f32_e32 v52, 1.0, v52
	v_add_f32_e32 v53, 1.0, v53
	v_add_f32_e32 v54, 1.0, v54
	v_add_f32_e32 v55, 1.0, v55
	v_add_f32_e32 v56, 1.0, v56
	v_add_f32_e32 v57, 1.0, v57
	v_rcp_f32_e32 v50, v50
	v_rcp_f32_e32 v51, v51
	v_rcp_f32_e32 v52, v52
	v_rcp_f32_e32 v53, v53
	v_rcp_f32_e32 v54, v54
	v_rcp_f32_e32 v55, v55
	v_rcp_f32_e32 v56, v56
	v_rcp_f32_e32 v57, v57
	v_lshlrev_b32_e32 v58, 16, v42
	v_and_b32_e32 v59, 0xffff0000, v42
	v_pk_fma_f32 v[50:51], v[50:51], v[58:59], v[62:63]
	v_lshlrev_b32_e32 v58, 16, v43
	v_and_b32_e32 v59, 0xffff0000, v43
	v_pk_fma_f32 v[52:53], v[52:53], v[58:59], v[62:63]
	v_lshlrev_b32_e32 v58, 16, v44
	v_and_b32_e32 v59, 0xffff0000, v44
	v_pk_fma_f32 v[54:55], v[54:55], v[58:59], v[62:63]
	v_lshlrev_b32_e32 v58, 16, v45
	v_and_b32_e32 v59, 0xffff0000, v45
	v_pk_fma_f32 v[56:57], v[56:57], v[58:59], v[62:63]
	v_cvt_pk_bf16_f32 v42, v50, v51
	v_cvt_pk_bf16_f32 v43, v52, v53
	v_cvt_pk_bf16_f32 v44, v54, v55
	v_cvt_pk_bf16_f32 v45, v56, v57
	s_cbranch_vccz .Lgate_f_m11
	global_store_dwordx4 v225, v[42:45], s[8:9]
	s_add_u32 s8, s8, 0x2000
	s_addc_u32 s9, s9, 0
	s_branch .Lgate_f_j11

; __device__ __forceinline__ unsigned pk2(float lo, float hi) { f32x2_t v = {lo, hi}; bf16x2_t b = __builtin_convertvector(v, bf16x2_t); return __builtin_bit_cast(unsigned, b); }
; __device__ __forceinline__ float sigmoidf_(float x) { return __builtin_amdgcn_rcpf(1.0f + fexp2(-x * LOG2E)); }
;     __device__ __forceinline__ void operator()(AccRef acc, const pg8::Unit& u, int wr, int wc, int fr, int fq) const {
;     ...
;                 for (int m = 0; m < 4; ++m) {
;                     const size_t ci = ub + (size_t)((ai * 2 + bj) * 4 + m) * NTHREADS;
;                     const v4u pw = pw4[m], tw = tw4[m];
;                     const float rs = rst[(row0 + ai * 128 + m * 16) & 255];
;                     float v[8];
;                     v[0] = sigmoidf_(acc[ai][bj][m][0][0] * rs + bv0[0]) * bflo(pw.x); v[1] = sigmoidf_(acc[ai][bj][m][0][1] * rs + bv0[1]) * bfhi(pw.x);
;                     v[2] = sigmoidf_(acc[ai][bj][m][0][2] * rs + bv0[2]) * bflo(pw.y); v[3] = sigmoidf_(acc[ai][bj][m][0][3] * rs + bv0[3]) * bfhi(pw.y);
;                     v[4] = sigmoidf_(acc[ai][bj][m][1][0] * rs + bv1[0]) * bflo(pw.z); v[5] = sigmoidf_(acc[ai][bj][m][1][1] * rs + bv1[1]) * bfhi(pw.z);
;                     v[6] = sigmoidf_(acc[ai][bj][m][1][2] * rs + bv1[2]) * bflo(pw.w); v[7] = sigmoidf_(acc[ai][bj][m][1][3] * rs + bv1[3]) * bfhi(pw.w);
;                     v[0] += bflo(tw.x); v[1] += bfhi(tw.x); v[2] += bflo(tw.y); v[3] += bfhi(tw.y);
;                     v[4] += bflo(tw.z); v[5] += bfhi(tw.z); v[6] += bflo(tw.w); v[7] += bfhi(tw.w);
;                     v4u w; w.x = pk2(v[0], v[1]); w.y = pk2(v[2], v[3]); w.z = pk2(v[4], v[5]); w.w = pk2(v[6], v[7]);
;                     if (!last) TMP[ci] = w;
;                     else *(v4u*)(MRG + (size_t)(row0 + ai * 128 + m * 16) * D + col0 + bj * 128) = w;
.Lgate_f_j11:
	s_waitcnt vmcnt(8)
	v_fma_f32 v50, v118, v228, v202
	v_fma_f32 v51, v119, v228, v203
	v_fma_f32 v52, v120, v228, v204
	v_fma_f32 v53, v121, v228, v205
	v_fma_f32 v54, v114, v228, v206
	v_fma_f32 v55, v115, v228, v207
	v_fma_f32 v56, v116, v228, v208
	v_fma_f32 v57, v117, v228, v209
	v_exp_f32_e32 v50, v50
	v_exp_f32_e32 v51, v51
	v_exp_f32_e32 v52, v52
	v_exp_f32_e32 v53, v53
	v_exp_f32_e32 v54, v54
	v_exp_f32_e32 v55, v55
	v_exp_f32_e32 v56, v56
	v_exp_f32_e32 v57, v57
	v_add_f32_e32 v50, 1.0, v50
	v_add_f32_e32 v51, 1.0, v51
	v_add_f32_e32 v52, 1.0, v52
	v_add_f32_e32 v53, 1.0, v53
	v_add_f32_e32 v54, 1.0, v54
	v_add_f32_e32 v55, 1.0, v55
	v_add_f32_e32 v56, 1.0, v56
	v_add_f32_e32 v57, 1.0, v57
	v_rcp_f32_e32 v50, v50
	v_rcp_f32_e32 v51, v51
	v_rcp_f32_e32 v52, v52
	v_rcp_f32_e32 v53, v53
	v_rcp_f32_e32 v54, v54
	v_rcp_f32_e32 v55, v55
	v_rcp_f32_e32 v56, v56
	v_rcp_f32_e32 v57, v57
	v_lshlrev_b32_e32 v58, 16, v2
	v_and_b32_e32 v59, 0xffff0000, v2
	v_pk_fma_f32 v[50:51], v[50:51], v[58:59], v[62:63]
	v_lshlrev_b32_e32 v58, 16, v3
	v_and_b32_e32 v59, 0xffff0000, v3
	v_pk_fma_f32 v[52:53], v[52:53], v[58:59], v[62:63]
	v_lshlrev_b32_e32 v58, 16, v4
	v_and_b32_e32 v59, 0xffff0000, v4
	v_pk_fma_f32 v[54:55], v[54:55], v[58:59], v[62:63]
	v_lshlrev_b32_e32 v58, 16, v5
	v_and_b32_e32 v59, 0xffff0000, v5
	v_pk_fma_f32 v[56:57], v[56:57], v[58:59], v[62:63]
	v_cvt_pk_bf16_f32 v2, v50, v51
	v_cvt_pk_bf16_f32 v3, v52, v53
	v_cvt_pk_bf16_f32 v4, v54, v55
	v_cvt_pk_bf16_f32 v5, v56, v57
	s_cbranch_vccz .Lgate_f_m12
	global_store_dwordx4 v225, v[2:5], s[8:9]
	s_add_u32 s8, s8, 0x2000
	s_addc_u32 s9, s9, 0
	s_branch .Lgate_f_j12

; __device__ __forceinline__ unsigned pk2(float lo, float hi) { f32x2_t v = {lo, hi}; bf16x2_t b = __builtin_convertvector(v, bf16x2_t); return __builtin_bit_cast(unsigned, b); }
; __device__ __forceinline__ float sigmoidf_(float x) { return __builtin_amdgcn_rcpf(1.0f + fexp2(-x * LOG2E)); }
;     __device__ __forceinline__ void operator()(AccRef acc, const pg8::Unit& u, int wr, int wc, int fr, int fq) const {
;     ...
;                 for (int m = 0; m < 4; ++m) {
;                     const size_t ci = ub + (size_t)((ai * 2 + bj) * 4 + m) * NTHREADS;
;                     const v4u pw = pw4[m], tw = tw4[m];
;                     const float rs = rst[(row0 + ai * 128 + m * 16) & 255];
;                     float v[8];
;                     v[0] = sigmoidf_(acc[ai][bj][m][0][0] * rs + bv0[0]) * bflo(pw.x); v[1] = sigmoidf_(acc[ai][bj][m][0][1] * rs + bv0[1]) * bfhi(pw.x);
;                     v[2] = sigmoidf_(acc[ai][bj][m][0][2] * rs + bv0[2]) * bflo(pw.y); v[3] = sigmoidf_(acc[ai][bj][m][0][3] * rs + bv0[3]) * bfhi(pw.y);
;                     v[4] = sigmoidf_(acc[ai][bj][m][1][0] * rs + bv1[0]) * bflo(pw.z); v[5] = sigmoidf_(acc[ai][bj][m][1][1] * rs + bv1[1]) * bfhi(pw.z);
;                     v[6] = sigmoidf_(acc[ai][bj][m][1][2] * rs + bv1[2]) * bflo(pw.w); v[7] = sigmoidf_(acc[ai][bj][m][1][3] * rs + bv1[3]) * bfhi(pw.w);
;                     v[0] += bflo(tw.x); v[1] += bfhi(tw.x); v[2] += bflo(tw.y); v[3] += bfhi(tw.y);
;                     v[4] += bflo(tw.z); v[5] += bfhi(tw.z); v[6] += bflo(tw.w); v[7] += bfhi(tw.w);
;                     v4u w; w.x = pk2(v[0], v[1]); w.y = pk2(v[2], v[3]); w.z = pk2(v[4], v[5]); w.w = pk2(v[6], v[7]);
;                     if (!last) TMP[ci] = w;
;                     else *(v4u*)(MRG + (size_t)(row0 + ai * 128 + m * 16) * D + col0 + bj * 128) = w;
.Lgate_f_j12:
	s_waitcnt vmcnt(7)
	v_fma_f32 v50, v102, v229, v202
	v_fma_f32 v51, v103, v229, v203
	v_fma_f32 v52, v104, v229, v204
	v_fma_f32 v53, v105, v229, v205
	v_fma_f32 v54, v98, v229, v206
	v_fma_f32 v55, v99, v229, v207
	v_fma_f32 v56, v100, v229, v208
	v_fma_f32 v57, v101, v229, v209
	v_exp_f32_e32 v50, v50
	v_exp_f32_e32 v51, v51
	v_exp_f32_e32 v52, v52
	v_exp_f32_e32 v53, v53
	v_exp_f32_e32 v54, v54
	v_exp_f32_e32 v55, v55
	v_exp_f32_e32 v56, v56
	v_exp_f32_e32 v57, v57
	v_add_f32_e32 v50, 1.0, v50
	v_add_f32_e32 v51, 1.0, v51
	v_add_f32_e32 v52, 1.0, v52
	v_add_f32_e32 v53, 1.0, v53
	v_add_f32_e32 v54, 1.0, v54
	v_add_f32_e32 v55, 1.0, v55
	v_add_f32_e32 v56, 1.0, v56
	v_add_f32_e32 v57, 1.0, v57
	v_rcp_f32_e32 v50, v50
	v_rcp_f32_e32 v51, v51
	v_rcp_f32_e32 v52, v52
	v_rcp_f32_e32 v53, v53
	v_rcp_f32_e32 v54, v54
	v_rcp_f32_e32 v55, v55
	v_rcp_f32_e32 v56, v56
	v_rcp_f32_e32 v57, v57
	v_lshlrev_b32_e32 v58, 16, v10
	v_and_b32_e32 v59, 0xffff0000, v10
	v_pk_fma_f32 v[50:51], v[50:51], v[58:59], v[62:63]
	v_lshlrev_b32_e32 v58, 16, v11
	v_and_b32_e32 v59, 0xffff0000, v11
	v_pk_fma_f32 v[52:53], v[52:53], v[58:59], v[62:63]
	v_lshlrev_b32_e32 v58, 16, v12
	v_and_b32_e32 v59, 0xffff0000, v12
	v_pk_fma_f32 v[54:55], v[54:55], v[58:59], v[62:63]
	v_lshlrev_b32_e32 v58, 16, v13
	v_and_b32_e32 v59, 0xffff0000, v13
	v_pk_fma_f32 v[56:57], v[56:57], v[58:59], v[62:63]
	v_cvt_pk_bf16_f32 v10, v50, v51
	v_cvt_pk_bf16_f32 v11, v52, v53
	v_cvt_pk_bf16_f32 v12, v54, v55
	v_cvt_pk_bf16_f32 v13, v56, v57
	s_cbranch_vccz .Lgate_f_m13
	global_store_dwordx4 v225, v[10:13], s[8:9]
	s_add_u32 s8, s8, 0x2000
	s_addc_u32 s9, s9, 0
	s_branch .Lgate_f_j13

; __device__ __forceinline__ unsigned pk2(float lo, float hi) { f32x2_t v = {lo, hi}; bf16x2_t b = __builtin_convertvector(v, bf16x2_t); return __builtin_bit_cast(unsigned, b); }
; __device__ __forceinline__ float sigmoidf_(float x) { return __builtin_amdgcn_rcpf(1.0f + fexp2(-x * LOG2E)); }
;     __device__ __forceinline__ void operator()(AccRef acc, const pg8::Unit& u, int wr, int wc, int fr, int fq) const {
;     ...
;                 for (int m = 0; m < 4; ++m) {
;                     const size_t ci = ub + (size_t)((ai * 2 + bj) * 4 + m) * NTHREADS;
;                     const v4u pw = pw4[m], tw = tw4[m];
;                     const float rs = rst[(row0 + ai * 128 + m * 16) & 255];
;                     float v[8];
;                     v[0] = sigmoidf_(acc[ai][bj][m][0][0] * rs + bv0[0]) * bflo(pw.x); v[1] = sigmoidf_(acc[ai][bj][m][0][1] * rs + bv0[1]) * bfhi(pw.x);
;                     v[2] = sigmoidf_(acc[ai][bj][m][0][2] * rs + bv0[2]) * bflo(pw.y); v[3] = sigmoidf_(acc[ai][bj][m][0][3] * rs + bv0[3]) * bfhi(pw.y);
;                     v[4] = sigmoidf_(acc[ai][bj][m][1][0] * rs + bv1[0]) * bflo(pw.z); v[5] = sigmoidf_(acc[ai][bj][m][1][1] * rs + bv1[1]) * bfhi(pw.z);
;                     v[6] = sigmoidf_(acc[ai][bj][m][1][2] * rs + bv1[2]) * bflo(pw.w); v[7] = sigmoidf_(acc[ai][bj][m][1][3] * rs + bv1[3]) * bfhi(pw.w);
;                     v[0] += bflo(tw.x); v[1] += bfhi(tw.x); v[2] += bflo(tw.y); v[3] += bfhi(tw.y);
;                     v[4] += bflo(tw.z); v[5] += bfhi(tw.z); v[6] += bflo(tw.w); v[7] += bfhi(tw.w);
;                     v4u w; w.x = pk2(v[0], v[1]); w.y = pk2(v[2], v[3]); w.z = pk2(v[4], v[5]); w.w = pk2(v[6], v[7]);
;                     if (!last) TMP[ci] = w;
;                     else *(v4u*)(MRG + (size_t)(row0 + ai * 128 + m * 16) * D + col0 + bj * 128) = w;
.Lgate_f_j13:
	s_waitcnt vmcnt(6)
	v_fma_f32 v50, v86, v230, v202
	v_fma_f32 v51, v87, v230, v203
	v_fma_f32 v52, v88, v230, v204
	v_fma_f32 v53, v89, v230, v205
	v_fma_f32 v54, v82, v230, v206
	v_fma_f32 v55, v83, v230, v207
	v_fma_f32 v56, v84, v230, v208
	v_fma_f32 v57, v85, v230, v209
	v_exp_f32_e32 v50, v50
	v_exp_f32_e32 v51, v51
	v_exp_f32_e32 v52, v52
	v_exp_f32_e32 v53, v53
	v_exp_f32_e32 v54, v54
	v_exp_f32_e32 v55, v55
	v_exp_f32_e32 v56, v56
	v_exp_f32_e32 v57, v57
	v_add_f32_e32 v50, 1.0, v50
	v_add_f32_e32 v51, 1.0, v51
	v_add_f32_e32 v52, 1.0, v52
	v_add_f32_e32 v53, 1.0, v53
	v_add_f32_e32 v54, 1.0, v54
	v_add_f32_e32 v55, 1.0, v55
	v_add_f32_e32 v56, 1.0, v56
	v_add_f32_e32 v57, 1.0, v57
	v_rcp_f32_e32 v50, v50
	v_rcp_f32_e32 v51, v51
	v_rcp_f32_e32 v52, v52
	v_rcp_f32_e32 v53, v53
	v_rcp_f32_e32 v54, v54
	v_rcp_f32_e32 v55, v55
	v_rcp_f32_e32 v56, v56
	v_rcp_f32_e32 v57, v57
	v_lshlrev_b32_e32 v58, 16, v18
	v_and_b32_e32 v59, 0xffff0000, v18
	v_pk_fma_f32 v[50:51], v[50:51], v[58:59], v[62:63]
	v_lshlrev_b32_e32 v58, 16, v19
	v_and_b32_e32 v59, 0xffff0000, v19
	v_pk_fma_f32 v[52:53], v[52:53], v[58:59], v[62:63]
	v_lshlrev_b32_e32 v58, 16, v20
	v_and_b32_e32 v59, 0xffff0000, v20
	v_pk_fma_f32 v[54:55], v[54:55], v[58:59], v[62:63]
	v_lshlrev_b32_e32 v58, 16, v21
	v_and_b32_e32 v59, 0xffff0000, v21
	v_pk_fma_f32 v[56:57], v[56:57], v[58:59], v[62:63]
	v_cvt_pk_bf16_f32 v18, v50, v51
	v_cvt_pk_bf16_f32 v19, v52, v53
	v_cvt_pk_bf16_f32 v20, v54, v55
	v_cvt_pk_bf16_f32 v21, v56, v57
	s_cbranch_vccz .Lgate_f_m14
	global_store_dwordx4 v225, v[18:21], s[8:9]
	s_add_u32 s8, s8, 0x2000
	s_addc_u32 s9, s9, 0
	s_branch .Lgate_f_j14

; __device__ __forceinline__ unsigned pk2(float lo, float hi) { f32x2_t v = {lo, hi}; bf16x2_t b = __builtin_convertvector(v, bf16x2_t); return __builtin_bit_cast(unsigned, b); }
; __device__ __forceinline__ float sigmoidf_(float x) { return __builtin_amdgcn_rcpf(1.0f + fexp2(-x * LOG2E)); }
;     __device__ __forceinline__ void operator()(AccRef acc, const pg8::Unit& u, int wr, int wc, int fr, int fq) const {
;     ...
;                 for (int m = 0; m < 4; ++m) {
;                     const size_t ci = ub + (size_t)((ai * 2 + bj) * 4 + m) * NTHREADS;
;                     const v4u pw = pw4[m], tw = tw4[m];
;                     const float rs = rst[(row0 + ai * 128 + m * 16) & 255];
;                     float v[8];
;                     v[0] = sigmoidf_(acc[ai][bj][m][0][0] * rs + bv0[0]) * bflo(pw.x); v[1] = sigmoidf_(acc[ai][bj][m][0][1] * rs + bv0[1]) * bfhi(pw.x);
;                     v[2] = sigmoidf_(acc[ai][bj][m][0][2] * rs + bv0[2]) * bflo(pw.y); v[3] = sigmoidf_(acc[ai][bj][m][0][3] * rs + bv0[3]) * bfhi(pw.y);
;                     v[4] = sigmoidf_(acc[ai][bj][m][1][0] * rs + bv1[0]) * bflo(pw.z); v[5] = sigmoidf_(acc[ai][bj][m][1][1] * rs + bv1[1]) * bfhi(pw.z);
;                     v[6] = sigmoidf_(acc[ai][bj][m][1][2] * rs + bv1[2]) * bflo(pw.w); v[7] = sigmoidf_(acc[ai][bj][m][1][3] * rs + bv1[3]) * bfhi(pw.w);
;                     v[0] += bflo(tw.x); v[1] += bfhi(tw.x); v[2] += bflo(tw.y); v[3] += bfhi(tw.y);
;                     v[4] += bflo(tw.z); v[5] += bfhi(tw.z); v[6] += bflo(tw.w); v[7] += bfhi(tw.w);
;                     v4u w; w.x = pk2(v[0], v[1]); w.y = pk2(v[2], v[3]); w.z = pk2(v[4], v[5]); w.w = pk2(v[6], v[7]);
;                     if (!last) TMP[ci] = w;
;                     else *(v4u*)(MRG + (size_t)(row0 + ai * 128 + m * 16) * D + col0 + bj * 128) = w;
.Lgate_f_j14:
	s_waitcnt vmcnt(5)
	v_fma_f32 v50, v70, v231, v202
	v_fma_f32 v51, v71, v231, v203
	v_fma_f32 v52, v72, v231, v204
	v_fma_f32 v53, v73, v231, v205
	v_fma_f32 v54, v66, v231, v206
	v_fma_f32 v55, v67, v231, v207
	v_fma_f32 v56, v68, v231, v208
	v_fma_f32 v57, v69, v231, v209
	v_exp_f32_e32 v50, v50
	v_exp_f32_e32 v51, v51
	v_exp_f32_e32 v52, v52
	v_exp_f32_e32 v53, v53
	v_exp_f32_e32 v54, v54
	v_exp_f32_e32 v55, v55
	v_exp_f32_e32 v56, v56
	v_exp_f32_e32 v57, v57
	v_add_f32_e32 v50, 1.0, v50
	v_add_f32_e32 v51, 1.0, v51
	v_add_f32_e32 v52, 1.0, v52
	v_add_f32_e32 v53, 1.0, v53
	v_add_f32_e32 v54, 1.0, v54
	v_add_f32_e32 v55, 1.0, v55
	v_add_f32_e32 v56, 1.0, v56
	v_add_f32_e32 v57, 1.0, v57
	v_rcp_f32_e32 v50, v50
	v_rcp_f32_e32 v51, v51
	v_rcp_f32_e32 v52, v52
	v_rcp_f32_e32 v53, v53
	v_rcp_f32_e32 v54, v54
	v_rcp_f32_e32 v55, v55
	v_rcp_f32_e32 v56, v56
	v_rcp_f32_e32 v57, v57
	v_lshlrev_b32_e32 v58, 16, v26
	v_and_b32_e32 v59, 0xffff0000, v26
	v_pk_fma_f32 v[50:51], v[50:51], v[58:59], v[62:63]
	v_lshlrev_b32_e32 v58, 16, v27
	v_and_b32_e32 v59, 0xffff0000, v27
	v_pk_fma_f32 v[52:53], v[52:53], v[58:59], v[62:63]
	v_lshlrev_b32_e32 v58, 16, v28
	v_and_b32_e32 v59, 0xffff0000, v28
	v_pk_fma_f32 v[54:55], v[54:55], v[58:59], v[62:63]
	v_lshlrev_b32_e32 v58, 16, v29
	v_and_b32_e32 v59, 0xffff0000, v29
	v_pk_fma_f32 v[56:57], v[56:57], v[58:59], v[62:63]
	v_cvt_pk_bf16_f32 v26, v50, v51
	v_cvt_pk_bf16_f32 v27, v52, v53
	v_cvt_pk_bf16_f32 v28, v54, v55
	v_cvt_pk_bf16_f32 v29, v56, v57
	s_cbranch_vccz .Lgate_f_m15
	global_store_dwordx4 v225, v[26:29], s[8:9]
	s_branch .Lgate_f_j15

; __device__ __forceinline__ unsigned pk2(float lo, float hi) { f32x2_t v = {lo, hi}; bf16x2_t b = __builtin_convertvector(v, bf16x2_t); return __builtin_bit_cast(unsigned, b); }
; __device__ __forceinline__ float sigmoidf_(float x) { return __builtin_amdgcn_rcpf(1.0f + fexp2(-x * LOG2E)); }
;     __device__ __forceinline__ void operator()(AccRef acc, const pg8::Unit& u, int wr, int wc, int fr, int fq) const {
;     ...
;                 v4u pw4[4], tw4[4];
; #pragma unroll
;                 for (int m = 0; m < 4; ++m) {
;                     const size_t ci = ub + (size_t)((ai * 2 + bj) * 4 + m) * NTHREADS;
;                     pw4[m] = P[ci];
;                     if (!first) tw4[m] = TMP[ci]; else tw4[m] = (v4u){0u, 0u, 0u, 0u};
;                 }
; #pragma unroll
;                 for (int m = 0; m < 4; ++m) {
;                     const size_t ci = ub + (size_t)((ai * 2 + bj) * 4 + m) * NTHREADS;
;                     const v4u pw = pw4[m], tw = tw4[m];
;                     const float rs = rst[(row0 + ai * 128 + m * 16) & 255];
;                     float v[8];
;                     v[0] = sigmoidf_(acc[ai][bj][m][0][0] * rs + bv0[0]) * bflo(pw.x); v[1] = sigmoidf_(acc[ai][bj][m][0][1] * rs + bv0[1]) * bfhi(pw.x);
;                     v[2] = sigmoidf_(acc[ai][bj][m][0][2] * rs + bv0[2]) * bflo(pw.y); v[3] = sigmoidf_(acc[ai][bj][m][0][3] * rs + bv0[3]) * bfhi(pw.y);
;                     v[4] = sigmoidf_(acc[ai][bj][m][1][0] * rs + bv1[0]) * bflo(pw.z); v[5] = sigmoidf_(acc[ai][bj][m][1][1] * rs + bv1[1]) * bfhi(pw.z);
;                     v[6] = sigmoidf_(acc[ai][bj][m][1][2] * rs + bv1[2]) * bflo(pw.w); v[7] = sigmoidf_(acc[ai][bj][m][1][3] * rs + bv1[3]) * bfhi(pw.w);
;                     v[0] += bflo(tw.x); v[1] += bfhi(tw.x); v[2] += bflo(tw.y); v[3] += bfhi(tw.y);
;                     v[4] += bflo(tw.z); v[5] += bfhi(tw.z); v[6] += bflo(tw.w); v[7] += bfhi(tw.w);
;                     v4u w; w.x = pk2(v[0], v[1]); w.y = pk2(v[2], v[3]); w.z = pk2(v[4], v[5]); w.w = pk2(v[6], v[7]);
;                     if (!last) TMP[ci] = w;
;                     else *(v4u*)(MRG + (size_t)(row0 + ai * 128 + m * 16) * D + col0 + bj * 128) = w;
.Lgate_n:
	global_load_dwordx4 v[2:5], v224, s[6:7]
	global_load_dwordx4 v[6:9], v225, s[6:7]
	s_add_u32 s6, s6, 0x2000
	s_addc_u32 s7, s7, 0
	global_load_dwordx4 v[10:13], v224, s[6:7]
	global_load_dwordx4 v[14:17], v225, s[6:7]
	s_add_u32 s6, s6, 0x2000
	s_addc_u32 s7, s7, 0
	global_load_dwordx4 v[18:21], v224, s[6:7]
	global_load_dwordx4 v[22:25], v225, s[6:7]
	s_add_u32 s6, s6, 0x2000
	s_addc_u32 s7, s7, 0
	global_load_dwordx4 v[26:29], v224, s[6:7]
	global_load_dwordx4 v[30:33], v225, s[6:7]
	s_add_u32 s6, s6, 0x2000
	s_addc_u32 s7, s7, 0
	global_load_dwordx4 v[34:37], v224, s[6:7]
	global_load_dwordx4 v[38:41], v225, s[6:7]
	s_add_u32 s6, s6, 0x2000
	s_addc_u32 s7, s7, 0
	global_load_dwordx4 v[42:45], v224, s[6:7]
	global_load_dwordx4 v[46:49], v225, s[6:7]
	s_add_u32 s6, s6, 0x2000
	s_addc_u32 s7, s7, 0
	ds_read_b32 v210, v227 offset:0
	ds_read_b32 v211, v227 offset:64
	ds_read_b32 v212, v227 offset:128
	ds_read_b32 v213, v227 offset:192
	ds_read_b32 v228, v227 offset:512
	ds_read_b32 v229, v227 offset:576
	ds_read_b32 v230, v227 offset:640
	ds_read_b32 v231, v227 offset:704
	s_waitcnt lgkmcnt(0)
	v_mul_f32_e32 v210, 0xbfb8aa3b, v210
	v_mul_f32_e32 v211, 0xbfb8aa3b, v211
	v_mul_f32_e32 v212, 0xbfb8aa3b, v212
	v_mul_f32_e32 v213, 0xbfb8aa3b, v213
	v_mul_f32_e32 v228, 0xbfb8aa3b, v228
	v_mul_f32_e32 v229, 0xbfb8aa3b, v229
	v_mul_f32_e32 v230, 0xbfb8aa3b, v230
	v_mul_f32_e32 v231, 0xbfb8aa3b, v231
	s_waitcnt vmcnt(12)
	v_mul_f32_e32 v194, 0xbfb8aa3b, v194
	v_mul_f32_e32 v195, 0xbfb8aa3b, v195
	v_mul_f32_e32 v196, 0xbfb8aa3b, v196
	v_mul_f32_e32 v197, 0xbfb8aa3b, v197
	v_mul_f32_e32 v198, 0xbfb8aa3b, v198
	v_mul_f32_e32 v199, 0xbfb8aa3b, v199
	v_mul_f32_e32 v200, 0xbfb8aa3b, v200
	v_mul_f32_e32 v201, 0xbfb8aa3b, v201
	v_mul_f32_e32 v202, 0xbfb8aa3b, v202
	v_mul_f32_e32 v203, 0xbfb8aa3b, v203
	v_mul_f32_e32 v204, 0xbfb8aa3b, v204
	v_mul_f32_e32 v205, 0xbfb8aa3b, v205
	v_mul_f32_e32 v206, 0xbfb8aa3b, v206
	v_mul_f32_e32 v207, 0xbfb8aa3b, v207
	v_mul_f32_e32 v208, 0xbfb8aa3b, v208
	v_mul_f32_e32 v209, 0xbfb8aa3b, v209
	s_waitcnt vmcnt(10)
	v_fma_f32 v50, v190, v210, v194
	v_fma_f32 v51, v191, v210, v195
	v_fma_f32 v52, v192, v210, v196
	v_fma_f32 v53, v193, v210, v197
	v_fma_f32 v54, v186, v210, v198
	v_fma_f32 v55, v187, v210, v199
	v_fma_f32 v56, v188, v210, v200
	v_fma_f32 v57, v189, v210, v201
	v_exp_f32_e32 v50, v50
	v_exp_f32_e32 v51, v51
	v_exp_f32_e32 v52, v52
	v_exp_f32_e32 v53, v53
	v_exp_f32_e32 v54, v54
	v_exp_f32_e32 v55, v55
	v_exp_f32_e32 v56, v56
	v_exp_f32_e32 v57, v57
	v_add_f32_e32 v50, 1.0, v50
	v_add_f32_e32 v51, 1.0, v51
	v_add_f32_e32 v52, 1.0, v52
	v_add_f32_e32 v53, 1.0, v53
	v_add_f32_e32 v54, 1.0, v54
	v_add_f32_e32 v55, 1.0, v55
	v_add_f32_e32 v56, 1.0, v56
	v_add_f32_e32 v57, 1.0, v57
	v_rcp_f32_e32 v50, v50
	v_rcp_f32_e32 v51, v51
	v_rcp_f32_e32 v52, v52
	v_rcp_f32_e32 v53, v53
	v_rcp_f32_e32 v54, v54
	v_rcp_f32_e32 v55, v55
	v_rcp_f32_e32 v56, v56
	v_rcp_f32_e32 v57, v57
	v_lshlrev_b32_e32 v58, 16, v2
	v_and_b32_e32 v59, 0xffff0000, v2
	v_lshlrev_b32_e32 v60, 16, v6
	v_and_b32_e32 v61, 0xffff0000, v6
	v_pk_fma_f32 v[50:51], v[50:51], v[58:59], v[60:61]
	v_lshlrev_b32_e32 v58, 16, v3
	v_and_b32_e32 v59, 0xffff0000, v3
	v_lshlrev_b32_e32 v60, 16, v7
	v_and_b32_e32 v61, 0xffff0000, v7
	v_pk_fma_f32 v[52:53], v[52:53], v[58:59], v[60:61]
	v_lshlrev_b32_e32 v58, 16, v4
	v_and_b32_e32 v59, 0xffff0000, v4
	v_lshlrev_b32_e32 v60, 16, v8
	v_and_b32_e32 v61, 0xffff0000, v8
	v_pk_fma_f32 v[54:55], v[54:55], v[58:59], v[60:61]
	v_lshlrev_b32_e32 v58, 16, v5
	v_and_b32_e32 v59, 0xffff0000, v5
	v_lshlrev_b32_e32 v60, 16, v9
	v_and_b32_e32 v61, 0xffff0000, v9
	v_pk_fma_f32 v[56:57], v[56:57], v[58:59], v[60:61]
	v_cvt_pk_bf16_f32 v2, v50, v51
	v_cvt_pk_bf16_f32 v3, v52, v53
	v_cvt_pk_bf16_f32 v4, v54, v55
	v_cvt_pk_bf16_f32 v5, v56, v57
	s_cbranch_vccz .Lgate_n_m0
	global_store_dwordx4 v225, v[2:5], s[8:9]
	s_add_u32 s8, s8, 0x2000
	s_addc_u32 s9, s9, 0
	s_branch .Lgate_n_j0

; __device__ __forceinline__ unsigned pk2(float lo, float hi) { f32x2_t v = {lo, hi}; bf16x2_t b = __builtin_convertvector(v, bf16x2_t); return __builtin_bit_cast(unsigned, b); }
; __device__ __forceinline__ float sigmoidf_(float x) { return __builtin_amdgcn_rcpf(1.0f + fexp2(-x * LOG2E)); }
;     __device__ __forceinline__ void operator()(AccRef acc, const pg8::Unit& u, int wr, int wc, int fr, int fq) const {
;     ...
;                 for (int m = 0; m < 4; ++m) {
;                     const size_t ci = ub + (size_t)((ai * 2 + bj) * 4 + m) * NTHREADS;
;                     const v4u pw = pw4[m], tw = tw4[m];
;                     const float rs = rst[(row0 + ai * 128 + m * 16) & 255];
;                     float v[8];
;                     v[0] = sigmoidf_(acc[ai][bj][m][0][0] * rs + bv0[0]) * bflo(pw.x); v[1] = sigmoidf_(acc[ai][bj][m][0][1] * rs + bv0[1]) * bfhi(pw.x);
;                     v[2] = sigmoidf_(acc[ai][bj][m][0][2] * rs + bv0[2]) * bflo(pw.y); v[3] = sigmoidf_(acc[ai][bj][m][0][3] * rs + bv0[3]) * bfhi(pw.y);
;                     v[4] = sigmoidf_(acc[ai][bj][m][1][0] * rs + bv1[0]) * bflo(pw.z); v[5] = sigmoidf_(acc[ai][bj][m][1][1] * rs + bv1[1]) * bfhi(pw.z);
;                     v[6] = sigmoidf_(acc[ai][bj][m][1][2] * rs + bv1[2]) * bflo(pw.w); v[7] = sigmoidf_(acc[ai][bj][m][1][3] * rs + bv1[3]) * bfhi(pw.w);
;                     v[0] += bflo(tw.x); v[1] += bfhi(tw.x); v[2] += bflo(tw.y); v[3] += bfhi(tw.y);
;                     v[4] += bflo(tw.z); v[5] += bfhi(tw.z); v[6] += bflo(tw.w); v[7] += bfhi(tw.w);
;                     v4u w; w.x = pk2(v[0], v[1]); w.y = pk2(v[2], v[3]); w.z = pk2(v[4], v[5]); w.w = pk2(v[6], v[7]);
;                     if (!last) TMP[ci] = w;
;                     else *(v4u*)(MRG + (size_t)(row0 + ai * 128 + m * 16) * D + col0 + bj * 128) = w;
.Lgate_n_j0:
	global_load_dwordx4 v[2:5], v224, s[6:7]
	global_load_dwordx4 v[6:9], v225, s[6:7]
	s_add_u32 s6, s6, 0x2000
	s_addc_u32 s7, s7, 0
	s_waitcnt vmcnt(11)
	v_fma_f32 v50, v174, v211, v194
	v_fma_f32 v51, v175, v211, v195
	v_fma_f32 v52, v176, v211, v196
	v_fma_f32 v53, v177, v211, v197
	v_fma_f32 v54, v170, v211, v198
	v_fma_f32 v55, v171, v211, v199
	v_fma_f32 v56, v172, v211, v200
	v_fma_f32 v57, v173, v211, v201
	v_exp_f32_e32 v50, v50
	v_exp_f32_e32 v51, v51
	v_exp_f32_e32 v52, v52
	v_exp_f32_e32 v53, v53
	v_exp_f32_e32 v54, v54
	v_exp_f32_e32 v55, v55
	v_exp_f32_e32 v56, v56
	v_exp_f32_e32 v57, v57
	v_add_f32_e32 v50, 1.0, v50
	v_add_f32_e32 v51, 1.0, v51
	v_add_f32_e32 v52, 1.0, v52
	v_add_f32_e32 v53, 1.0, v53
	v_add_f32_e32 v54, 1.0, v54
	v_add_f32_e32 v55, 1.0, v55
	v_add_f32_e32 v56, 1.0, v56
	v_add_f32_e32 v57, 1.0, v57
	v_rcp_f32_e32 v50, v50
	v_rcp_f32_e32 v51, v51
	v_rcp_f32_e32 v52, v52
	v_rcp_f32_e32 v53, v53
	v_rcp_f32_e32 v54, v54
	v_rcp_f32_e32 v55, v55
	v_rcp_f32_e32 v56, v56
	v_rcp_f32_e32 v57, v57
	v_lshlrev_b32_e32 v58, 16, v10
	v_and_b32_e32 v59, 0xffff0000, v10
	v_lshlrev_b32_e32 v60, 16, v14
	v_and_b32_e32 v61, 0xffff0000, v14
	v_pk_fma_f32 v[50:51], v[50:51], v[58:59], v[60:61]
	v_lshlrev_b32_e32 v58, 16, v11
	v_and_b32_e32 v59, 0xffff0000, v11
	v_lshlrev_b32_e32 v60, 16, v15
	v_and_b32_e32 v61, 0xffff0000, v15
	v_pk_fma_f32 v[52:53], v[52:53], v[58:59], v[60:61]
	v_lshlrev_b32_e32 v58, 16, v12
	v_and_b32_e32 v59, 0xffff0000, v12
	v_lshlrev_b32_e32 v60, 16, v16
	v_and_b32_e32 v61, 0xffff0000, v16
	v_pk_fma_f32 v[54:55], v[54:55], v[58:59], v[60:61]
	v_lshlrev_b32_e32 v58, 16, v13
	v_and_b32_e32 v59, 0xffff0000, v13
	v_lshlrev_b32_e32 v60, 16, v17
	v_and_b32_e32 v61, 0xffff0000, v17
	v_pk_fma_f32 v[56:57], v[56:57], v[58:59], v[60:61]
	v_cvt_pk_bf16_f32 v10, v50, v51
	v_cvt_pk_bf16_f32 v11, v52, v53
	v_cvt_pk_bf16_f32 v12, v54, v55
	v_cvt_pk_bf16_f32 v13, v56, v57
	s_cbranch_vccz .Lgate_n_m1
	global_store_dwordx4 v225, v[10:13], s[8:9]
	s_add_u32 s8, s8, 0x2000
	s_addc_u32 s9, s9, 0
	s_branch .Lgate_n_j1

; __device__ __forceinline__ unsigned pk2(float lo, float hi) { f32x2_t v = {lo, hi}; bf16x2_t b = __builtin_convertvector(v, bf16x2_t); return __builtin_bit_cast(unsigned, b); }
; __device__ __forceinline__ float sigmoidf_(float x) { return __builtin_amdgcn_rcpf(1.0f + fexp2(-x * LOG2E)); }
;     __device__ __forceinline__ void operator()(AccRef acc, const pg8::Unit& u, int wr, int wc, int fr, int fq) const {
;     ...
;                 for (int m = 0; m < 4; ++m) {
;                     const size_t ci = ub + (size_t)((ai * 2 + bj) * 4 + m) * NTHREADS;
;                     const v4u pw = pw4[m], tw = tw4[m];
;                     const float rs = rst[(row0 + ai * 128 + m * 16) & 255];
;                     float v[8];
;                     v[0] = sigmoidf_(acc[ai][bj][m][0][0] * rs + bv0[0]) * bflo(pw.x); v[1] = sigmoidf_(acc[ai][bj][m][0][1] * rs + bv0[1]) * bfhi(pw.x);
;                     v[2] = sigmoidf_(acc[ai][bj][m][0][2] * rs + bv0[2]) * bflo(pw.y); v[3] = sigmoidf_(acc[ai][bj][m][0][3] * rs + bv0[3]) * bfhi(pw.y);
;                     v[4] = sigmoidf_(acc[ai][bj][m][1][0] * rs + bv1[0]) * bflo(pw.z); v[5] = sigmoidf_(acc[ai][bj][m][1][1] * rs + bv1[1]) * bfhi(pw.z);
;                     v[6] = sigmoidf_(acc[ai][bj][m][1][2] * rs + bv1[2]) * bflo(pw.w); v[7] = sigmoidf_(acc[ai][bj][m][1][3] * rs + bv1[3]) * bfhi(pw.w);
;                     v[0] += bflo(tw.x); v[1] += bfhi(tw.x); v[2] += bflo(tw.y); v[3] += bfhi(tw.y);
;                     v[4] += bflo(tw.z); v[5] += bfhi(tw.z); v[6] += bflo(tw.w); v[7] += bfhi(tw.w);
;                     v4u w; w.x = pk2(v[0], v[1]); w.y = pk2(v[2], v[3]); w.z = pk2(v[4], v[5]); w.w = pk2(v[6], v[7]);
;                     if (!last) TMP[ci] = w;
;                     else *(v4u*)(MRG + (size_t)(row0 + ai * 128 + m * 16) * D + col0 + bj * 128) = w;
.Lgate_n_j1:
	global_load_dwordx4 v[10:13], v224, s[6:7]
	global_load_dwordx4 v[14:17], v225, s[6:7]
	s_add_u32 s6, s6, 0x2000
	s_addc_u32 s7, s7, 0
	s_waitcnt vmcnt(12)
	v_fma_f32 v50, v158, v212, v194
	v_fma_f32 v51, v159, v212, v195
	v_fma_f32 v52, v160, v212, v196
	v_fma_f32 v53, v161, v212, v197
	v_fma_f32 v54, v154, v212, v198
	v_fma_f32 v55, v155, v212, v199
	v_fma_f32 v56, v156, v212, v200
	v_fma_f32 v57, v157, v212, v201
	v_exp_f32_e32 v50, v50
	v_exp_f32_e32 v51, v51
	v_exp_f32_e32 v52, v52
	v_exp_f32_e32 v53, v53
	v_exp_f32_e32 v54, v54
	v_exp_f32_e32 v55, v55
	v_exp_f32_e32 v56, v56
	v_exp_f32_e32 v57, v57
	v_add_f32_e32 v50, 1.0, v50
	v_add_f32_e32 v51, 1.0, v51
	v_add_f32_e32 v52, 1.0, v52
	v_add_f32_e32 v53, 1.0, v53
	v_add_f32_e32 v54, 1.0, v54
	v_add_f32_e32 v55, 1.0, v55
	v_add_f32_e32 v56, 1.0, v56
	v_add_f32_e32 v57, 1.0, v57
	v_rcp_f32_e32 v50, v50
	v_rcp_f32_e32 v51, v51
	v_rcp_f32_e32 v52, v52
	v_rcp_f32_e32 v53, v53
	v_rcp_f32_e32 v54, v54
	v_rcp_f32_e32 v55, v55
	v_rcp_f32_e32 v56, v56
	v_rcp_f32_e32 v57, v57
	v_lshlrev_b32_e32 v58, 16, v18
	v_and_b32_e32 v59, 0xffff0000, v18
	v_lshlrev_b32_e32 v60, 16, v22
	v_and_b32_e32 v61, 0xffff0000, v22
	v_pk_fma_f32 v[50:51], v[50:51], v[58:59], v[60:61]
	v_lshlrev_b32_e32 v58, 16, v19
	v_and_b32_e32 v59, 0xffff0000, v19
	v_lshlrev_b32_e32 v60, 16, v23
	v_and_b32_e32 v61, 0xffff0000, v23
	v_pk_fma_f32 v[52:53], v[52:53], v[58:59], v[60:61]
	v_lshlrev_b32_e32 v58, 16, v20
	v_and_b32_e32 v59, 0xffff0000, v20
	v_lshlrev_b32_e32 v60, 16, v24
	v_and_b32_e32 v61, 0xffff0000, v24
	v_pk_fma_f32 v[54:55], v[54:55], v[58:59], v[60:61]
	v_lshlrev_b32_e32 v58, 16, v21
	v_and_b32_e32 v59, 0xffff0000, v21
	v_lshlrev_b32_e32 v60, 16, v25
	v_and_b32_e32 v61, 0xffff0000, v25
	v_pk_fma_f32 v[56:57], v[56:57], v[58:59], v[60:61]
	v_cvt_pk_bf16_f32 v18, v50, v51
	v_cvt_pk_bf16_f32 v19, v52, v53
	v_cvt_pk_bf16_f32 v20, v54, v55
	v_cvt_pk_bf16_f32 v21, v56, v57
	s_cbranch_vccz .Lgate_n_m2
	global_store_dwordx4 v225, v[18:21], s[8:9]
	s_add_u32 s8, s8, 0x2000
	s_addc_u32 s9, s9, 0
	s_branch .Lgate_n_j2

; __device__ __forceinline__ unsigned pk2(float lo, float hi) { f32x2_t v = {lo, hi}; bf16x2_t b = __builtin_convertvector(v, bf16x2_t); return __builtin_bit_cast(unsigned, b); }
; __device__ __forceinline__ float sigmoidf_(float x) { return __builtin_amdgcn_rcpf(1.0f + fexp2(-x * LOG2E)); }
;     __device__ __forceinline__ void operator()(AccRef acc, const pg8::Unit& u, int wr, int wc, int fr, int fq) const {
;     ...
;                 for (int m = 0; m < 4; ++m) {
;                     const size_t ci = ub + (size_t)((ai * 2 + bj) * 4 + m) * NTHREADS;
;                     const v4u pw = pw4[m], tw = tw4[m];
;                     const float rs = rst[(row0 + ai * 128 + m * 16) & 255];
;                     float v[8];
;                     v[0] = sigmoidf_(acc[ai][bj][m][0][0] * rs + bv0[0]) * bflo(pw.x); v[1] = sigmoidf_(acc[ai][bj][m][0][1] * rs + bv0[1]) * bfhi(pw.x);
;                     v[2] = sigmoidf_(acc[ai][bj][m][0][2] * rs + bv0[2]) * bflo(pw.y); v[3] = sigmoidf_(acc[ai][bj][m][0][3] * rs + bv0[3]) * bfhi(pw.y);
;                     v[4] = sigmoidf_(acc[ai][bj][m][1][0] * rs + bv1[0]) * bflo(pw.z); v[5] = sigmoidf_(acc[ai][bj][m][1][1] * rs + bv1[1]) * bfhi(pw.z);
;                     v[6] = sigmoidf_(acc[ai][bj][m][1][2] * rs + bv1[2]) * bflo(pw.w); v[7] = sigmoidf_(acc[ai][bj][m][1][3] * rs + bv1[3]) * bfhi(pw.w);
;                     v[0] += bflo(tw.x); v[1] += bfhi(tw.x); v[2] += bflo(tw.y); v[3] += bfhi(tw.y);
;                     v[4] += bflo(tw.z); v[5] += bfhi(tw.z); v[6] += bflo(tw.w); v[7] += bfhi(tw.w);
;                     v4u w; w.x = pk2(v[0], v[1]); w.y = pk2(v[2], v[3]); w.z = pk2(v[4], v[5]); w.w = pk2(v[6], v[7]);
;                     if (!last) TMP[ci] = w;
;                     else *(v4u*)(MRG + (size_t)(row0 + ai * 128 + m * 16) * D + col0 + bj * 128) = w;
.Lgate_n_j2:
	global_load_dwordx4 v[18:21], v224, s[6:7]
	global_load_dwordx4 v[22:25], v225, s[6:7]
	s_add_u32 s6, s6, 0x2000
	s_addc_u32 s7, s7, 0
	s_waitcnt vmcnt(13)
	v_fma_f32 v50, v142, v213, v194
	v_fma_f32 v51, v143, v213, v195
	v_fma_f32 v52, v144, v213, v196
	v_fma_f32 v53, v145, v213, v197
	v_fma_f32 v54, v138, v213, v198
	v_fma_f32 v55, v139, v213, v199
	v_fma_f32 v56, v140, v213, v200
	v_fma_f32 v57, v141, v213, v201
	v_exp_f32_e32 v50, v50
	v_exp_f32_e32 v51, v51
	v_exp_f32_e32 v52, v52
	v_exp_f32_e32 v53, v53
	v_exp_f32_e32 v54, v54
	v_exp_f32_e32 v55, v55
	v_exp_f32_e32 v56, v56
	v_exp_f32_e32 v57, v57
	v_add_f32_e32 v50, 1.0, v50
	v_add_f32_e32 v51, 1.0, v51
	v_add_f32_e32 v52, 1.0, v52
	v_add_f32_e32 v53, 1.0, v53
	v_add_f32_e32 v54, 1.0, v54
	v_add_f32_e32 v55, 1.0, v55
	v_add_f32_e32 v56, 1.0, v56
	v_add_f32_e32 v57, 1.0, v57
	v_rcp_f32_e32 v50, v50
	v_rcp_f32_e32 v51, v51
	v_rcp_f32_e32 v52, v52
	v_rcp_f32_e32 v53, v53
	v_rcp_f32_e32 v54, v54
	v_rcp_f32_e32 v55, v55
	v_rcp_f32_e32 v56, v56
	v_rcp_f32_e32 v57, v57
	v_lshlrev_b32_e32 v58, 16, v26
	v_and_b32_e32 v59, 0xffff0000, v26
	v_lshlrev_b32_e32 v60, 16, v30
	v_and_b32_e32 v61, 0xffff0000, v30
	v_pk_fma_f32 v[50:51], v[50:51], v[58:59], v[60:61]
	v_lshlrev_b32_e32 v58, 16, v27
	v_and_b32_e32 v59, 0xffff0000, v27
	v_lshlrev_b32_e32 v60, 16, v31
	v_and_b32_e32 v61, 0xffff0000, v31
	v_pk_fma_f32 v[52:53], v[52:53], v[58:59], v[60:61]
	v_lshlrev_b32_e32 v58, 16, v28
	v_and_b32_e32 v59, 0xffff0000, v28
	v_lshlrev_b32_e32 v60, 16, v32
	v_and_b32_e32 v61, 0xffff0000, v32
	v_pk_fma_f32 v[54:55], v[54:55], v[58:59], v[60:61]
	v_lshlrev_b32_e32 v58, 16, v29
	v_and_b32_e32 v59, 0xffff0000, v29
	v_lshlrev_b32_e32 v60, 16, v33
	v_and_b32_e32 v61, 0xffff0000, v33
	v_pk_fma_f32 v[56:57], v[56:57], v[58:59], v[60:61]
	v_cvt_pk_bf16_f32 v26, v50, v51
	v_cvt_pk_bf16_f32 v27, v52, v53
	v_cvt_pk_bf16_f32 v28, v54, v55
	v_cvt_pk_bf16_f32 v29, v56, v57
	s_cbranch_vccz .Lgate_n_m3
	global_store_dwordx4 v225, v[26:29], s[8:9]
	s_add_u32 s8, s8, 0x2000
	s_addc_u32 s9, s9, 0
	s_branch .Lgate_n_j3

; __device__ __forceinline__ unsigned pk2(float lo, float hi) { f32x2_t v = {lo, hi}; bf16x2_t b = __builtin_convertvector(v, bf16x2_t); return __builtin_bit_cast(unsigned, b); }
; __device__ __forceinline__ float sigmoidf_(float x) { return __builtin_amdgcn_rcpf(1.0f + fexp2(-x * LOG2E)); }
;     __device__ __forceinline__ void operator()(AccRef acc, const pg8::Unit& u, int wr, int wc, int fr, int fq) const {
;     ...
;                 for (int m = 0; m < 4; ++m) {
;                     const size_t ci = ub + (size_t)((ai * 2 + bj) * 4 + m) * NTHREADS;
;                     const v4u pw = pw4[m], tw = tw4[m];
;                     const float rs = rst[(row0 + ai * 128 + m * 16) & 255];
;                     float v[8];
;                     v[0] = sigmoidf_(acc[ai][bj][m][0][0] * rs + bv0[0]) * bflo(pw.x); v[1] = sigmoidf_(acc[ai][bj][m][0][1] * rs + bv0[1]) * bfhi(pw.x);
;                     v[2] = sigmoidf_(acc[ai][bj][m][0][2] * rs + bv0[2]) * bflo(pw.y); v[3] = sigmoidf_(acc[ai][bj][m][0][3] * rs + bv0[3]) * bfhi(pw.y);
;                     v[4] = sigmoidf_(acc[ai][bj][m][1][0] * rs + bv1[0]) * bflo(pw.z); v[5] = sigmoidf_(acc[ai][bj][m][1][1] * rs + bv1[1]) * bfhi(pw.z);
;                     v[6] = sigmoidf_(acc[ai][bj][m][1][2] * rs + bv1[2]) * bflo(pw.w); v[7] = sigmoidf_(acc[ai][bj][m][1][3] * rs + bv1[3]) * bfhi(pw.w);
;                     v[0] += bflo(tw.x); v[1] += bfhi(tw.x); v[2] += bflo(tw.y); v[3] += bfhi(tw.y);
;                     v[4] += bflo(tw.z); v[5] += bfhi(tw.z); v[6] += bflo(tw.w); v[7] += bfhi(tw.w);
;                     v4u w; w.x = pk2(v[0], v[1]); w.y = pk2(v[2], v[3]); w.z = pk2(v[4], v[5]); w.w = pk2(v[6], v[7]);
;                     if (!last) TMP[ci] = w;
;                     else *(v4u*)(MRG + (size_t)(row0 + ai * 128 + m * 16) * D + col0 + bj * 128) = w;
.Lgate_n_j3:
	global_load_dwordx4 v[26:29], v224, s[6:7]
	global_load_dwordx4 v[30:33], v225, s[6:7]
	s_add_u32 s6, s6, 0x2000
	s_addc_u32 s7, s7, 0
	s_waitcnt vmcnt(14)
	v_fma_f32 v50, v182, v210, v202
	v_fma_f32 v51, v183, v210, v203
	v_fma_f32 v52, v184, v210, v204
	v_fma_f32 v53, v185, v210, v205
	v_fma_f32 v54, v178, v210, v206
	v_fma_f32 v55, v179, v210, v207
	v_fma_f32 v56, v180, v210, v208
	v_fma_f32 v57, v181, v210, v209
	v_exp_f32_e32 v50, v50
	v_exp_f32_e32 v51, v51
	v_exp_f32_e32 v52, v52
	v_exp_f32_e32 v53, v53
	v_exp_f32_e32 v54, v54
	v_exp_f32_e32 v55, v55
	v_exp_f32_e32 v56, v56
	v_exp_f32_e32 v57, v57
	v_add_f32_e32 v50, 1.0, v50
	v_add_f32_e32 v51, 1.0, v51
	v_add_f32_e32 v52, 1.0, v52
	v_add_f32_e32 v53, 1.0, v53
	v_add_f32_e32 v54, 1.0, v54
	v_add_f32_e32 v55, 1.0, v55
	v_add_f32_e32 v56, 1.0, v56
	v_add_f32_e32 v57, 1.0, v57
	v_rcp_f32_e32 v50, v50
	v_rcp_f32_e32 v51, v51
	v_rcp_f32_e32 v52, v52
	v_rcp_f32_e32 v53, v53
	v_rcp_f32_e32 v54, v54
	v_rcp_f32_e32 v55, v55
	v_rcp_f32_e32 v56, v56
	v_rcp_f32_e32 v57, v57
	v_lshlrev_b32_e32 v58, 16, v34
	v_and_b32_e32 v59, 0xffff0000, v34
	v_lshlrev_b32_e32 v60, 16, v38
	v_and_b32_e32 v61, 0xffff0000, v38
	v_pk_fma_f32 v[50:51], v[50:51], v[58:59], v[60:61]
	v_lshlrev_b32_e32 v58, 16, v35
	v_and_b32_e32 v59, 0xffff0000, v35
	v_lshlrev_b32_e32 v60, 16, v39
	v_and_b32_e32 v61, 0xffff0000, v39
	v_pk_fma_f32 v[52:53], v[52:53], v[58:59], v[60:61]
	v_lshlrev_b32_e32 v58, 16, v36
	v_and_b32_e32 v59, 0xffff0000, v36
	v_lshlrev_b32_e32 v60, 16, v40
	v_and_b32_e32 v61, 0xffff0000, v40
	v_pk_fma_f32 v[54:55], v[54:55], v[58:59], v[60:61]
	v_lshlrev_b32_e32 v58, 16, v37
	v_and_b32_e32 v59, 0xffff0000, v37
	v_lshlrev_b32_e32 v60, 16, v41
	v_and_b32_e32 v61, 0xffff0000, v41
	v_pk_fma_f32 v[56:57], v[56:57], v[58:59], v[60:61]
	v_cvt_pk_bf16_f32 v34, v50, v51
	v_cvt_pk_bf16_f32 v35, v52, v53
	v_cvt_pk_bf16_f32 v36, v54, v55
	v_cvt_pk_bf16_f32 v37, v56, v57
	s_cbranch_vccz .Lgate_n_m4
	global_store_dwordx4 v225, v[34:37], s[8:9]
	s_add_u32 s8, s8, 0x2000
	s_addc_u32 s9, s9, 0
	s_branch .Lgate_n_j4

; __device__ __forceinline__ unsigned pk2(float lo, float hi) { f32x2_t v = {lo, hi}; bf16x2_t b = __builtin_convertvector(v, bf16x2_t); return __builtin_bit_cast(unsigned, b); }
; __device__ __forceinline__ float sigmoidf_(float x) { return __builtin_amdgcn_rcpf(1.0f + fexp2(-x * LOG2E)); }
;     __device__ __forceinline__ void operator()(AccRef acc, const pg8::Unit& u, int wr, int wc, int fr, int fq) const {
;     ...
;                 for (int m = 0; m < 4; ++m) {
;                     const size_t ci = ub + (size_t)((ai * 2 + bj) * 4 + m) * NTHREADS;
;                     const v4u pw = pw4[m], tw = tw4[m];
;                     const float rs = rst[(row0 + ai * 128 + m * 16) & 255];
;                     float v[8];
;                     v[0] = sigmoidf_(acc[ai][bj][m][0][0] * rs + bv0[0]) * bflo(pw.x); v[1] = sigmoidf_(acc[ai][bj][m][0][1] * rs + bv0[1]) * bfhi(pw.x);
;                     v[2] = sigmoidf_(acc[ai][bj][m][0][2] * rs + bv0[2]) * bflo(pw.y); v[3] = sigmoidf_(acc[ai][bj][m][0][3] * rs + bv0[3]) * bfhi(pw.y);
;                     v[4] = sigmoidf_(acc[ai][bj][m][1][0] * rs + bv1[0]) * bflo(pw.z); v[5] = sigmoidf_(acc[ai][bj][m][1][1] * rs + bv1[1]) * bfhi(pw.z);
;                     v[6] = sigmoidf_(acc[ai][bj][m][1][2] * rs + bv1[2]) * bflo(pw.w); v[7] = sigmoidf_(acc[ai][bj][m][1][3] * rs + bv1[3]) * bfhi(pw.w);
;                     v[0] += bflo(tw.x); v[1] += bfhi(tw.x); v[2] += bflo(tw.y); v[3] += bfhi(tw.y);
;                     v[4] += bflo(tw.z); v[5] += bfhi(tw.z); v[6] += bflo(tw.w); v[7] += bfhi(tw.w);
;                     v4u w; w.x = pk2(v[0], v[1]); w.y = pk2(v[2], v[3]); w.z = pk2(v[4], v[5]); w.w = pk2(v[6], v[7]);
;                     if (!last) TMP[ci] = w;
;                     else *(v4u*)(MRG + (size_t)(row0 + ai * 128 + m * 16) * D + col0 + bj * 128) = w;
.Lgate_n_j4:
	global_load_dwordx4 v[34:37], v224, s[6:7]
	global_load_dwordx4 v[38:41], v225, s[6:7]
	s_add_u32 s6, s6, 0x2000
	s_addc_u32 s7, s7, 0
	s_waitcnt vmcnt(15)
	v_fma_f32 v50, v166, v211, v202
	v_fma_f32 v51, v167, v211, v203
	v_fma_f32 v52, v168, v211, v204
	v_fma_f32 v53, v169, v211, v205
	v_fma_f32 v54, v162, v211, v206
	v_fma_f32 v55, v163, v211, v207
	v_fma_f32 v56, v164, v211, v208
	v_fma_f32 v57, v165, v211, v209
	v_exp_f32_e32 v50, v50
	v_exp_f32_e32 v51, v51
	v_exp_f32_e32 v52, v52
	v_exp_f32_e32 v53, v53
	v_exp_f32_e32 v54, v54
	v_exp_f32_e32 v55, v55
	v_exp_f32_e32 v56, v56
	v_exp_f32_e32 v57, v57
	v_add_f32_e32 v50, 1.0, v50
	v_add_f32_e32 v51, 1.0, v51
	v_add_f32_e32 v52, 1.0, v52
	v_add_f32_e32 v53, 1.0, v53
	v_add_f32_e32 v54, 1.0, v54
	v_add_f32_e32 v55, 1.0, v55
	v_add_f32_e32 v56, 1.0, v56
	v_add_f32_e32 v57, 1.0, v57
	v_rcp_f32_e32 v50, v50
	v_rcp_f32_e32 v51, v51
	v_rcp_f32_e32 v52, v52
	v_rcp_f32_e32 v53, v53
	v_rcp_f32_e32 v54, v54
	v_rcp_f32_e32 v55, v55
	v_rcp_f32_e32 v56, v56
	v_rcp_f32_e32 v57, v57
	v_lshlrev_b32_e32 v58, 16, v42
	v_and_b32_e32 v59, 0xffff0000, v42
	v_lshlrev_b32_e32 v60, 16, v46
	v_and_b32_e32 v61, 0xffff0000, v46
	v_pk_fma_f32 v[50:51], v[50:51], v[58:59], v[60:61]
	v_lshlrev_b32_e32 v58, 16, v43
	v_and_b32_e32 v59, 0xffff0000, v43
	v_lshlrev_b32_e32 v60, 16, v47
	v_and_b32_e32 v61, 0xffff0000, v47
	v_pk_fma_f32 v[52:53], v[52:53], v[58:59], v[60:61]
	v_lshlrev_b32_e32 v58, 16, v44
	v_and_b32_e32 v59, 0xffff0000, v44
	v_lshlrev_b32_e32 v60, 16, v48
	v_and_b32_e32 v61, 0xffff0000, v48
	v_pk_fma_f32 v[54:55], v[54:55], v[58:59], v[60:61]
	v_lshlrev_b32_e32 v58, 16, v45
	v_and_b32_e32 v59, 0xffff0000, v45
	v_lshlrev_b32_e32 v60, 16, v49
	v_and_b32_e32 v61, 0xffff0000, v49
	v_pk_fma_f32 v[56:57], v[56:57], v[58:59], v[60:61]
	v_cvt_pk_bf16_f32 v42, v50, v51
	v_cvt_pk_bf16_f32 v43, v52, v53
	v_cvt_pk_bf16_f32 v44, v54, v55
	v_cvt_pk_bf16_f32 v45, v56, v57
	s_cbranch_vccz .Lgate_n_m5
	global_store_dwordx4 v225, v[42:45], s[8:9]
	s_add_u32 s8, s8, 0x2000
	s_addc_u32 s9, s9, 0
	s_branch .Lgate_n_j5

; __device__ __forceinline__ unsigned pk2(float lo, float hi) { f32x2_t v = {lo, hi}; bf16x2_t b = __builtin_convertvector(v, bf16x2_t); return __builtin_bit_cast(unsigned, b); }
; __device__ __forceinline__ float sigmoidf_(float x) { return __builtin_amdgcn_rcpf(1.0f + fexp2(-x * LOG2E)); }
;     __device__ __forceinline__ void operator()(AccRef acc, const pg8::Unit& u, int wr, int wc, int fr, int fq) const {
;     ...
;                 for (int m = 0; m < 4; ++m) {
;                     const size_t ci = ub + (size_t)((ai * 2 + bj) * 4 + m) * NTHREADS;
;                     const v4u pw = pw4[m], tw = tw4[m];
;                     const float rs = rst[(row0 + ai * 128 + m * 16) & 255];
;                     float v[8];
;                     v[0] = sigmoidf_(acc[ai][bj][m][0][0] * rs + bv0[0]) * bflo(pw.x); v[1] = sigmoidf_(acc[ai][bj][m][0][1] * rs + bv0[1]) * bfhi(pw.x);
;                     v[2] = sigmoidf_(acc[ai][bj][m][0][2] * rs + bv0[2]) * bflo(pw.y); v[3] = sigmoidf_(acc[ai][bj][m][0][3] * rs + bv0[3]) * bfhi(pw.y);
;                     v[4] = sigmoidf_(acc[ai][bj][m][1][0] * rs + bv1[0]) * bflo(pw.z); v[5] = sigmoidf_(acc[ai][bj][m][1][1] * rs + bv1[1]) * bfhi(pw.z);
;                     v[6] = sigmoidf_(acc[ai][bj][m][1][2] * rs + bv1[2]) * bflo(pw.w); v[7] = sigmoidf_(acc[ai][bj][m][1][3] * rs + bv1[3]) * bfhi(pw.w);
;                     v[0] += bflo(tw.x); v[1] += bfhi(tw.x); v[2] += bflo(tw.y); v[3] += bfhi(tw.y);
;                     v[4] += bflo(tw.z); v[5] += bfhi(tw.z); v[6] += bflo(tw.w); v[7] += bfhi(tw.w);
;                     v4u w; w.x = pk2(v[0], v[1]); w.y = pk2(v[2], v[3]); w.z = pk2(v[4], v[5]); w.w = pk2(v[6], v[7]);
;                     if (!last) TMP[ci] = w;
;                     else *(v4u*)(MRG + (size_t)(row0 + ai * 128 + m * 16) * D + col0 + bj * 128) = w;
.Lgate_n_j5:
	global_load_dwordx4 v[42:45], v224, s[6:7]
	global_load_dwordx4 v[46:49], v225, s[6:7]
	s_add_u32 s6, s6, 0x2000
	s_addc_u32 s7, s7, 0
	s_waitcnt vmcnt(15)
	v_fma_f32 v50, v150, v212, v202
	v_fma_f32 v51, v151, v212, v203
	v_fma_f32 v52, v152, v212, v204
	v_fma_f32 v53, v153, v212, v205
	v_fma_f32 v54, v146, v212, v206
	v_fma_f32 v55, v147, v212, v207
	v_fma_f32 v56, v148, v212, v208
	v_fma_f32 v57, v149, v212, v209
	v_exp_f32_e32 v50, v50
	v_exp_f32_e32 v51, v51
	v_exp_f32_e32 v52, v52
	v_exp_f32_e32 v53, v53
	v_exp_f32_e32 v54, v54
	v_exp_f32_e32 v55, v55
	v_exp_f32_e32 v56, v56
	v_exp_f32_e32 v57, v57
	v_add_f32_e32 v50, 1.0, v50
	v_add_f32_e32 v51, 1.0, v51
	v_add_f32_e32 v52, 1.0, v52
	v_add_f32_e32 v53, 1.0, v53
	v_add_f32_e32 v54, 1.0, v54
	v_add_f32_e32 v55, 1.0, v55
	v_add_f32_e32 v56, 1.0, v56
	v_add_f32_e32 v57, 1.0, v57
	v_rcp_f32_e32 v50, v50
	v_rcp_f32_e32 v51, v51
	v_rcp_f32_e32 v52, v52
	v_rcp_f32_e32 v53, v53
	v_rcp_f32_e32 v54, v54
	v_rcp_f32_e32 v55, v55
	v_rcp_f32_e32 v56, v56
	v_rcp_f32_e32 v57, v57
	v_lshlrev_b32_e32 v58, 16, v2
	v_and_b32_e32 v59, 0xffff0000, v2
	v_lshlrev_b32_e32 v60, 16, v6
	v_and_b32_e32 v61, 0xffff0000, v6
	v_pk_fma_f32 v[50:51], v[50:51], v[58:59], v[60:61]
	v_lshlrev_b32_e32 v58, 16, v3
	v_and_b32_e32 v59, 0xffff0000, v3
	v_lshlrev_b32_e32 v60, 16, v7
	v_and_b32_e32 v61, 0xffff0000, v7
	v_pk_fma_f32 v[52:53], v[52:53], v[58:59], v[60:61]
	v_lshlrev_b32_e32 v58, 16, v4
	v_and_b32_e32 v59, 0xffff0000, v4
	v_lshlrev_b32_e32 v60, 16, v8
	v_and_b32_e32 v61, 0xffff0000, v8
	v_pk_fma_f32 v[54:55], v[54:55], v[58:59], v[60:61]
	v_lshlrev_b32_e32 v58, 16, v5
	v_and_b32_e32 v59, 0xffff0000, v5
	v_lshlrev_b32_e32 v60, 16, v9
	v_and_b32_e32 v61, 0xffff0000, v9
	v_pk_fma_f32 v[56:57], v[56:57], v[58:59], v[60:61]
	v_cvt_pk_bf16_f32 v2, v50, v51
	v_cvt_pk_bf16_f32 v3, v52, v53
	v_cvt_pk_bf16_f32 v4, v54, v55
	v_cvt_pk_bf16_f32 v5, v56, v57
	s_cbranch_vccz .Lgate_n_m6
	global_store_dwordx4 v225, v[2:5], s[8:9]
	s_add_u32 s8, s8, 0x2000
	s_addc_u32 s9, s9, 0
	s_branch .Lgate_n_j6

; __device__ __forceinline__ unsigned pk2(float lo, float hi) { f32x2_t v = {lo, hi}; bf16x2_t b = __builtin_convertvector(v, bf16x2_t); return __builtin_bit_cast(unsigned, b); }
; __device__ __forceinline__ float sigmoidf_(float x) { return __builtin_amdgcn_rcpf(1.0f + fexp2(-x * LOG2E)); }
;     __device__ __forceinline__ void operator()(AccRef acc, const pg8::Unit& u, int wr, int wc, int fr, int fq) const {
;     ...
;                 for (int m = 0; m < 4; ++m) {
;                     const size_t ci = ub + (size_t)((ai * 2 + bj) * 4 + m) * NTHREADS;
;                     const v4u pw = pw4[m], tw = tw4[m];
;                     const float rs = rst[(row0 + ai * 128 + m * 16) & 255];
;                     float v[8];
;                     v[0] = sigmoidf_(acc[ai][bj][m][0][0] * rs + bv0[0]) * bflo(pw.x); v[1] = sigmoidf_(acc[ai][bj][m][0][1] * rs + bv0[1]) * bfhi(pw.x);
;                     v[2] = sigmoidf_(acc[ai][bj][m][0][2] * rs + bv0[2]) * bflo(pw.y); v[3] = sigmoidf_(acc[ai][bj][m][0][3] * rs + bv0[3]) * bfhi(pw.y);
;                     v[4] = sigmoidf_(acc[ai][bj][m][1][0] * rs + bv1[0]) * bflo(pw.z); v[5] = sigmoidf_(acc[ai][bj][m][1][1] * rs + bv1[1]) * bfhi(pw.z);
;                     v[6] = sigmoidf_(acc[ai][bj][m][1][2] * rs + bv1[2]) * bflo(pw.w); v[7] = sigmoidf_(acc[ai][bj][m][1][3] * rs + bv1[3]) * bfhi(pw.w);
;                     v[0] += bflo(tw.x); v[1] += bfhi(tw.x); v[2] += bflo(tw.y); v[3] += bfhi(tw.y);
;                     v[4] += bflo(tw.z); v[5] += bfhi(tw.z); v[6] += bflo(tw.w); v[7] += bfhi(tw.w);
;                     v4u w; w.x = pk2(v[0], v[1]); w.y = pk2(v[2], v[3]); w.z = pk2(v[4], v[5]); w.w = pk2(v[6], v[7]);
;                     if (!last) TMP[ci] = w;
;                     else *(v4u*)(MRG + (size_t)(row0 + ai * 128 + m * 16) * D + col0 + bj * 128) = w;
.Lgate_n_j6:
	global_load_dwordx4 v[2:5], v224, s[6:7]
	global_load_dwordx4 v[6:9], v225, s[6:7]
	s_add_u32 s6, s6, 0x2000
	s_addc_u32 s7, s7, 0
	s_waitcnt vmcnt(15)
	v_fma_f32 v50, v134, v213, v202
	v_fma_f32 v51, v135, v213, v203
	v_fma_f32 v52, v136, v213, v204
	v_fma_f32 v53, v137, v213, v205
	v_fma_f32 v54, v130, v213, v206
	v_fma_f32 v55, v131, v213, v207
	v_fma_f32 v56, v132, v213, v208
	v_fma_f32 v57, v133, v213, v209
	v_exp_f32_e32 v50, v50
	v_exp_f32_e32 v51, v51
	v_exp_f32_e32 v52, v52
	v_exp_f32_e32 v53, v53
	v_exp_f32_e32 v54, v54
	v_exp_f32_e32 v55, v55
	v_exp_f32_e32 v56, v56
	v_exp_f32_e32 v57, v57
	v_add_f32_e32 v50, 1.0, v50
	v_add_f32_e32 v51, 1.0, v51
	v_add_f32_e32 v52, 1.0, v52
	v_add_f32_e32 v53, 1.0, v53
	v_add_f32_e32 v54, 1.0, v54
	v_add_f32_e32 v55, 1.0, v55
	v_add_f32_e32 v56, 1.0, v56
	v_add_f32_e32 v57, 1.0, v57
	v_rcp_f32_e32 v50, v50
	v_rcp_f32_e32 v51, v51
	v_rcp_f32_e32 v52, v52
	v_rcp_f32_e32 v53, v53
	v_rcp_f32_e32 v54, v54
	v_rcp_f32_e32 v55, v55
	v_rcp_f32_e32 v56, v56
	v_rcp_f32_e32 v57, v57
	v_lshlrev_b32_e32 v58, 16, v10
	v_and_b32_e32 v59, 0xffff0000, v10
	v_lshlrev_b32_e32 v60, 16, v14
	v_and_b32_e32 v61, 0xffff0000, v14
	v_pk_fma_f32 v[50:51], v[50:51], v[58:59], v[60:61]
	v_lshlrev_b32_e32 v58, 16, v11
	v_and_b32_e32 v59, 0xffff0000, v11
	v_lshlrev_b32_e32 v60, 16, v15
	v_and_b32_e32 v61, 0xffff0000, v15
	v_pk_fma_f32 v[52:53], v[52:53], v[58:59], v[60:61]
	v_lshlrev_b32_e32 v58, 16, v12
	v_and_b32_e32 v59, 0xffff0000, v12
	v_lshlrev_b32_e32 v60, 16, v16
	v_and_b32_e32 v61, 0xffff0000, v16
	v_pk_fma_f32 v[54:55], v[54:55], v[58:59], v[60:61]
	v_lshlrev_b32_e32 v58, 16, v13
	v_and_b32_e32 v59, 0xffff0000, v13
	v_lshlrev_b32_e32 v60, 16, v17
	v_and_b32_e32 v61, 0xffff0000, v17
	v_pk_fma_f32 v[56:57], v[56:57], v[58:59], v[60:61]
	v_cvt_pk_bf16_f32 v10, v50, v51
	v_cvt_pk_bf16_f32 v11, v52, v53
	v_cvt_pk_bf16_f32 v12, v54, v55
	v_cvt_pk_bf16_f32 v13, v56, v57
	s_cbranch_vccz .Lgate_n_m7
	global_store_dwordx4 v225, v[10:13], s[8:9]
	s_add_u32 s8, s8, 0x2000
	s_addc_u32 s9, s9, 0
	s_branch .Lgate_n_j7

; __device__ __forceinline__ unsigned pk2(float lo, float hi) { f32x2_t v = {lo, hi}; bf16x2_t b = __builtin_convertvector(v, bf16x2_t); return __builtin_bit_cast(unsigned, b); }
; __device__ __forceinline__ float sigmoidf_(float x) { return __builtin_amdgcn_rcpf(1.0f + fexp2(-x * LOG2E)); }
;     __device__ __forceinline__ void operator()(AccRef acc, const pg8::Unit& u, int wr, int wc, int fr, int fq) const {
;     ...
;                 for (int m = 0; m < 4; ++m) {
;                     const size_t ci = ub + (size_t)((ai * 2 + bj) * 4 + m) * NTHREADS;
;                     const v4u pw = pw4[m], tw = tw4[m];
;                     const float rs = rst[(row0 + ai * 128 + m * 16) & 255];
;                     float v[8];
;                     v[0] = sigmoidf_(acc[ai][bj][m][0][0] * rs + bv0[0]) * bflo(pw.x); v[1] = sigmoidf_(acc[ai][bj][m][0][1] * rs + bv0[1]) * bfhi(pw.x);
;                     v[2] = sigmoidf_(acc[ai][bj][m][0][2] * rs + bv0[2]) * bflo(pw.y); v[3] = sigmoidf_(acc[ai][bj][m][0][3] * rs + bv0[3]) * bfhi(pw.y);
;                     v[4] = sigmoidf_(acc[ai][bj][m][1][0] * rs + bv1[0]) * bflo(pw.z); v[5] = sigmoidf_(acc[ai][bj][m][1][1] * rs + bv1[1]) * bfhi(pw.z);
;                     v[6] = sigmoidf_(acc[ai][bj][m][1][2] * rs + bv1[2]) * bflo(pw.w); v[7] = sigmoidf_(acc[ai][bj][m][1][3] * rs + bv1[3]) * bfhi(pw.w);
;                     v[0] += bflo(tw.x); v[1] += bfhi(tw.x); v[2] += bflo(tw.y); v[3] += bfhi(tw.y);
;                     v[4] += bflo(tw.z); v[5] += bfhi(tw.z); v[6] += bflo(tw.w); v[7] += bfhi(tw.w);
;                     v4u w; w.x = pk2(v[0], v[1]); w.y = pk2(v[2], v[3]); w.z = pk2(v[4], v[5]); w.w = pk2(v[6], v[7]);
;                     if (!last) TMP[ci] = w;
;                     else *(v4u*)(MRG + (size_t)(row0 + ai * 128 + m * 16) * D + col0 + bj * 128) = w;
.Lgate_n_j7:
	global_load_dwordx4 v[10:13], v224, s[6:7]
	global_load_dwordx4 v[14:17], v225, s[6:7]
	s_add_u32 s6, s6, 0x2000
	s_addc_u32 s7, s7, 0
	s_waitcnt vmcnt(15)
	v_fma_f32 v50, v126, v228, v194
	v_fma_f32 v51, v127, v228, v195
	v_fma_f32 v52, v128, v228, v196
	v_fma_f32 v53, v129, v228, v197
	v_fma_f32 v54, v122, v228, v198
	v_fma_f32 v55, v123, v228, v199
	v_fma_f32 v56, v124, v228, v200
	v_fma_f32 v57, v125, v228, v201
	v_exp_f32_e32 v50, v50
	v_exp_f32_e32 v51, v51
	v_exp_f32_e32 v52, v52
	v_exp_f32_e32 v53, v53
	v_exp_f32_e32 v54, v54
	v_exp_f32_e32 v55, v55
	v_exp_f32_e32 v56, v56
	v_exp_f32_e32 v57, v57
	v_add_f32_e32 v50, 1.0, v50
	v_add_f32_e32 v51, 1.0, v51
	v_add_f32_e32 v52, 1.0, v52
	v_add_f32_e32 v53, 1.0, v53
	v_add_f32_e32 v54, 1.0, v54
	v_add_f32_e32 v55, 1.0, v55
	v_add_f32_e32 v56, 1.0, v56
	v_add_f32_e32 v57, 1.0, v57
	v_rcp_f32_e32 v50, v50
	v_rcp_f32_e32 v51, v51
	v_rcp_f32_e32 v52, v52
	v_rcp_f32_e32 v53, v53
	v_rcp_f32_e32 v54, v54
	v_rcp_f32_e32 v55, v55
	v_rcp_f32_e32 v56, v56
	v_rcp_f32_e32 v57, v57
	v_lshlrev_b32_e32 v58, 16, v18
	v_and_b32_e32 v59, 0xffff0000, v18
	v_lshlrev_b32_e32 v60, 16, v22
	v_and_b32_e32 v61, 0xffff0000, v22
	v_pk_fma_f32 v[50:51], v[50:51], v[58:59], v[60:61]
	v_lshlrev_b32_e32 v58, 16, v19
	v_and_b32_e32 v59, 0xffff0000, v19
	v_lshlrev_b32_e32 v60, 16, v23
	v_and_b32_e32 v61, 0xffff0000, v23
	v_pk_fma_f32 v[52:53], v[52:53], v[58:59], v[60:61]
	v_lshlrev_b32_e32 v58, 16, v20
	v_and_b32_e32 v59, 0xffff0000, v20
	v_lshlrev_b32_e32 v60, 16, v24
	v_and_b32_e32 v61, 0xffff0000, v24
	v_pk_fma_f32 v[54:55], v[54:55], v[58:59], v[60:61]
	v_lshlrev_b32_e32 v58, 16, v21
	v_and_b32_e32 v59, 0xffff0000, v21
	v_lshlrev_b32_e32 v60, 16, v25
	v_and_b32_e32 v61, 0xffff0000, v25
	v_pk_fma_f32 v[56:57], v[56:57], v[58:59], v[60:61]
	v_cvt_pk_bf16_f32 v18, v50, v51
	v_cvt_pk_bf16_f32 v19, v52, v53
	v_cvt_pk_bf16_f32 v20, v54, v55
	v_cvt_pk_bf16_f32 v21, v56, v57
	s_cbranch_vccz .Lgate_n_m8
	global_store_dwordx4 v225, v[18:21], s[8:9]
	s_add_u32 s8, s8, 0x2000
	s_addc_u32 s9, s9, 0
	s_branch .Lgate_n_j8

; __device__ __forceinline__ unsigned pk2(float lo, float hi) { f32x2_t v = {lo, hi}; bf16x2_t b = __builtin_convertvector(v, bf16x2_t); return __builtin_bit_cast(unsigned, b); }
; __device__ __forceinline__ float sigmoidf_(float x) { return __builtin_amdgcn_rcpf(1.0f + fexp2(-x * LOG2E)); }
;     __device__ __forceinline__ void operator()(AccRef acc, const pg8::Unit& u, int wr, int wc, int fr, int fq) const {
;     ...
;                 for (int m = 0; m < 4; ++m) {
;                     const size_t ci = ub + (size_t)((ai * 2 + bj) * 4 + m) * NTHREADS;
;                     const v4u pw = pw4[m], tw = tw4[m];
;                     const float rs = rst[(row0 + ai * 128 + m * 16) & 255];
;                     float v[8];
;                     v[0] = sigmoidf_(acc[ai][bj][m][0][0] * rs + bv0[0]) * bflo(pw.x); v[1] = sigmoidf_(acc[ai][bj][m][0][1] * rs + bv0[1]) * bfhi(pw.x);
;                     v[2] = sigmoidf_(acc[ai][bj][m][0][2] * rs + bv0[2]) * bflo(pw.y); v[3] = sigmoidf_(acc[ai][bj][m][0][3] * rs + bv0[3]) * bfhi(pw.y);
;                     v[4] = sigmoidf_(acc[ai][bj][m][1][0] * rs + bv1[0]) * bflo(pw.z); v[5] = sigmoidf_(acc[ai][bj][m][1][1] * rs + bv1[1]) * bfhi(pw.z);
;                     v[6] = sigmoidf_(acc[ai][bj][m][1][2] * rs + bv1[2]) * bflo(pw.w); v[7] = sigmoidf_(acc[ai][bj][m][1][3] * rs + bv1[3]) * bfhi(pw.w);
;                     v[0] += bflo(tw.x); v[1] += bfhi(tw.x); v[2] += bflo(tw.y); v[3] += bfhi(tw.y);
;                     v[4] += bflo(tw.z); v[5] += bfhi(tw.z); v[6] += bflo(tw.w); v[7] += bfhi(tw.w);
;                     v4u w; w.x = pk2(v[0], v[1]); w.y = pk2(v[2], v[3]); w.z = pk2(v[4], v[5]); w.w = pk2(v[6], v[7]);
;                     if (!last) TMP[ci] = w;
;                     else *(v4u*)(MRG + (size_t)(row0 + ai * 128 + m * 16) * D + col0 + bj * 128) = w;
.Lgate_n_j8:
	global_load_dwordx4 v[18:21], v224, s[6:7]
	global_load_dwordx4 v[22:25], v225, s[6:7]
	s_add_u32 s6, s6, 0x2000
	s_addc_u32 s7, s7, 0
	s_waitcnt vmcnt(15)
	v_fma_f32 v50, v110, v229, v194
	v_fma_f32 v51, v111, v229, v195
	v_fma_f32 v52, v112, v229, v196
	v_fma_f32 v53, v113, v229, v197
	v_fma_f32 v54, v106, v229, v198
	v_fma_f32 v55, v107, v229, v199
	v_fma_f32 v56, v108, v229, v200
	v_fma_f32 v57, v109, v229, v201
	v_exp_f32_e32 v50, v50
	v_exp_f32_e32 v51, v51
	v_exp_f32_e32 v52, v52
	v_exp_f32_e32 v53, v53
	v_exp_f32_e32 v54, v54
	v_exp_f32_e32 v55, v55
	v_exp_f32_e32 v56, v56
	v_exp_f32_e32 v57, v57
	v_add_f32_e32 v50, 1.0, v50
	v_add_f32_e32 v51, 1.0, v51
	v_add_f32_e32 v52, 1.0, v52
	v_add_f32_e32 v53, 1.0, v53
	v_add_f32_e32 v54, 1.0, v54
	v_add_f32_e32 v55, 1.0, v55
	v_add_f32_e32 v56, 1.0, v56
	v_add_f32_e32 v57, 1.0, v57
	v_rcp_f32_e32 v50, v50
	v_rcp_f32_e32 v51, v51
	v_rcp_f32_e32 v52, v52
	v_rcp_f32_e32 v53, v53
	v_rcp_f32_e32 v54, v54
	v_rcp_f32_e32 v55, v55
	v_rcp_f32_e32 v56, v56
	v_rcp_f32_e32 v57, v57
	v_lshlrev_b32_e32 v58, 16, v26
	v_and_b32_e32 v59, 0xffff0000, v26
	v_lshlrev_b32_e32 v60, 16, v30
	v_and_b32_e32 v61, 0xffff0000, v30
	v_pk_fma_f32 v[50:51], v[50:51], v[58:59], v[60:61]
	v_lshlrev_b32_e32 v58, 16, v27
	v_and_b32_e32 v59, 0xffff0000, v27
	v_lshlrev_b32_e32 v60, 16, v31
	v_and_b32_e32 v61, 0xffff0000, v31
	v_pk_fma_f32 v[52:53], v[52:53], v[58:59], v[60:61]
	v_lshlrev_b32_e32 v58, 16, v28
	v_and_b32_e32 v59, 0xffff0000, v28
	v_lshlrev_b32_e32 v60, 16, v32
	v_and_b32_e32 v61, 0xffff0000, v32
	v_pk_fma_f32 v[54:55], v[54:55], v[58:59], v[60:61]
	v_lshlrev_b32_e32 v58, 16, v29
	v_and_b32_e32 v59, 0xffff0000, v29
	v_lshlrev_b32_e32 v60, 16, v33
	v_and_b32_e32 v61, 0xffff0000, v33
	v_pk_fma_f32 v[56:57], v[56:57], v[58:59], v[60:61]
	v_cvt_pk_bf16_f32 v26, v50, v51
	v_cvt_pk_bf16_f32 v27, v52, v53
	v_cvt_pk_bf16_f32 v28, v54, v55
	v_cvt_pk_bf16_f32 v29, v56, v57
	s_cbranch_vccz .Lgate_n_m9
	global_store_dwordx4 v225, v[26:29], s[8:9]
	s_add_u32 s8, s8, 0x2000
	s_addc_u32 s9, s9, 0
	s_branch .Lgate_n_j9

; __device__ __forceinline__ unsigned pk2(float lo, float hi) { f32x2_t v = {lo, hi}; bf16x2_t b = __builtin_convertvector(v, bf16x2_t); return __builtin_bit_cast(unsigned, b); }
; __device__ __forceinline__ float sigmoidf_(float x) { return __builtin_amdgcn_rcpf(1.0f + fexp2(-x * LOG2E)); }
;     __device__ __forceinline__ void operator()(AccRef acc, const pg8::Unit& u, int wr, int wc, int fr, int fq) const {
;     ...
;                 for (int m = 0; m < 4; ++m) {
;                     const size_t ci = ub + (size_t)((ai * 2 + bj) * 4 + m) * NTHREADS;
;                     const v4u pw = pw4[m], tw = tw4[m];
;                     const float rs = rst[(row0 + ai * 128 + m * 16) & 255];
;                     float v[8];
;                     v[0] = sigmoidf_(acc[ai][bj][m][0][0] * rs + bv0[0]) * bflo(pw.x); v[1] = sigmoidf_(acc[ai][bj][m][0][1] * rs + bv0[1]) * bfhi(pw.x);
;                     v[2] = sigmoidf_(acc[ai][bj][m][0][2] * rs + bv0[2]) * bflo(pw.y); v[3] = sigmoidf_(acc[ai][bj][m][0][3] * rs + bv0[3]) * bfhi(pw.y);
;                     v[4] = sigmoidf_(acc[ai][bj][m][1][0] * rs + bv1[0]) * bflo(pw.z); v[5] = sigmoidf_(acc[ai][bj][m][1][1] * rs + bv1[1]) * bfhi(pw.z);
;                     v[6] = sigmoidf_(acc[ai][bj][m][1][2] * rs + bv1[2]) * bflo(pw.w); v[7] = sigmoidf_(acc[ai][bj][m][1][3] * rs + bv1[3]) * bfhi(pw.w);
;                     v[0] += bflo(tw.x); v[1] += bfhi(tw.x); v[2] += bflo(tw.y); v[3] += bfhi(tw.y);
;                     v[4] += bflo(tw.z); v[5] += bfhi(tw.z); v[6] += bflo(tw.w); v[7] += bfhi(tw.w);
;                     v4u w; w.x = pk2(v[0], v[1]); w.y = pk2(v[2], v[3]); w.z = pk2(v[4], v[5]); w.w = pk2(v[6], v[7]);
;                     if (!last) TMP[ci] = w;
;                     else *(v4u*)(MRG + (size_t)(row0 + ai * 128 + m * 16) * D + col0 + bj * 128) = w;
.Lgate_n_j9:
	global_load_dwordx4 v[26:29], v224, s[6:7]
	global_load_dwordx4 v[30:33], v225, s[6:7]
	s_add_u32 s6, s6, 0x2000
	s_addc_u32 s7, s7, 0
	s_waitcnt vmcnt(15)
	v_fma_f32 v50, v94, v230, v194
	v_fma_f32 v51, v95, v230, v195
	v_fma_f32 v52, v96, v230, v196
	v_fma_f32 v53, v97, v230, v197
	v_fma_f32 v54, v90, v230, v198
	v_fma_f32 v55, v91, v230, v199
	v_fma_f32 v56, v92, v230, v200
	v_fma_f32 v57, v93, v230, v201
	v_exp_f32_e32 v50, v50
	v_exp_f32_e32 v51, v51
	v_exp_f32_e32 v52, v52
	v_exp_f32_e32 v53, v53
	v_exp_f32_e32 v54, v54
	v_exp_f32_e32 v55, v55
	v_exp_f32_e32 v56, v56
	v_exp_f32_e32 v57, v57
	v_add_f32_e32 v50, 1.0, v50
	v_add_f32_e32 v51, 1.0, v51
	v_add_f32_e32 v52, 1.0, v52
	v_add_f32_e32 v53, 1.0, v53
	v_add_f32_e32 v54, 1.0, v54
	v_add_f32_e32 v55, 1.0, v55
	v_add_f32_e32 v56, 1.0, v56
	v_add_f32_e32 v57, 1.0, v57
	v_rcp_f32_e32 v50, v50
	v_rcp_f32_e32 v51, v51
	v_rcp_f32_e32 v52, v52
	v_rcp_f32_e32 v53, v53
	v_rcp_f32_e32 v54, v54
	v_rcp_f32_e32 v55, v55
	v_rcp_f32_e32 v56, v56
	v_rcp_f32_e32 v57, v57
	v_lshlrev_b32_e32 v58, 16, v34
	v_and_b32_e32 v59, 0xffff0000, v34
	v_lshlrev_b32_e32 v60, 16, v38
	v_and_b32_e32 v61, 0xffff0000, v38
	v_pk_fma_f32 v[50:51], v[50:51], v[58:59], v[60:61]
	v_lshlrev_b32_e32 v58, 16, v35
	v_and_b32_e32 v59, 0xffff0000, v35
	v_lshlrev_b32_e32 v60, 16, v39
	v_and_b32_e32 v61, 0xffff0000, v39
	v_pk_fma_f32 v[52:53], v[52:53], v[58:59], v[60:61]
	v_lshlrev_b32_e32 v58, 16, v36
	v_and_b32_e32 v59, 0xffff0000, v36
	v_lshlrev_b32_e32 v60, 16, v40
	v_and_b32_e32 v61, 0xffff0000, v40
	v_pk_fma_f32 v[54:55], v[54:55], v[58:59], v[60:61]
	v_lshlrev_b32_e32 v58, 16, v37
	v_and_b32_e32 v59, 0xffff0000, v37
	v_lshlrev_b32_e32 v60, 16, v41
	v_and_b32_e32 v61, 0xffff0000, v41
	v_pk_fma_f32 v[56:57], v[56:57], v[58:59], v[60:61]
	v_cvt_pk_bf16_f32 v34, v50, v51
	v_cvt_pk_bf16_f32 v35, v52, v53
	v_cvt_pk_bf16_f32 v36, v54, v55
	v_cvt_pk_bf16_f32 v37, v56, v57
	s_cbranch_vccz .Lgate_n_m10
	global_store_dwordx4 v225, v[34:37], s[8:9]
	s_add_u32 s8, s8, 0x2000
	s_addc_u32 s9, s9, 0
	s_branch .Lgate_n_j10

; __device__ __forceinline__ unsigned pk2(float lo, float hi) { f32x2_t v = {lo, hi}; bf16x2_t b = __builtin_convertvector(v, bf16x2_t); return __builtin_bit_cast(unsigned, b); }
; __device__ __forceinline__ float sigmoidf_(float x) { return __builtin_amdgcn_rcpf(1.0f + fexp2(-x * LOG2E)); }
;     __device__ __forceinline__ void operator()(AccRef acc, const pg8::Unit& u, int wr, int wc, int fr, int fq) const {
;     ...
;                 for (int m = 0; m < 4; ++m) {
;                     const size_t ci = ub + (size_t)((ai * 2 + bj) * 4 + m) * NTHREADS;
;                     const v4u pw = pw4[m], tw = tw4[m];
;                     const float rs = rst[(row0 + ai * 128 + m * 16) & 255];
;                     float v[8];
;                     v[0] = sigmoidf_(acc[ai][bj][m][0][0] * rs + bv0[0]) * bflo(pw.x); v[1] = sigmoidf_(acc[ai][bj][m][0][1] * rs + bv0[1]) * bfhi(pw.x);
;                     v[2] = sigmoidf_(acc[ai][bj][m][0][2] * rs + bv0[2]) * bflo(pw.y); v[3] = sigmoidf_(acc[ai][bj][m][0][3] * rs + bv0[3]) * bfhi(pw.y);
;                     v[4] = sigmoidf_(acc[ai][bj][m][1][0] * rs + bv1[0]) * bflo(pw.z); v[5] = sigmoidf_(acc[ai][bj][m][1][1] * rs + bv1[1]) * bfhi(pw.z);
;                     v[6] = sigmoidf_(acc[ai][bj][m][1][2] * rs + bv1[2]) * bflo(pw.w); v[7] = sigmoidf_(acc[ai][bj][m][1][3] * rs + bv1[3]) * bfhi(pw.w);
;                     v[0] += bflo(tw.x); v[1] += bfhi(tw.x); v[2] += bflo(tw.y); v[3] += bfhi(tw.y);
;                     v[4] += bflo(tw.z); v[5] += bfhi(tw.z); v[6] += bflo(tw.w); v[7] += bfhi(tw.w);
;                     v4u w; w.x = pk2(v[0], v[1]); w.y = pk2(v[2], v[3]); w.z = pk2(v[4], v[5]); w.w = pk2(v[6], v[7]);
;                     if (!last) TMP[ci] = w;
;                     else *(v4u*)(MRG + (size_t)(row0 + ai * 128 + m * 16) * D + col0 + bj * 128) = w;
.Lgate_n_j10:
	s_waitcnt vmcnt(13)
	v_fma_f32 v50, v78, v231, v194
	v_fma_f32 v51, v79, v231, v195
	v_fma_f32 v52, v80, v231, v196
	v_fma_f32 v53, v81, v231, v197
	v_fma_f32 v54, v74, v231, v198
	v_fma_f32 v55, v75, v231, v199
	v_fma_f32 v56, v76, v231, v200
	v_fma_f32 v57, v77, v231, v201
	v_exp_f32_e32 v50, v50
	v_exp_f32_e32 v51, v51
	v_exp_f32_e32 v52, v52
	v_exp_f32_e32 v53, v53
	v_exp_f32_e32 v54, v54
	v_exp_f32_e32 v55, v55
	v_exp_f32_e32 v56, v56
	v_exp_f32_e32 v57, v57
	v_add_f32_e32 v50, 1.0, v50
	v_add_f32_e32 v51, 1.0, v51
	v_add_f32_e32 v52, 1.0, v52
	v_add_f32_e32 v53, 1.0, v53
	v_add_f32_e32 v54, 1.0, v54
	v_add_f32_e32 v55, 1.0, v55
	v_add_f32_e32 v56, 1.0, v56
	v_add_f32_e32 v57, 1.0, v57
	v_rcp_f32_e32 v50, v50
	v_rcp_f32_e32 v51, v51
	v_rcp_f32_e32 v52, v52
	v_rcp_f32_e32 v53, v53
	v_rcp_f32_e32 v54, v54
	v_rcp_f32_e32 v55, v55
	v_rcp_f32_e32 v56, v56
	v_rcp_f32_e32 v57, v57
	v_lshlrev_b32_e32 v58, 16, v42
	v_and_b32_e32 v59, 0xffff0000, v42
	v_lshlrev_b32_e32 v60, 16, v46
	v_and_b32_e32 v61, 0xffff0000, v46
	v_pk_fma_f32 v[50:51], v[50:51], v[58:59], v[60:61]
	v_lshlrev_b32_e32 v58, 16, v43
	v_and_b32_e32 v59, 0xffff0000, v43
	v_lshlrev_b32_e32 v60, 16, v47
	v_and_b32_e32 v61, 0xffff0000, v47
	v_pk_fma_f32 v[52:53], v[52:53], v[58:59], v[60:61]
	v_lshlrev_b32_e32 v58, 16, v44
	v_and_b32_e32 v59, 0xffff0000, v44
	v_lshlrev_b32_e32 v60, 16, v48
	v_and_b32_e32 v61, 0xffff0000, v48
	v_pk_fma_f32 v[54:55], v[54:55], v[58:59], v[60:61]
	v_lshlrev_b32_e32 v58, 16, v45
	v_and_b32_e32 v59, 0xffff0000, v45
	v_lshlrev_b32_e32 v60, 16, v49
	v_and_b32_e32 v61, 0xffff0000, v49
	v_pk_fma_f32 v[56:57], v[56:57], v[58:59], v[60:61]
	v_cvt_pk_bf16_f32 v42, v50, v51
	v_cvt_pk_bf16_f32 v43, v52, v53
	v_cvt_pk_bf16_f32 v44, v54, v55
	v_cvt_pk_bf16_f32 v45, v56, v57
	s_cbranch_vccz .Lgate_n_m11
	global_store_dwordx4 v225, v[42:45], s[8:9]
	s_add_u32 s8, s8, 0x2000
	s_addc_u32 s9, s9, 0
	s_branch .Lgate_n_j11

; __device__ __forceinline__ unsigned pk2(float lo, float hi) { f32x2_t v = {lo, hi}; bf16x2_t b = __builtin_convertvector(v, bf16x2_t); return __builtin_bit_cast(unsigned, b); }
; __device__ __forceinline__ float sigmoidf_(float x) { return __builtin_amdgcn_rcpf(1.0f + fexp2(-x * LOG2E)); }
;     __device__ __forceinline__ void operator()(AccRef acc, const pg8::Unit& u, int wr, int wc, int fr, int fq) const {
;     ...
;                 for (int m = 0; m < 4; ++m) {
;                     const size_t ci = ub + (size_t)((ai * 2 + bj) * 4 + m) * NTHREADS;
;                     const v4u pw = pw4[m], tw = tw4[m];
;                     const float rs = rst[(row0 + ai * 128 + m * 16) & 255];
;                     float v[8];
;                     v[0] = sigmoidf_(acc[ai][bj][m][0][0] * rs + bv0[0]) * bflo(pw.x); v[1] = sigmoidf_(acc[ai][bj][m][0][1] * rs + bv0[1]) * bfhi(pw.x);
;                     v[2] = sigmoidf_(acc[ai][bj][m][0][2] * rs + bv0[2]) * bflo(pw.y); v[3] = sigmoidf_(acc[ai][bj][m][0][3] * rs + bv0[3]) * bfhi(pw.y);
;                     v[4] = sigmoidf_(acc[ai][bj][m][1][0] * rs + bv1[0]) * bflo(pw.z); v[5] = sigmoidf_(acc[ai][bj][m][1][1] * rs + bv1[1]) * bfhi(pw.z);
;                     v[6] = sigmoidf_(acc[ai][bj][m][1][2] * rs + bv1[2]) * bflo(pw.w); v[7] = sigmoidf_(acc[ai][bj][m][1][3] * rs + bv1[3]) * bfhi(pw.w);
;                     v[0] += bflo(tw.x); v[1] += bfhi(tw.x); v[2] += bflo(tw.y); v[3] += bfhi(tw.y);
;                     v[4] += bflo(tw.z); v[5] += bfhi(tw.z); v[6] += bflo(tw.w); v[7] += bfhi(tw.w);
;                     v4u w; w.x = pk2(v[0], v[1]); w.y = pk2(v[2], v[3]); w.z = pk2(v[4], v[5]); w.w = pk2(v[6], v[7]);
;                     if (!last) TMP[ci] = w;
;                     else *(v4u*)(MRG + (size_t)(row0 + ai * 128 + m * 16) * D + col0 + bj * 128) = w;
.Lgate_n_j11:
	s_waitcnt vmcnt(11)
	v_fma_f32 v50, v118, v228, v202
	v_fma_f32 v51, v119, v228, v203
	v_fma_f32 v52, v120, v228, v204
	v_fma_f32 v53, v121, v228, v205
	v_fma_f32 v54, v114, v228, v206
	v_fma_f32 v55, v115, v228, v207
	v_fma_f32 v56, v116, v228, v208
	v_fma_f32 v57, v117, v228, v209
	v_exp_f32_e32 v50, v50
	v_exp_f32_e32 v51, v51
	v_exp_f32_e32 v52, v52
	v_exp_f32_e32 v53, v53
	v_exp_f32_e32 v54, v54
	v_exp_f32_e32 v55, v55
	v_exp_f32_e32 v56, v56
	v_exp_f32_e32 v57, v57
	v_add_f32_e32 v50, 1.0, v50
	v_add_f32_e32 v51, 1.0, v51
	v_add_f32_e32 v52, 1.0, v52
	v_add_f32_e32 v53, 1.0, v53
	v_add_f32_e32 v54, 1.0, v54
	v_add_f32_e32 v55, 1.0, v55
	v_add_f32_e32 v56, 1.0, v56
	v_add_f32_e32 v57, 1.0, v57
	v_rcp_f32_e32 v50, v50
	v_rcp_f32_e32 v51, v51
	v_rcp_f32_e32 v52, v52
	v_rcp_f32_e32 v53, v53
	v_rcp_f32_e32 v54, v54
	v_rcp_f32_e32 v55, v55
	v_rcp_f32_e32 v56, v56
	v_rcp_f32_e32 v57, v57
	v_lshlrev_b32_e32 v58, 16, v2
	v_and_b32_e32 v59, 0xffff0000, v2
	v_lshlrev_b32_e32 v60, 16, v6
	v_and_b32_e32 v61, 0xffff0000, v6
	v_pk_fma_f32 v[50:51], v[50:51], v[58:59], v[60:61]
	v_lshlrev_b32_e32 v58, 16, v3
	v_and_b32_e32 v59, 0xffff0000, v3
	v_lshlrev_b32_e32 v60, 16, v7
	v_and_b32_e32 v61, 0xffff0000, v7
	v_pk_fma_f32 v[52:53], v[52:53], v[58:59], v[60:61]
	v_lshlrev_b32_e32 v58, 16, v4
	v_and_b32_e32 v59, 0xffff0000, v4
	v_lshlrev_b32_e32 v60, 16, v8
	v_and_b32_e32 v61, 0xffff0000, v8
	v_pk_fma_f32 v[54:55], v[54:55], v[58:59], v[60:61]
	v_lshlrev_b32_e32 v58, 16, v5
	v_and_b32_e32 v59, 0xffff0000, v5
	v_lshlrev_b32_e32 v60, 16, v9
	v_and_b32_e32 v61, 0xffff0000, v9
	v_pk_fma_f32 v[56:57], v[56:57], v[58:59], v[60:61]
	v_cvt_pk_bf16_f32 v2, v50, v51
	v_cvt_pk_bf16_f32 v3, v52, v53
	v_cvt_pk_bf16_f32 v4, v54, v55
	v_cvt_pk_bf16_f32 v5, v56, v57
	s_cbranch_vccz .Lgate_n_m12
	global_store_dwordx4 v225, v[2:5], s[8:9]
	s_add_u32 s8, s8, 0x2000
	s_addc_u32 s9, s9, 0
	s_branch .Lgate_n_j12

; __device__ __forceinline__ unsigned pk2(float lo, float hi) { f32x2_t v = {lo, hi}; bf16x2_t b = __builtin_convertvector(v, bf16x2_t); return __builtin_bit_cast(unsigned, b); }
; __device__ __forceinline__ float sigmoidf_(float x) { return __builtin_amdgcn_rcpf(1.0f + fexp2(-x * LOG2E)); }
;     __device__ __forceinline__ void operator()(AccRef acc, const pg8::Unit& u, int wr, int wc, int fr, int fq) const {
;     ...
;                 for (int m = 0; m < 4; ++m) {
;                     const size_t ci = ub + (size_t)((ai * 2 + bj) * 4 + m) * NTHREADS;
;                     const v4u pw = pw4[m], tw = tw4[m];
;                     const float rs = rst[(row0 + ai * 128 + m * 16) & 255];
;                     float v[8];
;                     v[0] = sigmoidf_(acc[ai][bj][m][0][0] * rs + bv0[0]) * bflo(pw.x); v[1] = sigmoidf_(acc[ai][bj][m][0][1] * rs + bv0[1]) * bfhi(pw.x);
;                     v[2] = sigmoidf_(acc[ai][bj][m][0][2] * rs + bv0[2]) * bflo(pw.y); v[3] = sigmoidf_(acc[ai][bj][m][0][3] * rs + bv0[3]) * bfhi(pw.y);
;                     v[4] = sigmoidf_(acc[ai][bj][m][1][0] * rs + bv1[0]) * bflo(pw.z); v[5] = sigmoidf_(acc[ai][bj][m][1][1] * rs + bv1[1]) * bfhi(pw.z);
;                     v[6] = sigmoidf_(acc[ai][bj][m][1][2] * rs + bv1[2]) * bflo(pw.w); v[7] = sigmoidf_(acc[ai][bj][m][1][3] * rs + bv1[3]) * bfhi(pw.w);
;                     v[0] += bflo(tw.x); v[1] += bfhi(tw.x); v[2] += bflo(tw.y); v[3] += bfhi(tw.y);
;                     v[4] += bflo(tw.z); v[5] += bfhi(tw.z); v[6] += bflo(tw.w); v[7] += bfhi(tw.w);
;                     v4u w; w.x = pk2(v[0], v[1]); w.y = pk2(v[2], v[3]); w.z = pk2(v[4], v[5]); w.w = pk2(v[6], v[7]);
;                     if (!last) TMP[ci] = w;
;                     else *(v4u*)(MRG + (size_t)(row0 + ai * 128 + m * 16) * D + col0 + bj * 128) = w;
.Lgate_n_j12:
	s_waitcnt vmcnt(9)
	v_fma_f32 v50, v102, v229, v202
	v_fma_f32 v51, v103, v229, v203
	v_fma_f32 v52, v104, v229, v204
	v_fma_f32 v53, v105, v229, v205
	v_fma_f32 v54, v98, v229, v206
	v_fma_f32 v55, v99, v229, v207
	v_fma_f32 v56, v100, v229, v208
	v_fma_f32 v57, v101, v229, v209
	v_exp_f32_e32 v50, v50
	v_exp_f32_e32 v51, v51
	v_exp_f32_e32 v52, v52
	v_exp_f32_e32 v53, v53
	v_exp_f32_e32 v54, v54
	v_exp_f32_e32 v55, v55
	v_exp_f32_e32 v56, v56
	v_exp_f32_e32 v57, v57
	v_add_f32_e32 v50, 1.0, v50
	v_add_f32_e32 v51, 1.0, v51
	v_add_f32_e32 v52, 1.0, v52
	v_add_f32_e32 v53, 1.0, v53
	v_add_f32_e32 v54, 1.0, v54
	v_add_f32_e32 v55, 1.0, v55
	v_add_f32_e32 v56, 1.0, v56
	v_add_f32_e32 v57, 1.0, v57
	v_rcp_f32_e32 v50, v50
	v_rcp_f32_e32 v51, v51
	v_rcp_f32_e32 v52, v52
	v_rcp_f32_e32 v53, v53
	v_rcp_f32_e32 v54, v54
	v_rcp_f32_e32 v55, v55
	v_rcp_f32_e32 v56, v56
	v_rcp_f32_e32 v57, v57
	v_lshlrev_b32_e32 v58, 16, v10
	v_and_b32_e32 v59, 0xffff0000, v10
	v_lshlrev_b32_e32 v60, 16, v14
	v_and_b32_e32 v61, 0xffff0000, v14
	v_pk_fma_f32 v[50:51], v[50:51], v[58:59], v[60:61]
	v_lshlrev_b32_e32 v58, 16, v11
	v_and_b32_e32 v59, 0xffff0000, v11
	v_lshlrev_b32_e32 v60, 16, v15
	v_and_b32_e32 v61, 0xffff0000, v15
	v_pk_fma_f32 v[52:53], v[52:53], v[58:59], v[60:61]
	v_lshlrev_b32_e32 v58, 16, v12
	v_and_b32_e32 v59, 0xffff0000, v12
	v_lshlrev_b32_e32 v60, 16, v16
	v_and_b32_e32 v61, 0xffff0000, v16
	v_pk_fma_f32 v[54:55], v[54:55], v[58:59], v[60:61]
	v_lshlrev_b32_e32 v58, 16, v13
	v_and_b32_e32 v59, 0xffff0000, v13
	v_lshlrev_b32_e32 v60, 16, v17
	v_and_b32_e32 v61, 0xffff0000, v17
	v_pk_fma_f32 v[56:57], v[56:57], v[58:59], v[60:61]
	v_cvt_pk_bf16_f32 v10, v50, v51
	v_cvt_pk_bf16_f32 v11, v52, v53
	v_cvt_pk_bf16_f32 v12, v54, v55
	v_cvt_pk_bf16_f32 v13, v56, v57
	s_cbranch_vccz .Lgate_n_m13
	global_store_dwordx4 v225, v[10:13], s[8:9]
	s_add_u32 s8, s8, 0x2000
	s_addc_u32 s9, s9, 0
	s_branch .Lgate_n_j13

; __device__ __forceinline__ unsigned pk2(float lo, float hi) { f32x2_t v = {lo, hi}; bf16x2_t b = __builtin_convertvector(v, bf16x2_t); return __builtin_bit_cast(unsigned, b); }
; __device__ __forceinline__ float sigmoidf_(float x) { return __builtin_amdgcn_rcpf(1.0f + fexp2(-x * LOG2E)); }
;     __device__ __forceinline__ void operator()(AccRef acc, const pg8::Unit& u, int wr, int wc, int fr, int fq) const {
;     ...
;                 for (int m = 0; m < 4; ++m) {
;                     const size_t ci = ub + (size_t)((ai * 2 + bj) * 4 + m) * NTHREADS;
;                     const v4u pw = pw4[m], tw = tw4[m];
;                     const float rs = rst[(row0 + ai * 128 + m * 16) & 255];
;                     float v[8];
;                     v[0] = sigmoidf_(acc[ai][bj][m][0][0] * rs + bv0[0]) * bflo(pw.x); v[1] = sigmoidf_(acc[ai][bj][m][0][1] * rs + bv0[1]) * bfhi(pw.x);
;                     v[2] = sigmoidf_(acc[ai][bj][m][0][2] * rs + bv0[2]) * bflo(pw.y); v[3] = sigmoidf_(acc[ai][bj][m][0][3] * rs + bv0[3]) * bfhi(pw.y);
;                     v[4] = sigmoidf_(acc[ai][bj][m][1][0] * rs + bv1[0]) * bflo(pw.z); v[5] = sigmoidf_(acc[ai][bj][m][1][1] * rs + bv1[1]) * bfhi(pw.z);
;                     v[6] = sigmoidf_(acc[ai][bj][m][1][2] * rs + bv1[2]) * bflo(pw.w); v[7] = sigmoidf_(acc[ai][bj][m][1][3] * rs + bv1[3]) * bfhi(pw.w);
;                     v[0] += bflo(tw.x); v[1] += bfhi(tw.x); v[2] += bflo(tw.y); v[3] += bfhi(tw.y);
;                     v[4] += bflo(tw.z); v[5] += bfhi(tw.z); v[6] += bflo(tw.w); v[7] += bfhi(tw.w);
;                     v4u w; w.x = pk2(v[0], v[1]); w.y = pk2(v[2], v[3]); w.z = pk2(v[4], v[5]); w.w = pk2(v[6], v[7]);
;                     if (!last) TMP[ci] = w;
;                     else *(v4u*)(MRG + (size_t)(row0 + ai * 128 + m * 16) * D + col0 + bj * 128) = w;
.Lgate_n_j13:
	s_waitcnt vmcnt(7)
	v_fma_f32 v50, v86, v230, v202
	v_fma_f32 v51, v87, v230, v203
	v_fma_f32 v52, v88, v230, v204
	v_fma_f32 v53, v89, v230, v205
	v_fma_f32 v54, v82, v230, v206
	v_fma_f32 v55, v83, v230, v207
	v_fma_f32 v56, v84, v230, v208
	v_fma_f32 v57, v85, v230, v209
	v_exp_f32_e32 v50, v50
	v_exp_f32_e32 v51, v51
	v_exp_f32_e32 v52, v52
	v_exp_f32_e32 v53, v53
	v_exp_f32_e32 v54, v54
	v_exp_f32_e32 v55, v55
	v_exp_f32_e32 v56, v56
	v_exp_f32_e32 v57, v57
	v_add_f32_e32 v50, 1.0, v50
	v_add_f32_e32 v51, 1.0, v51
	v_add_f32_e32 v52, 1.0, v52
	v_add_f32_e32 v53, 1.0, v53
	v_add_f32_e32 v54, 1.0, v54
	v_add_f32_e32 v55, 1.0, v55
	v_add_f32_e32 v56, 1.0, v56
	v_add_f32_e32 v57, 1.0, v57
	v_rcp_f32_e32 v50, v50
	v_rcp_f32_e32 v51, v51
	v_rcp_f32_e32 v52, v52
	v_rcp_f32_e32 v53, v53
	v_rcp_f32_e32 v54, v54
	v_rcp_f32_e32 v55, v55
	v_rcp_f32_e32 v56, v56
	v_rcp_f32_e32 v57, v57
	v_lshlrev_b32_e32 v58, 16, v18
	v_and_b32_e32 v59, 0xffff0000, v18
	v_lshlrev_b32_e32 v60, 16, v22
	v_and_b32_e32 v61, 0xffff0000, v22
	v_pk_fma_f32 v[50:51], v[50:51], v[58:59], v[60:61]
	v_lshlrev_b32_e32 v58, 16, v19
	v_and_b32_e32 v59, 0xffff0000, v19
	v_lshlrev_b32_e32 v60, 16, v23
	v_and_b32_e32 v61, 0xffff0000, v23
	v_pk_fma_f32 v[52:53], v[52:53], v[58:59], v[60:61]
	v_lshlrev_b32_e32 v58, 16, v20
	v_and_b32_e32 v59, 0xffff0000, v20
	v_lshlrev_b32_e32 v60, 16, v24
	v_and_b32_e32 v61, 0xffff0000, v24
	v_pk_fma_f32 v[54:55], v[54:55], v[58:59], v[60:61]
	v_lshlrev_b32_e32 v58, 16, v21
	v_and_b32_e32 v59, 0xffff0000, v21
	v_lshlrev_b32_e32 v60, 16, v25
	v_and_b32_e32 v61, 0xffff0000, v25
	v_pk_fma_f32 v[56:57], v[56:57], v[58:59], v[60:61]
	v_cvt_pk_bf16_f32 v18, v50, v51
	v_cvt_pk_bf16_f32 v19, v52, v53
	v_cvt_pk_bf16_f32 v20, v54, v55
	v_cvt_pk_bf16_f32 v21, v56, v57
	s_cbranch_vccz .Lgate_n_m14
	global_store_dwordx4 v225, v[18:21], s[8:9]
	s_add_u32 s8, s8, 0x2000
	s_addc_u32 s9, s9, 0
	s_branch .Lgate_n_j14

; __device__ __forceinline__ unsigned pk2(float lo, float hi) { f32x2_t v = {lo, hi}; bf16x2_t b = __builtin_convertvector(v, bf16x2_t); return __builtin_bit_cast(unsigned, b); }
; __device__ __forceinline__ float sigmoidf_(float x) { return __builtin_amdgcn_rcpf(1.0f + fexp2(-x * LOG2E)); }
;     __device__ __forceinline__ void operator()(AccRef acc, const pg8::Unit& u, int wr, int wc, int fr, int fq) const {
;     ...
;                 for (int m = 0; m < 4; ++m) {
;                     const size_t ci = ub + (size_t)((ai * 2 + bj) * 4 + m) * NTHREADS;
;                     const v4u pw = pw4[m], tw = tw4[m];
;                     const float rs = rst[(row0 + ai * 128 + m * 16) & 255];
;                     float v[8];
;                     v[0] = sigmoidf_(acc[ai][bj][m][0][0] * rs + bv0[0]) * bflo(pw.x); v[1] = sigmoidf_(acc[ai][bj][m][0][1] * rs + bv0[1]) * bfhi(pw.x);
;                     v[2] = sigmoidf_(acc[ai][bj][m][0][2] * rs + bv0[2]) * bflo(pw.y); v[3] = sigmoidf_(acc[ai][bj][m][0][3] * rs + bv0[3]) * bfhi(pw.y);
;                     v[4] = sigmoidf_(acc[ai][bj][m][1][0] * rs + bv1[0]) * bflo(pw.z); v[5] = sigmoidf_(acc[ai][bj][m][1][1] * rs + bv1[1]) * bfhi(pw.z);
;                     v[6] = sigmoidf_(acc[ai][bj][m][1][2] * rs + bv1[2]) * bflo(pw.w); v[7] = sigmoidf_(acc[ai][bj][m][1][3] * rs + bv1[3]) * bfhi(pw.w);
;                     v[0] += bflo(tw.x); v[1] += bfhi(tw.x); v[2] += bflo(tw.y); v[3] += bfhi(tw.y);
;                     v[4] += bflo(tw.z); v[5] += bfhi(tw.z); v[6] += bflo(tw.w); v[7] += bfhi(tw.w);
;                     v4u w; w.x = pk2(v[0], v[1]); w.y = pk2(v[2], v[3]); w.z = pk2(v[4], v[5]); w.w = pk2(v[6], v[7]);
;                     if (!last) TMP[ci] = w;
;                     else *(v4u*)(MRG + (size_t)(row0 + ai * 128 + m * 16) * D + col0 + bj * 128) = w;
.Lgate_n_j14:
	s_waitcnt vmcnt(5)
	v_fma_f32 v50, v70, v231, v202
	v_fma_f32 v51, v71, v231, v203
	v_fma_f32 v52, v72, v231, v204
	v_fma_f32 v53, v73, v231, v205
	v_fma_f32 v54, v66, v231, v206
	v_fma_f32 v55, v67, v231, v207
	v_fma_f32 v56, v68, v231, v208
	v_fma_f32 v57, v69, v231, v209
	v_exp_f32_e32 v50, v50
	v_exp_f32_e32 v51, v51
	v_exp_f32_e32 v52, v52
	v_exp_f32_e32 v53, v53
	v_exp_f32_e32 v54, v54
	v_exp_f32_e32 v55, v55
	v_exp_f32_e32 v56, v56
	v_exp_f32_e32 v57, v57
	v_add_f32_e32 v50, 1.0, v50
	v_add_f32_e32 v51, 1.0, v51
	v_add_f32_e32 v52, 1.0, v52
	v_add_f32_e32 v53, 1.0, v53
	v_add_f32_e32 v54, 1.0, v54
	v_add_f32_e32 v55, 1.0, v55
	v_add_f32_e32 v56, 1.0, v56
	v_add_f32_e32 v57, 1.0, v57
	v_rcp_f32_e32 v50, v50
	v_rcp_f32_e32 v51, v51
	v_rcp_f32_e32 v52, v52
	v_rcp_f32_e32 v53, v53
	v_rcp_f32_e32 v54, v54
	v_rcp_f32_e32 v55, v55
	v_rcp_f32_e32 v56, v56
	v_rcp_f32_e32 v57, v57
	v_lshlrev_b32_e32 v58, 16, v26
	v_and_b32_e32 v59, 0xffff0000, v26
	v_lshlrev_b32_e32 v60, 16, v30
	v_and_b32_e32 v61, 0xffff0000, v30
	v_pk_fma_f32 v[50:51], v[50:51], v[58:59], v[60:61]
	v_lshlrev_b32_e32 v58, 16, v27
	v_and_b32_e32 v59, 0xffff0000, v27
	v_lshlrev_b32_e32 v60, 16, v31
	v_and_b32_e32 v61, 0xffff0000, v31
	v_pk_fma_f32 v[52:53], v[52:53], v[58:59], v[60:61]
	v_lshlrev_b32_e32 v58, 16, v28
	v_and_b32_e32 v59, 0xffff0000, v28
	v_lshlrev_b32_e32 v60, 16, v32
	v_and_b32_e32 v61, 0xffff0000, v32
	v_pk_fma_f32 v[54:55], v[54:55], v[58:59], v[60:61]
	v_lshlrev_b32_e32 v58, 16, v29
	v_and_b32_e32 v59, 0xffff0000, v29
	v_lshlrev_b32_e32 v60, 16, v33
	v_and_b32_e32 v61, 0xffff0000, v33
	v_pk_fma_f32 v[56:57], v[56:57], v[58:59], v[60:61]
	v_cvt_pk_bf16_f32 v26, v50, v51
	v_cvt_pk_bf16_f32 v27, v52, v53
	v_cvt_pk_bf16_f32 v28, v54, v55
	v_cvt_pk_bf16_f32 v29, v56, v57
	s_cbranch_vccz .Lgate_n_m15
	global_store_dwordx4 v225, v[26:29], s[8:9]
	s_branch .Lgate_n_j15

; __device__ __forceinline__ void attention_phase(PPtr p, int layer, LAS unsigned char* L, unsigned* counter, const bool do_store) {
;     ...
;             { const float inv = lam / (l + __shfl_xor(l, 32));
;               float ss = 0.f;
; #pragma unroll
;               for (int db = 0; db < 4; ++db)
; #pragma unroll
;                   for (int i = 0; i < 8; ++i) {
;                       const unsigned w0 = o0p[(db * 8 + i) * NTHREADS];
;                       const float a = bflo(w0) - o[db][2 * i] * inv, c = bfhi(w0) - o[db][2 * i + 1] * inv;
;                       o[db][2 * i] = a; o[db][2 * i + 1] = c; ss += a * a + c * c;
;                   }
;               ss += __shfl_xor(ss, 32);
.LBB0_496:
	s_load_dword s1, s[50:51], 0xc0
	ds_bpermute_b32 v66, v159, v176
	v_sub_f32_e32 v0, v241, v242
	s_waitcnt lgkmcnt(0)
	v_add_f32_e32 v0, s1, v0
	v_add_f32_e32 v66, v176, v66
	v_div_scale_f32 v67, s[2:3], v66, v66, v0
	v_rcp_f32_e32 v68, v67
	s_mov_b32 s2, 0x800000
	v_fma_f32 v69, -v67, v68, 1.0
	v_fmac_f32_e32 v68, v69, v68
	v_div_scale_f32 v69, vcc, v0, v66, v0
	v_mul_f32_e32 v70, v69, v68
	v_fma_f32 v71, -v67, v70, v69
	v_fmac_f32_e32 v70, v71, v68
	v_fma_f32 v67, -v67, v70, v69
	v_div_fmas_f32 v67, v67, v68, v70
	v_div_fixup_f32 v72, v67, v66, v0
	ds_read2st64_b32 v[66:67], v210 offset1:8
	v_mov_b32_e32 v70, v10
	v_mov_b32_e32 v71, v12
	v_mov_b32_e32 v12, v11
	v_lshlrev_b32_e32 v0, 3, v230
	s_waitcnt lgkmcnt(0)
	v_lshlrev_b32_e32 v128, 16, v66
	v_and_b32_e32 v129, 0xffff0000, v66
	s_waitcnt vmcnt(2)
	v_lshlrev_b32_e32 v130, 16, v67
	v_and_b32_e32 v131, 0xffff0000, v67
	ds_read2st64_b32 v[66:67], v210 offset0:16 offset1:24
	s_waitcnt lgkmcnt(0)
	v_lshlrev_b32_e32 v122, 16, v66
	v_and_b32_e32 v123, 0xffff0000, v66
	v_lshlrev_b32_e32 v126, 16, v67
	v_and_b32_e32 v127, 0xffff0000, v67
	ds_read2st64_b32 v[66:67], v210 offset0:32 offset1:40
	s_waitcnt lgkmcnt(0)
	v_lshlrev_b32_e32 v118, 16, v66
	v_and_b32_e32 v119, 0xffff0000, v66
	v_lshlrev_b32_e32 v124, 16, v67
	v_and_b32_e32 v125, 0xffff0000, v67
	ds_read2st64_b32 v[66:67], v210 offset0:48 offset1:56
	s_waitcnt lgkmcnt(0)
	v_lshlrev_b32_e32 v114, 16, v66
	v_and_b32_e32 v115, 0xffff0000, v66
	v_lshlrev_b32_e32 v120, 16, v67
	v_and_b32_e32 v121, 0xffff0000, v67
	ds_read2st64_b32 v[66:67], v210 offset0:64 offset1:72
	s_waitcnt lgkmcnt(0)
	v_lshlrev_b32_e32 v110, 16, v66
	v_and_b32_e32 v111, 0xffff0000, v66
	v_lshlrev_b32_e32 v116, 16, v67
	v_and_b32_e32 v117, 0xffff0000, v67
	ds_read2st64_b32 v[66:67], v210 offset0:80 offset1:88
	s_waitcnt lgkmcnt(0)
	v_lshlrev_b32_e32 v106, 16, v66
	v_and_b32_e32 v107, 0xffff0000, v66
	v_lshlrev_b32_e32 v112, 16, v67
	v_and_b32_e32 v113, 0xffff0000, v67
	ds_read2st64_b32 v[66:67], v210 offset0:96 offset1:104
	s_waitcnt lgkmcnt(0)
	v_lshlrev_b32_e32 v102, 16, v66
	v_and_b32_e32 v103, 0xffff0000, v66
	v_lshlrev_b32_e32 v108, 16, v67
	v_and_b32_e32 v109, 0xffff0000, v67
	ds_read2st64_b32 v[66:67], v210 offset0:112 offset1:120
	s_waitcnt lgkmcnt(0)
	v_lshlrev_b32_e32 v98, 16, v66
	v_and_b32_e32 v99, 0xffff0000, v66
	v_lshlrev_b32_e32 v104, 16, v67
	v_and_b32_e32 v105, 0xffff0000, v67
	ds_read2st64_b32 v[66:67], v210 offset0:128 offset1:136
	s_waitcnt lgkmcnt(0)
	v_lshlrev_b32_e32 v94, 16, v66
	v_and_b32_e32 v95, 0xffff0000, v66
	v_lshlrev_b32_e32 v100, 16, v67
	v_and_b32_e32 v101, 0xffff0000, v67
	ds_read2st64_b32 v[66:67], v210 offset0:144 offset1:152
	s_waitcnt lgkmcnt(0)
	v_lshlrev_b32_e32 v90, 16, v66
	v_and_b32_e32 v91, 0xffff0000, v66
	v_lshlrev_b32_e32 v96, 16, v67
	v_and_b32_e32 v97, 0xffff0000, v67
	ds_read2st64_b32 v[66:67], v210 offset0:160 offset1:168
	s_waitcnt lgkmcnt(0)
	v_lshlrev_b32_e32 v86, 16, v66
	v_and_b32_e32 v87, 0xffff0000, v66
	v_lshlrev_b32_e32 v92, 16, v67
	v_and_b32_e32 v93, 0xffff0000, v67
	ds_read2st64_b32 v[66:67], v210 offset0:176 offset1:184
	s_waitcnt lgkmcnt(0)
	v_lshlrev_b32_e32 v84, 16, v66
	v_and_b32_e32 v85, 0xffff0000, v66
	v_lshlrev_b32_e32 v88, 16, v67
	v_and_b32_e32 v89, 0xffff0000, v67
	ds_read2st64_b32 v[66:67], v210 offset0:192 offset1:200
	s_waitcnt lgkmcnt(0)
	v_lshlrev_b32_e32 v80, 16, v66
	v_and_b32_e32 v81, 0xffff0000, v66
	v_lshlrev_b32_e32 v82, 16, v67
	v_and_b32_e32 v83, 0xffff0000, v67
	ds_read2st64_b32 v[66:67], v210 offset0:208 offset1:216
	s_waitcnt lgkmcnt(0)
	v_lshlrev_b32_e32 v76, 16, v66
	v_and_b32_e32 v77, 0xffff0000, v66
	v_lshlrev_b32_e32 v78, 16, v67
	v_and_b32_e32 v79, 0xffff0000, v67
	ds_read2st64_b32 v[66:67], v210 offset0:224 offset1:232
	s_waitcnt lgkmcnt(0)
	v_lshlrev_b32_e32 v69, 16, v67
	v_lshlrev_b32_e32 v68, 16, v66
	v_and_b32_e32 v67, 0xffff0000, v67
	v_and_b32_e32 v66, 0xffff0000, v66
	v_pk_fma_f32 v[70:71], v[70:71], v[72:73], v[68:69] op_sel_hi:[1,0,1] neg_lo:[1,0,0] neg_hi:[1,0,0]
	v_pk_fma_f32 v[68:69], v[12:13], v[72:73], v[66:67] op_sel_hi:[1,0,1] neg_lo:[1,0,0] neg_hi:[1,0,0]
	v_mov_b32_e32 v67, v16
	v_pk_mul_f32 v[10:11], v[68:69], v[68:69]
	v_mov_b32_e32 v16, v15
	v_pk_fma_f32 v[74:75], v[70:71], v[70:71], v[10:11]
	ds_read2st64_b32 v[10:11], v210 offset0:240 offset1:248
	s_load_dword s1, s[50:51], 0xc8
	s_load_dwordx2 s[16:17], s[42:43], 0x60
	v_mov_b32_e32 v66, v14
	s_waitcnt lgkmcnt(0)
; __device__ __forceinline__ void attention_phase(PPtr p, int layer, LAS unsigned char* L, unsigned* counter, const bool do_store) {
;     ...
;                       const float a = bflo(w0) - o[db][2 * i] * inv, c = bfhi(w0) - o[db][2 * i + 1] * inv;
;                       o[db][2 * i] = a; o[db][2 * i + 1] = c; ss += a * a + c * c;
;                   }
;               ss += __shfl_xor(ss, 32);
;               const float rs = rsqrtf(ss * (1.0f / 128.0f) + RMS_EPS) * p->one_minus_lam_init[layer];
;               const float* sg = p->in[12] + (size_t)layer * 128;
;               bf16* orow = QA + (size_t)(q0w + r) * 512;
;               if (do_store)
; #pragma unroll
;               for (int db = 0; db < 4; ++db)
; #pragma unroll
;                   for (int c = 0; c < 4; ++c) {
;                       const int dv = 32 * db + 8 * c + 4 * h;
;                       const f32x4 g4 = *(const f32x4*)(sg + dv);
	v_lshlrev_b32_e32 v13, 16, v11
	v_lshlrev_b32_e32 v12, 16, v10
	v_and_b32_e32 v11, 0xffff0000, v11
	v_and_b32_e32 v10, 0xffff0000, v10
	v_pk_fma_f32 v[14:15], v[16:17], v[72:73], v[10:11] op_sel_hi:[1,0,1] neg_lo:[1,0,0] neg_hi:[1,0,0]
	v_pk_fma_f32 v[66:67], v[66:67], v[72:73], v[12:13] op_sel_hi:[1,0,1] neg_lo:[1,0,0] neg_hi:[1,0,0]
	v_pk_mul_f32 v[10:11], v[14:15], v[14:15]
	s_add_u32 s16, s16, s52
	v_pk_fma_f32 v[16:17], v[66:67], v[66:67], v[10:11]
	v_or_b32_e32 v10, v240, v231
	v_ashrrev_i32_e32 v11, 31, v10
	s_addc_u32 s17, s17, s53
	v_lshlrev_b64 v[10:11], 10, v[10:11]
	v_lshlrev_b32_e32 v73, 4, v230
	v_add_u32_e32 v73, 0x13000, v73
	v_lshl_add_u64 v[132:133], s[14:15], 0, v[10:11]
	ds_read_b128 v[10:13], v73
	v_pk_fma_f32 v[130:131], v[52:53], v[72:73], v[130:131] op_sel_hi:[1,0,1] neg_lo:[1,0,0] neg_hi:[1,0,0]
	v_pk_fma_f32 v[128:129], v[50:51], v[72:73], v[128:129] op_sel_hi:[1,0,1] neg_lo:[1,0,0] neg_hi:[1,0,0]
	v_lshl_add_u64 v[50:51], v[132:133], 0, v[0:1]
	v_pk_fma_f32 v[132:133], v[54:55], v[72:73], v[122:123] op_sel_hi:[1,0,1] neg_lo:[1,0,0] neg_hi:[1,0,0]
	v_pk_fma_f32 v[122:123], v[60:61], v[72:73], v[124:125] op_sel_hi:[1,0,1] neg_lo:[1,0,0] neg_hi:[1,0,0]
	v_pk_fma_f32 v[60:61], v[34:35], v[72:73], v[110:111] op_sel_hi:[1,0,1] neg_lo:[1,0,0] neg_hi:[1,0,0]
	v_pk_fma_f32 v[52:53], v[40:41], v[72:73], v[112:113] op_sel_hi:[1,0,1] neg_lo:[1,0,0] neg_hi:[1,0,0]
	v_pk_fma_f32 v[40:41], v[18:19], v[72:73], v[94:95] op_sel_hi:[1,0,1] neg_lo:[1,0,0] neg_hi:[1,0,0]
	v_pk_fma_f32 v[34:35], v[24:25], v[72:73], v[96:97] op_sel_hi:[1,0,1] neg_lo:[1,0,0] neg_hi:[1,0,0]
	v_pk_fma_f32 v[18:19], v[32:33], v[72:73], v[88:89] op_sel_hi:[1,0,1] neg_lo:[1,0,0] neg_hi:[1,0,0]
	v_pk_fma_f32 v[24:25], v[30:31], v[72:73], v[84:85] op_sel_hi:[1,0,1] neg_lo:[1,0,0] neg_hi:[1,0,0]
	v_mov_b32_e32 v31, v19
	v_mov_b32_e32 v30, v25
	v_pk_fma_f32 v[126:127], v[56:57], v[72:73], v[126:127] op_sel_hi:[1,0,1] neg_lo:[1,0,0] neg_hi:[1,0,0]
	v_pk_fma_f32 v[56:57], v[38:39], v[72:73], v[106:107] op_sel_hi:[1,0,1] neg_lo:[1,0,0] neg_hi:[1,0,0]
	v_pk_fma_f32 v[38:39], v[20:21], v[72:73], v[100:101] op_sel_hi:[1,0,1] neg_lo:[1,0,0] neg_hi:[1,0,0]
	v_mov_b32_e32 v20, v24
	v_mov_b32_e32 v21, v18
	v_pk_mul_f32 v[30:31], v[30:31], v[30:31]
	v_pk_fma_f32 v[4:5], v[4:5], v[72:73], v[82:83] op_sel_hi:[1,0,1] neg_lo:[1,0,0] neg_hi:[1,0,0]
	v_pk_fma_f32 v[30:31], v[20:21], v[20:21], v[30:31]
	v_pk_fma_f32 v[20:21], v[2:3], v[72:73], v[80:81] op_sel_hi:[1,0,1] neg_lo:[1,0,0] neg_hi:[1,0,0]
	v_mov_b32_e32 v33, v5
	v_mov_b32_e32 v32, v21
	s_waitcnt vmcnt(1)
	v_pk_mul_f32 v[134:135], v[130:131], v[130:131]
	v_pk_mul_f32 v[136:137], v[128:129], v[128:129]
	v_mov_b32_e32 v2, v20
	v_mov_b32_e32 v3, v4
	v_pk_mul_f32 v[32:33], v[32:33], v[32:33]
	s_waitcnt vmcnt(0)
	v_pk_mul_f32 v[140:141], v[132:133], v[132:133]
	v_pk_fma_f32 v[118:119], v[58:59], v[72:73], v[118:119] op_sel_hi:[1,0,1] neg_lo:[1,0,0] neg_hi:[1,0,0]
	v_pk_fma_f32 v[64:65], v[64:65], v[72:73], v[120:121] op_sel_hi:[1,0,1] neg_lo:[1,0,0] neg_hi:[1,0,0]
	v_pk_fma_f32 v[62:63], v[62:63], v[72:73], v[114:115] op_sel_hi:[1,0,1] neg_lo:[1,0,0] neg_hi:[1,0,0]
	v_pk_fma_f32 v[58:59], v[36:37], v[72:73], v[116:117] op_sel_hi:[1,0,1] neg_lo:[1,0,0] neg_hi:[1,0,0]
	v_pk_fma_f32 v[44:45], v[44:45], v[72:73], v[108:109] op_sel_hi:[1,0,1] neg_lo:[1,0,0] neg_hi:[1,0,0]
	v_pk_fma_f32 v[54:55], v[42:43], v[72:73], v[102:103] op_sel_hi:[1,0,1] neg_lo:[1,0,0] neg_hi:[1,0,0]
	v_pk_fma_f32 v[42:43], v[48:49], v[72:73], v[104:105] op_sel_hi:[1,0,1] neg_lo:[1,0,0] neg_hi:[1,0,0]
	v_pk_fma_f32 v[46:47], v[46:47], v[72:73], v[98:99] op_sel_hi:[1,0,1] neg_lo:[1,0,0] neg_hi:[1,0,0]
	v_pk_fma_f32 v[36:37], v[22:23], v[72:73], v[90:91] op_sel_hi:[1,0,1] neg_lo:[1,0,0] neg_hi:[1,0,0]
	v_pk_fma_f32 v[22:23], v[28:29], v[72:73], v[92:93] op_sel_hi:[1,0,1] neg_lo:[1,0,0] neg_hi:[1,0,0]
	v_pk_fma_f32 v[26:27], v[26:27], v[72:73], v[86:87] op_sel_hi:[1,0,1] neg_lo:[1,0,0] neg_hi:[1,0,0]
	v_pk_fma_f32 v[32:33], v[2:3], v[2:3], v[32:33]
	v_pk_fma_f32 v[2:3], v[8:9], v[72:73], v[78:79] op_sel_hi:[1,0,1] neg_lo:[1,0,0] neg_hi:[1,0,0]
	v_pk_fma_f32 v[6:7], v[6:7], v[72:73], v[76:77] op_sel_hi:[1,0,1] neg_lo:[1,0,0] neg_hi:[1,0,0]
	v_add_f32_e32 v0, v134, v135
	v_add_f32_e32 v72, v136, v137
	v_pk_mul_f32 v[138:139], v[126:127], v[126:127]
	v_add_f32_e32 v0, v72, v0
	v_add_f32_e32 v72, v140, v141
	v_pk_mul_f32 v[142:143], v[118:119], v[118:119]
	v_add_f32_e32 v0, v0, v72
	v_add_f32_e32 v72, v138, v139
	v_pk_mul_f32 v[124:125], v[122:123], v[122:123]
	v_add_f32_e32 v0, v0, v72
	v_add_f32_e32 v72, v142, v143
	v_pk_mul_f32 v[114:115], v[62:63], v[62:63]
	v_add_f32_e32 v0, v0, v72
	v_add_f32_e32 v72, v124, v125
	v_pk_mul_f32 v[120:121], v[64:65], v[64:65]
	v_add_f32_e32 v0, v0, v72
	v_add_f32_e32 v72, v114, v115
	v_pk_mul_f32 v[110:111], v[60:61], v[60:61]
	v_add_f32_e32 v0, v0, v72
	v_add_f32_e32 v72, v120, v121
	v_pk_mul_f32 v[116:117], v[58:59], v[58:59]
	v_add_f32_e32 v0, v0, v72
	v_add_f32_e32 v72, v110, v111
	v_pk_mul_f32 v[106:107], v[56:57], v[56:57]
	v_add_f32_e32 v0, v0, v72
	v_add_f32_e32 v72, v116, v117
	v_pk_mul_f32 v[112:113], v[52:53], v[52:53]
	v_add_f32_e32 v0, v0, v72
	v_add_f32_e32 v72, v106, v107
	v_pk_mul_f32 v[102:103], v[54:55], v[54:55]
	v_add_f32_e32 v0, v0, v72
	v_add_f32_e32 v72, v112, v113
	v_pk_mul_f32 v[108:109], v[44:45], v[44:45]
	v_add_f32_e32 v0, v0, v72
	v_add_f32_e32 v72, v102, v103
	v_pk_mul_f32 v[98:99], v[46:47], v[46:47]
	v_add_f32_e32 v0, v0, v72
	v_add_f32_e32 v72, v108, v109
	v_pk_mul_f32 v[48:49], v[42:43], v[42:43]
	v_add_f32_e32 v0, v0, v72
	v_add_f32_e32 v72, v98, v99
	v_pk_mul_f32 v[94:95], v[40:41], v[40:41]
	v_add_f32_e32 v0, v0, v72
	v_add_f32_e32 v48, v48, v49
	v_pk_mul_f32 v[100:101], v[38:39], v[38:39]
	v_add_f32_e32 v0, v0, v48
	v_add_f32_e32 v48, v94, v95
	v_pk_mul_f32 v[90:91], v[36:37], v[36:37]
	v_add_f32_e32 v0, v0, v48
	v_add_f32_e32 v48, v100, v101
	v_pk_mul_f32 v[96:97], v[34:35], v[34:35]
	v_add_f32_e32 v0, v0, v48
	v_add_f32_e32 v48, v90, v91
	v_pk_mul_f32 v[86:87], v[26:27], v[26:27]
	v_add_f32_e32 v0, v0, v48
	v_add_f32_e32 v48, v96, v97
	v_pk_mul_f32 v[28:29], v[22:23], v[22:23]
	v_add_f32_e32 v0, v0, v48
	v_add_f32_e32 v48, v86, v87
	v_add_f32_e32 v0, v0, v48
	v_add_f32_e32 v28, v28, v29
	v_add_f32_e32 v0, v0, v28
	v_add_f32_e32 v0, v0, v30
	v_mov_b32_e32 v76, v7
	v_mov_b32_e32 v77, v3
	v_add_f32_e32 v0, v0, v31
	v_mov_b32_e32 v8, v6
	v_mov_b32_e32 v9, v2
	v_pk_mul_f32 v[76:77], v[76:77], v[76:77]
	v_add_f32_e32 v0, v0, v32
	v_pk_fma_f32 v[8:9], v[8:9], v[8:9], v[76:77]
	v_add_f32_e32 v0, v0, v33
	v_add_f32_e32 v0, v0, v8
	v_add_f32_e32 v0, v0, v9
	v_add_f32_e32 v0, v0, v74
	v_add_f32_e32 v0, v0, v75
	v_add_f32_e32 v0, v0, v16
	v_add_f32_e32 v0, v0, v17
	ds_bpermute_b32 v8, v159, v0
	s_waitcnt lgkmcnt(0)
; __device__ __forceinline__ unsigned pk2(float lo, float hi) { f32x2_t v = {lo, hi}; bf16x2_t b = __builtin_convertvector(v, bf16x2_t); return __builtin_bit_cast(unsigned, b); }
; __device__ __forceinline__ void attention_phase(PPtr p, int layer, LAS unsigned char* L, unsigned* counter, const bool do_store) {
;     ...
;               ss += __shfl_xor(ss, 32);
;               const float rs = rsqrtf(ss * (1.0f / 128.0f) + RMS_EPS) * p->one_minus_lam_init[layer];
;               const float* sg = p->in[12] + (size_t)layer * 128;
;               bf16* orow = QA + (size_t)(q0w + r) * 512;
;               if (do_store)
; #pragma unroll
;               for (int db = 0; db < 4; ++db)
; #pragma unroll
;                   for (int c = 0; c < 4; ++c) {
;                       const int dv = 32 * db + 8 * c + 4 * h;
;                       const f32x4 g4 = *(const f32x4*)(sg + dv);
;                       v2u w; w.x = pk2(o[db][4 * c] * rs * g4[0], o[db][4 * c + 1] * rs * g4[1]); w.y = pk2(o[db][4 * c + 2] * rs * g4[2], o[db][4 * c + 3] * rs * g4[3]);
;                       *(v2u*)(orow + dv) = w;
;                   }
	v_add_f32_e32 v0, v0, v8
	v_fmamk_f32 v0, v0, 0x3c000000, v215
	v_cmp_gt_f32_e32 vcc, s2, v0
	v_mul_f32_e32 v8, 0x4b800000, v0
	s_nop 0
	v_cndmask_b32_e32 v0, v0, v8, vcc
	v_rsq_f32_e32 v0, v0
	s_nop 0
	v_mul_f32_e32 v8, 0x45800000, v0
	v_cndmask_b32_e32 v0, v0, v8, vcc
	v_mul_f32_e32 v0, s1, v0
	v_pk_mul_f32 v[8:9], v[128:129], v[0:1] op_sel_hi:[1,0]
	v_pk_mul_f32 v[4:5], v[4:5], v[0:1] op_sel_hi:[1,0]
	s_waitcnt vmcnt(0) lgkmcnt(0)
	v_pk_mul_f32 v[8:9], v[10:11], v[8:9]
	v_pk_mul_f32 v[10:11], v[130:131], v[0:1] op_sel_hi:[1,0]
	v_cvt_pk_bf16_f32 v8, v8, v9
	v_pk_mul_f32 v[10:11], v[12:13], v[10:11]
	v_pk_mul_f32 v[12:13], v[132:133], v[0:1] op_sel_hi:[1,0]
	v_cvt_pk_bf16_f32 v9, v10, v11
	global_store_dwordx2 v[50:51], v[8:9], off
	ds_read_b128 v[8:11], v73 offset:32
	v_pk_mul_f32 v[2:3], v[2:3], v[0:1] op_sel_hi:[1,0]
	s_waitcnt lgkmcnt(0)
	v_pk_mul_f32 v[8:9], v[8:9], v[12:13]
	v_pk_mul_f32 v[12:13], v[126:127], v[0:1] op_sel_hi:[1,0]
	v_cvt_pk_bf16_f32 v8, v8, v9
	v_pk_mul_f32 v[10:11], v[10:11], v[12:13]
	v_pk_mul_f32 v[12:13], v[118:119], v[0:1] op_sel_hi:[1,0]
	v_cvt_pk_bf16_f32 v9, v10, v11
	global_store_dwordx2 v[50:51], v[8:9], off offset:16
	ds_read_b128 v[8:11], v73 offset:64
	s_waitcnt lgkmcnt(0)
	v_pk_mul_f32 v[8:9], v[8:9], v[12:13]
	v_pk_mul_f32 v[12:13], v[122:123], v[0:1] op_sel_hi:[1,0]
	v_cvt_pk_bf16_f32 v8, v8, v9
	v_pk_mul_f32 v[10:11], v[10:11], v[12:13]
	v_pk_mul_f32 v[12:13], v[62:63], v[0:1] op_sel_hi:[1,0]
	v_cvt_pk_bf16_f32 v9, v10, v11
	global_store_dwordx2 v[50:51], v[8:9], off offset:32
	ds_read_b128 v[8:11], v73 offset:96
	s_waitcnt lgkmcnt(0)
	v_pk_mul_f32 v[8:9], v[8:9], v[12:13]
	v_pk_mul_f32 v[12:13], v[64:65], v[0:1] op_sel_hi:[1,0]
	v_cvt_pk_bf16_f32 v8, v8, v9
	v_pk_mul_f32 v[10:11], v[10:11], v[12:13]
	v_pk_mul_f32 v[12:13], v[60:61], v[0:1] op_sel_hi:[1,0]
	v_cvt_pk_bf16_f32 v9, v10, v11
	global_store_dwordx2 v[50:51], v[8:9], off offset:48
	ds_read_b128 v[8:11], v73 offset:128
	s_waitcnt lgkmcnt(0)
	v_pk_mul_f32 v[8:9], v[8:9], v[12:13]
	v_pk_mul_f32 v[12:13], v[58:59], v[0:1] op_sel_hi:[1,0]
	v_cvt_pk_bf16_f32 v8, v8, v9
	v_pk_mul_f32 v[10:11], v[10:11], v[12:13]
	v_pk_mul_f32 v[12:13], v[56:57], v[0:1] op_sel_hi:[1,0]
	v_cvt_pk_bf16_f32 v9, v10, v11
	global_store_dwordx2 v[50:51], v[8:9], off offset:64
	ds_read_b128 v[8:11], v73 offset:160
	s_waitcnt lgkmcnt(0)
	v_pk_mul_f32 v[8:9], v[8:9], v[12:13]
	v_pk_mul_f32 v[12:13], v[52:53], v[0:1] op_sel_hi:[1,0]
	v_cvt_pk_bf16_f32 v8, v8, v9
	v_pk_mul_f32 v[10:11], v[10:11], v[12:13]
	v_pk_mul_f32 v[12:13], v[54:55], v[0:1] op_sel_hi:[1,0]
	v_cvt_pk_bf16_f32 v9, v10, v11
	global_store_dwordx2 v[50:51], v[8:9], off offset:80
	ds_read_b128 v[8:11], v73 offset:192
	s_waitcnt lgkmcnt(0)
	v_pk_mul_f32 v[8:9], v[8:9], v[12:13]
	v_pk_mul_f32 v[12:13], v[44:45], v[0:1] op_sel_hi:[1,0]
	v_cvt_pk_bf16_f32 v8, v8, v9
	v_pk_mul_f32 v[10:11], v[10:11], v[12:13]
	v_pk_mul_f32 v[12:13], v[46:47], v[0:1] op_sel_hi:[1,0]
	v_cvt_pk_bf16_f32 v9, v10, v11
	global_store_dwordx2 v[50:51], v[8:9], off offset:96
	ds_read_b128 v[8:11], v73 offset:224
	s_waitcnt lgkmcnt(0)
	v_pk_mul_f32 v[8:9], v[12:13], v[8:9]
	v_pk_mul_f32 v[12:13], v[42:43], v[0:1] op_sel_hi:[1,0]
	v_cvt_pk_bf16_f32 v8, v8, v9
	v_pk_mul_f32 v[10:11], v[12:13], v[10:11]
	v_pk_mul_f32 v[12:13], v[40:41], v[0:1] op_sel_hi:[1,0]
	v_cvt_pk_bf16_f32 v9, v10, v11
	global_store_dwordx2 v[50:51], v[8:9], off offset:112
	ds_read_b128 v[8:11], v73 offset:256
	s_waitcnt lgkmcnt(0)
	v_pk_mul_f32 v[8:9], v[12:13], v[8:9]
	v_pk_mul_f32 v[12:13], v[38:39], v[0:1] op_sel_hi:[1,0]
	v_cvt_pk_bf16_f32 v8, v8, v9
	v_pk_mul_f32 v[10:11], v[12:13], v[10:11]
	v_pk_mul_f32 v[12:13], v[36:37], v[0:1] op_sel_hi:[1,0]
	v_cvt_pk_bf16_f32 v9, v10, v11
	global_store_dwordx2 v[50:51], v[8:9], off offset:128
	ds_read_b128 v[8:11], v73 offset:288
	s_waitcnt lgkmcnt(0)
	v_pk_mul_f32 v[8:9], v[12:13], v[8:9]
	v_pk_mul_f32 v[12:13], v[34:35], v[0:1] op_sel_hi:[1,0]
	v_cvt_pk_bf16_f32 v8, v8, v9
	v_pk_mul_f32 v[10:11], v[12:13], v[10:11]
	v_pk_mul_f32 v[12:13], v[26:27], v[0:1] op_sel_hi:[1,0]
	v_cvt_pk_bf16_f32 v9, v10, v11
	global_store_dwordx2 v[50:51], v[8:9], off offset:144
	ds_read_b128 v[8:11], v73 offset:320
	s_waitcnt lgkmcnt(0)
	v_pk_mul_f32 v[8:9], v[12:13], v[8:9]
	v_pk_mul_f32 v[12:13], v[22:23], v[0:1] op_sel_hi:[1,0]
	v_cvt_pk_bf16_f32 v8, v8, v9
	v_pk_mul_f32 v[10:11], v[12:13], v[10:11]
	v_pk_mul_f32 v[12:13], v[24:25], v[0:1] op_sel_hi:[1,0]
	v_cvt_pk_bf16_f32 v9, v10, v11
	global_store_dwordx2 v[50:51], v[8:9], off offset:160
	ds_read_b128 v[8:11], v73 offset:352
	s_waitcnt lgkmcnt(0)
	v_pk_mul_f32 v[8:9], v[12:13], v[8:9]
	v_pk_mul_f32 v[12:13], v[18:19], v[0:1] op_sel_hi:[1,0]
	v_cvt_pk_bf16_f32 v8, v8, v9
	v_pk_mul_f32 v[10:11], v[12:13], v[10:11]
	v_pk_mul_f32 v[12:13], v[20:21], v[0:1] op_sel_hi:[1,0]
	v_cvt_pk_bf16_f32 v9, v10, v11
	global_store_dwordx2 v[50:51], v[8:9], off offset:176
	ds_read_b128 v[8:11], v73 offset:384
	s_waitcnt lgkmcnt(0)
	v_pk_mul_f32 v[8:9], v[12:13], v[8:9]
	v_pk_mul_f32 v[4:5], v[4:5], v[10:11]
	v_cvt_pk_bf16_f32 v8, v8, v9
	v_cvt_pk_bf16_f32 v9, v4, v5
	global_store_dwordx2 v[50:51], v[8:9], off offset:192
	ds_read_b128 v[8:11], v73 offset:416
	v_pk_mul_f32 v[4:5], v[6:7], v[0:1] op_sel_hi:[1,0]
	v_mov_b32_e32 v6, v70
	v_mov_b32_e32 v7, v68
	v_pk_mul_f32 v[6:7], v[6:7], v[0:1] op_sel_hi:[1,0]
	v_mov_b32_e32 v68, v71
	s_waitcnt lgkmcnt(0)
	v_pk_mul_f32 v[4:5], v[4:5], v[8:9]
	v_pk_mul_f32 v[2:3], v[2:3], v[10:11]
	v_cvt_pk_bf16_f32 v4, v4, v5
	v_cvt_pk_bf16_f32 v5, v2, v3
	global_store_dwordx2 v[50:51], v[4:5], off offset:208
	ds_read_b128 v[2:5], v73 offset:448
	s_waitcnt lgkmcnt(0)
	v_pk_mul_f32 v[2:3], v[6:7], v[2:3]
	v_pk_mul_f32 v[6:7], v[68:69], v[0:1] op_sel_hi:[1,0]
	v_cvt_pk_bf16_f32 v2, v2, v3
	v_pk_mul_f32 v[4:5], v[6:7], v[4:5]
	v_mov_b32_e32 v6, v66
	v_cvt_pk_bf16_f32 v3, v4, v5
	global_store_dwordx2 v[50:51], v[2:3], off offset:224
	ds_read_b128 v[2:5], v73 offset:480
	v_mov_b32_e32 v7, v14
	v_pk_mul_f32 v[6:7], v[6:7], v[0:1] op_sel_hi:[1,0]
	v_mov_b32_e32 v14, v67
	s_waitcnt lgkmcnt(0)
	v_pk_mul_f32 v[2:3], v[6:7], v[2:3]
	v_pk_mul_f32 v[6:7], v[14:15], v[0:1] op_sel_hi:[1,0]
	v_cvt_pk_bf16_f32 v2, v2, v3
	v_pk_mul_f32 v[4:5], v[6:7], v[4:5]
	s_nop 0
	v_cvt_pk_bf16_f32 v3, v4, v5
	global_store_dwordx2 v[50:51], v[2:3], off offset:240

; template <int KIND  , int DV> ...
;     ...
;     for (int ks = 0; ks < 4; ++ks) qf[ks] = *(const bf16x8*)(Qp + (unsigned)((wave_on ? t : 0) * qpitch + 16 * ks + 8 * h));
;     TileRegs<DV> TA, TB;
;     __syncthreads();
;     tile_load<DV>(TA, Kp, kpitch, Vp, vpitch, t_hi * 64, tid);
;     tile_store<DV>(TA, L + AL_KS0, L + AL_VT0, tid);
;     if (t_hi - 1 >= t_lo) tile_load<DV>(TA, Kp, kpitch, Vp, vpitch, (t_hi - 1) * 64, tid);
; __device__ __forceinline__ void attention_phase(PPtr p, int layer, LAS unsigned char* L, unsigned* counter, const bool do_store) {
;     ...
;             if (tid <= 128) lut[tid] = rel[rel_bucket(tid) * 10 + hd] * LOG2E - bnd;
;             const float* lv = p->in[11] + (size_t)layer * 256;
;             const float lam = expf(wave_sum(lv[lane] * lv[64 + lane])) - expf(wave_sum(lv[128 + lane] * lv[192 + lane])) + p->lam_init[layer];
.LBB0_645:
	s_or_b64 exec, exec, s[14:15]
	s_waitcnt lgkmcnt(0)
	s_barrier
	v_subrev_u32_e32 v6, 0x60, v190
	v_med3_i32 v7, v6, 0, v237
	v_lshl_add_u32 v7, v7, 2, s67
	ds_read_b32 v7, v7
	v_cmp_gt_i32_e32 vcc, 0, v6
	v_lshlrev_b32_e32 v6, 2, v190
	v_add_u32_e32 v6, 0x12800, v6
	s_waitcnt lgkmcnt(0)
	v_cndmask_b32_e32 v7, v7, v238, vcc
	ds_write_b32 v6, v7
	s_waitcnt lgkmcnt(0)
	s_load_dwordx2 s[14:15], s[42:43], 0x60
	v_and_b32_e32 v6, 0x7f, v190
	v_lshlrev_b32_e32 v6, 2, v6
	s_waitcnt lgkmcnt(0)
	s_add_u32 s14, s14, s52
	s_addc_u32 s15, s15, s53
	global_load_dword v7, v6, s[14:15]
	v_add_u32_e32 v6, 0x13000, v6
	s_waitcnt vmcnt(0)
	ds_write_b32 v6, v7
	s_waitcnt lgkmcnt(0)
	s_load_dwordx2 s[14:15], s[42:43], 0x58
	s_lshl_b32 s2, s96, 8
	s_lshr_b32 s9, s2, 6
	s_or_b32 s1, s9, 3
	v_lshlrev_b32_e32 v6, 2, v157
	s_waitcnt lgkmcnt(0)
	s_add_u32 s14, s14, s48
	s_addc_u32 s15, s15, s49
	global_load_dword v7, v6, s[14:15]
	global_load_dword v8, v6, s[14:15] offset:256
	s_lshl_b32 s3, s97, 19
	s_and_b32 s3, s3, 0x1e00000
	v_add_u32_e32 v240, s2, v192
	v_or_b32_e32 v158, v240, v194
	v_lshl_add_u32 v14, s1, 15, v211
	v_mov_b32_e32 v15, v1
	v_lshl_add_u32 v160, s96, 17, v226
	v_lshl_add_u32 v162, s9, 15, v227
	v_or_b32_e32 v243, 31, v240
	v_add_u32_e32 v244, 0xffffff41, v240
	v_add_u32_e32 v245, 0xffffff81, v240
	v_mov_b32_e32 v157, v158
	v_mov_b32_e32 v161, 0
	v_mov_b32_e32 v176, v162
	v_mov_b32_e32 v174, v160
	v_mov_b32_e32 v163, v225
	s_mov_b32 s30, s2
	s_mov_b32 s33, s1
	s_waitcnt vmcnt(0)
	v_mul_f32_e32 v9, v7, v8
	ds_bpermute_b32 v9, v0, v9
	s_waitcnt lgkmcnt(0)
	v_fmac_f32_e32 v9, v7, v8
	ds_bpermute_b32 v7, v2, v9
	s_waitcnt lgkmcnt(0)
	v_add_f32_e32 v7, v9, v7
	ds_bpermute_b32 v8, v3, v7
	s_waitcnt lgkmcnt(0)
	v_add_f32_e32 v7, v7, v8
	ds_bpermute_b32 v8, v4, v7
	s_waitcnt lgkmcnt(0)
	v_add_f32_e32 v7, v7, v8
	ds_bpermute_b32 v8, v5, v7
	s_waitcnt lgkmcnt(0)
	v_add_f32_e32 v7, v7, v8
	ds_bpermute_b32 v8, v159, v7
	s_waitcnt lgkmcnt(0)
	v_add_f32_e32 v7, v7, v8
	v_mul_f32_e32 v8, 0x3fb8aa3b, v7
	v_fma_f32 v9, v7, s70, -v8
	v_rndne_f32_e32 v10, v8
	v_fmac_f32_e32 v9, 0x32a5705f, v7
	v_sub_f32_e32 v8, v8, v10
	v_add_f32_e32 v8, v8, v9
	v_exp_f32_e32 v8, v8
	v_cvt_i32_f32_e32 v9, v10
	v_cmp_ngt_f32_e32 vcc, s72, v7
	v_ldexp_f32 v8, v8, v9
	s_nop 0
	v_cndmask_b32_e32 v8, 0, v8, vcc
	v_cmp_nlt_f32_e32 vcc, s73, v7
	global_load_dword v7, v6, s[14:15] offset:512
	s_nop 0
	global_load_dword v6, v6, s[14:15] offset:768
	v_cndmask_b32_e32 v241, v239, v8, vcc
	v_readlane_b32 s14, v255, 23
	v_readlane_b32 s15, v255, 24
	s_add_u32 s14, s14, s3
	s_addc_u32 s15, s15, 0
	s_lshl_b32 s8, s8, 8
	s_add_u32 s14, s14, s8
	s_addc_u32 s15, s15, 0
	s_add_u32 s16, s90, s3
	s_addc_u32 s17, s91, 0
	s_add_u32 s16, s16, s8
	s_addc_u32 s17, s17, 0
	s_add_u32 s3, s92, s3
	s_addc_u32 s18, s93, 0
	s_add_u32 s20, s3, s8
	s_addc_u32 s21, s18, 0
	s_waitcnt vmcnt(0)
	v_mul_f32_e32 v8, v7, v6
	ds_bpermute_b32 v0, v0, v8
	s_waitcnt lgkmcnt(0)
	v_fmac_f32_e32 v0, v7, v6
	ds_bpermute_b32 v2, v2, v0
	s_waitcnt lgkmcnt(0)
	v_add_f32_e32 v0, v0, v2
	ds_bpermute_b32 v2, v3, v0
	s_waitcnt lgkmcnt(0)
	v_add_f32_e32 v0, v0, v2
	ds_bpermute_b32 v2, v4, v0
	s_waitcnt lgkmcnt(0)
	v_add_f32_e32 v0, v0, v2
	ds_bpermute_b32 v2, v5, v0
	s_waitcnt lgkmcnt(0)
	v_add_f32_e32 v0, v0, v2
	ds_bpermute_b32 v2, v159, v0
	s_waitcnt lgkmcnt(0)
	v_add_f32_e32 v0, v0, v2
	v_mul_f32_e32 v2, 0x3fb8aa3b, v0
	v_fma_f32 v3, v0, s70, -v2
	v_rndne_f32_e32 v4, v2
	v_fmac_f32_e32 v3, 0x32a5705f, v0
	v_sub_f32_e32 v2, v2, v4
	v_add_f32_e32 v2, v2, v3
	v_exp_f32_e32 v2, v2
	v_cvt_i32_f32_e32 v3, v4
	v_cmp_ngt_f32_e32 vcc, s72, v0
	v_ldexp_f32 v2, v2, v3
	s_nop 0
	v_cndmask_b32_e32 v2, 0, v2, vcc
	v_cmp_nlt_f32_e32 vcc, s73, v0
	v_lshl_or_b32 v0, v158, 9, v195
	v_lshl_add_u64 v[164:165], v[0:1], 1, s[14:15]
	v_or_b32_e32 v0, v14, v156
	v_lshlrev_b64 v[6:7], 1, v[0:1]
	v_lshl_add_u64 v[166:167], s[16:17], 0, v[6:7]
	v_lshl_add_u64 v[170:171], s[20:21], 0, v[6:7]
	v_cndmask_b32_e32 v242, v239, v2, vcc
	global_load_dwordx4 v[128:131], v[164:165], off
	global_load_dwordx4 v[132:135], v[164:165], off offset:32
	global_load_dwordx4 v[136:139], v[164:165], off offset:64
	global_load_dwordx4 v[140:143], v[164:165], off offset:96
	s_barrier
	global_load_dwordx4 v[2:5], v[166:167], off
	global_load_dwordx4 v[6:9], v[170:171], off
	global_load_dwordx4 v[10:13], v[170:171], off offset:128
	v_add_u32_e32 v0, v14, v212
	v_mov_b32_e32 v14, v1
	s_waitcnt vmcnt(2)
	ds_write_b128 v197, v[2:5]
	s_waitcnt vmcnt(1)
	ds_write_b128 v229, v[6:9] offset:36864
	s_waitcnt vmcnt(0)
	ds_write_b128 v229, v[10:13] offset:36992
	v_lshlrev_b64 v[2:3], 1, v[0:1]
	v_lshl_add_u64 v[172:173], s[16:17], 0, v[2:3]
	v_lshl_add_u64 v[168:169], s[20:21], 0, v[2:3]
	global_load_dwordx4 v[144:147], v[172:173], off
	global_load_dwordx4 v[148:151], v[168:169], off
	global_load_dwordx4 v[152:155], v[168:169], off offset:128
	v_mov_b32_e32 v0, v1
	v_mov_b32_e32 v2, v1
	v_mov_b32_e32 v3, v1
	v_mov_b32_e32 v4, v1
	v_mov_b32_e32 v5, v1
	v_mov_b32_e32 v6, v1
	v_mov_b32_e32 v7, v1
	v_mov_b32_e32 v8, v1
	v_mov_b32_e32 v9, v1
	v_mov_b32_e32 v10, v1
	v_mov_b32_e32 v11, v1
	v_mov_b32_e32 v12, v1
	v_mov_b32_e32 v13, v1
	v_mov_b64_e32 v[30:31], v[14:15]
	v_mov_b64_e32 v[62:63], v[14:15]
	v_mov_b64_e32 v[78:79], v[14:15]
	v_mov_b64_e32 v[46:47], v[14:15]
	v_mov_b64_e32 v[28:29], v[12:13]
	v_mov_b64_e32 v[26:27], v[10:11]
	v_mov_b64_e32 v[24:25], v[8:9]
	v_mov_b64_e32 v[22:23], v[6:7]
	v_mov_b64_e32 v[20:21], v[4:5]
	v_mov_b64_e32 v[18:19], v[2:3]
	v_mov_b64_e32 v[16:17], v[0:1]
	v_mov_b64_e32 v[60:61], v[12:13]
	v_mov_b64_e32 v[58:59], v[10:11]
	v_mov_b64_e32 v[56:57], v[8:9]
	v_mov_b64_e32 v[54:55], v[6:7]
	v_mov_b64_e32 v[52:53], v[4:5]
	v_mov_b64_e32 v[50:51], v[2:3]
	v_mov_b64_e32 v[48:49], v[0:1]
	v_mov_b64_e32 v[76:77], v[12:13]
	v_mov_b64_e32 v[74:75], v[10:11]
	v_mov_b64_e32 v[72:73], v[8:9]
	v_mov_b64_e32 v[70:71], v[6:7]
	v_mov_b64_e32 v[68:69], v[4:5]
	v_mov_b64_e32 v[66:67], v[2:3]
	v_mov_b64_e32 v[64:65], v[0:1]
	v_mov_b64_e32 v[44:45], v[12:13]
	v_mov_b64_e32 v[42:43], v[10:11]
	v_mov_b64_e32 v[40:41], v[8:9]
	v_mov_b64_e32 v[38:39], v[6:7]
	v_mov_b64_e32 v[36:37], v[4:5]
	v_mov_b64_e32 v[34:35], v[2:3]
	v_mov_b64_e32 v[32:33], v[0:1]
	s_branch .LBB0_647

; template <int KIND>
; __device__ __forceinline__ void softmax_tile(f32x16& s0, f32x16& s1, float& l, int t, int k0, int h, int qlo, const LAS float* lut, const LAS float* cb, int W, int dmask, float rowshift) {
;     ...
; #pragma unroll
;             for (int i = 0; i < 16; ++i) {
;                 const int j0 = k0 + (i & 3) + 8 * (i >> 2) + 4 * h, n0 = t - j0, n1 = n0 - 32;
;                 const float b0 = lut[min(max(n0, 0), 128)], b1 = lut[min(max(n1, 0), 128)];
;                 s0[i] = (n0 >= 0) ? s0[i] + b0 : NINF; s1[i] = (n1 >= 0) ? s1[i] + b1 : NINF;
;             }
.LBB0_653:
	s_andn2_saveexec_b64 s[56:57], s[56:57]
	s_cbranch_execz .LBB0_655
	v_lshlrev_b32_e32 v0, 2, v163
	v_add_u32_e32 v0, 0x12898, v0
	ds_read_b32 v178, v0 offset:108
	ds_read_b32 v179, v0 offset:104
	ds_read_b32 v14, v0 offset:100
	ds_read_b32 v15, v0 offset:96
	ds_read_b32 v182, v0 offset:76
	ds_read_b32 v183, v0 offset:72
	ds_read_b32 v180, v0 offset:68
	ds_read_b32 v181, v0 offset:64
	ds_read_b32 v184, v0 offset:44
	ds_read_b32 v185, v0 offset:40
	ds_read_b32 v186, v0 offset:36
	ds_read_b32 v187, v0 offset:32
	s_waitcnt lgkmcnt(6)
	v_pk_add_f32 v[178:179], v[80:81], v[178:179]
	v_pk_add_f32 v[14:15], v[82:83], v[14:15]
	v_pk_add_f32 v[182:183], v[84:85], v[182:183]
	ds_read_b32 v188, v0 offset:12
	ds_read_b32 v189, v0 offset:8
	ds_read_b32 v175, v0 offset:4
	ds_read_b32 v177, v0 offset:0
	s_waitcnt lgkmcnt(4)
	v_pk_add_f32 v[180:181], v[86:87], v[180:181]
	v_pk_add_f32 v[184:185], v[88:89], v[184:185]
	v_pk_add_f32 v[186:187], v[90:91], v[186:187]
	ds_read_b32 v112, v0 offset:236
	ds_read_b32 v113, v0 offset:232
	ds_read_b32 v114, v0 offset:228
	ds_read_b32 v115, v0 offset:224
	ds_read_b32 v116, v0 offset:204
	ds_read_b32 v117, v0 offset:200
	s_waitcnt lgkmcnt(6)
	v_pk_add_f32 v[188:189], v[92:93], v[188:189]
	v_add_f32_e32 v175, v94, v175
	v_add_f32_e32 v177, v95, v177
	ds_read_b32 v118, v0 offset:196
	ds_read_b32 v119, v0 offset:192
	ds_read_b32 v120, v0 offset:172
	ds_read_b32 v121, v0 offset:168
	ds_read_b32 v122, v0 offset:164
	ds_read_b32 v123, v0 offset:160
	s_waitcnt lgkmcnt(6)
	v_pk_add_f32 v[112:113], v[96:97], v[112:113]
	v_pk_add_f32 v[114:115], v[98:99], v[114:115]
	v_pk_add_f32 v[116:117], v[100:101], v[116:117]
	ds_read_b32 v124, v0 offset:140
	ds_read_b32 v125, v0 offset:136
	ds_read_b32 v126, v0 offset:132
	ds_read_b32 v127, v0 offset:128
	s_waitcnt lgkmcnt(4)
	v_pk_add_f32 v[118:119], v[102:103], v[118:119]
	v_pk_add_f32 v[120:121], v[104:105], v[120:121]
	v_pk_add_f32 v[122:123], v[106:107], v[122:123]
	s_waitcnt lgkmcnt(0)
	v_pk_add_f32 v[124:125], v[108:109], v[124:125]
	v_pk_add_f32 v[126:127], v[110:111], v[126:127]

; template <int KIND>
; __device__ __forceinline__ void softmax_tile(f32x16& s0, f32x16& s1, float& l, int t, int k0, int h, int qlo, const LAS float* lut, const LAS float* cb, int W, int dmask, float rowshift) {
;     ...
; #pragma unroll
;             for (int i = 0; i < 16; ++i) {
;                 const int j0 = k0 + (i & 3) + 8 * (i >> 2) + 4 * h, n0 = t - j0, n1 = n0 - 32;
;                 const float b0 = lut[min(max(n0, 0), 128)], b1 = lut[min(max(n1, 0), 128)];
;                 s0[i] = (n0 >= 0) ? s0[i] + b0 : NINF; s1[i] = (n1 >= 0) ? s1[i] + b1 : NINF;
;             }
.LBB0_664:
	s_andn2_saveexec_b64 s[56:57], s[56:57]
	s_cbranch_execz .LBB0_666
	v_lshlrev_b32_e32 v0, 2, v163
	v_add_u32_e32 v0, 0x12998, v0
	ds_read_b32 v178, v0 offset:108
	ds_read_b32 v179, v0 offset:104
	ds_read_b32 v14, v0 offset:100
	ds_read_b32 v15, v0 offset:96
	ds_read_b32 v182, v0 offset:76
	ds_read_b32 v183, v0 offset:72
	ds_read_b32 v180, v0 offset:68
	ds_read_b32 v181, v0 offset:64
	ds_read_b32 v184, v0 offset:44
	ds_read_b32 v185, v0 offset:40
	ds_read_b32 v186, v0 offset:36
	ds_read_b32 v187, v0 offset:32
	s_waitcnt lgkmcnt(6)
	v_pk_add_f32 v[178:179], v[80:81], v[178:179]
	v_pk_add_f32 v[14:15], v[82:83], v[14:15]
	v_pk_add_f32 v[182:183], v[84:85], v[182:183]
	ds_read_b32 v188, v0 offset:12
	ds_read_b32 v189, v0 offset:8
	ds_read_b32 v175, v0 offset:4
	ds_read_b32 v177, v0 offset:0
	s_waitcnt lgkmcnt(4)
	v_pk_add_f32 v[180:181], v[86:87], v[180:181]
	v_pk_add_f32 v[184:185], v[88:89], v[184:185]
	v_pk_add_f32 v[186:187], v[90:91], v[186:187]
	ds_read_b32 v112, v0 offset:236
	ds_read_b32 v113, v0 offset:232
	ds_read_b32 v114, v0 offset:228
	ds_read_b32 v115, v0 offset:224
	ds_read_b32 v116, v0 offset:204
	ds_read_b32 v117, v0 offset:200
	s_waitcnt lgkmcnt(6)
	v_pk_add_f32 v[188:189], v[92:93], v[188:189]
	v_add_f32_e32 v175, v94, v175
	v_add_f32_e32 v177, v95, v177
	ds_read_b32 v118, v0 offset:196
	ds_read_b32 v119, v0 offset:192
	ds_read_b32 v120, v0 offset:172
	ds_read_b32 v121, v0 offset:168
	ds_read_b32 v122, v0 offset:164
	ds_read_b32 v123, v0 offset:160
	s_waitcnt lgkmcnt(6)
	v_pk_add_f32 v[112:113], v[96:97], v[112:113]
	v_pk_add_f32 v[114:115], v[98:99], v[114:115]
	v_pk_add_f32 v[116:117], v[100:101], v[116:117]
	ds_read_b32 v124, v0 offset:140
	ds_read_b32 v125, v0 offset:136
	ds_read_b32 v126, v0 offset:132
	ds_read_b32 v127, v0 offset:128
	s_waitcnt lgkmcnt(4)
	v_pk_add_f32 v[118:119], v[102:103], v[118:119]
	v_pk_add_f32 v[120:121], v[104:105], v[120:121]
	v_pk_add_f32 v[122:123], v[106:107], v[122:123]
	s_waitcnt lgkmcnt(0)
	v_pk_add_f32 v[124:125], v[108:109], v[124:125]
	v_pk_add_f32 v[126:127], v[110:111], v[126:127]

; template <int KIND>
; __device__ __forceinline__ void softmax_tile(f32x16& s0, f32x16& s1, float& l, int t, int k0, int h, int qlo, const LAS float* lut, const LAS float* cb, int W, int dmask, float rowshift) {
;     ...
; #pragma unroll
;             for (int i = 0; i < 16; ++i) {
;                 const int j0 = k0 + (i & 3) + 8 * (i >> 2) + 4 * h, n0 = t - j0, n1 = n0 - 32;
;                 const float b0 = lut[min(max(n0, 0), 128)], b1 = lut[min(max(n1, 0), 128)];
;                 s0[i] = (n0 >= 0) ? s0[i] + b0 : NINF; s1[i] = (n1 >= 0) ? s1[i] + b1 : NINF;
;             }
.LBB0_675:
	s_andn2_saveexec_b64 s[56:57], s[56:57]
	s_cbranch_execz .LBB0_677
	v_lshlrev_b32_e32 v0, 2, v177
	v_add_u32_e32 v0, 0x12898, v0
	ds_read_b32 v164, v0 offset:108
	ds_read_b32 v165, v0 offset:104
	ds_read_b32 v154, v0 offset:100
	ds_read_b32 v155, v0 offset:96
	ds_read_b32 v168, v0 offset:76
	ds_read_b32 v169, v0 offset:72
	ds_read_b32 v166, v0 offset:68
	ds_read_b32 v167, v0 offset:64
	ds_read_b32 v170, v0 offset:44
	ds_read_b32 v171, v0 offset:40
	ds_read_b32 v172, v0 offset:36
	ds_read_b32 v173, v0 offset:32
	s_waitcnt lgkmcnt(6)
	v_pk_add_f32 v[164:165], v[66:67], v[164:165]
	v_pk_add_f32 v[154:155], v[68:69], v[154:155]
	v_pk_add_f32 v[168:169], v[70:71], v[168:169]
	ds_read_b32 v174, v0 offset:12
	ds_read_b32 v175, v0 offset:8
	ds_read_b32 v161, v0 offset:4
	ds_read_b32 v163, v0 offset:0
	s_waitcnt lgkmcnt(4)
	v_pk_add_f32 v[166:167], v[72:73], v[166:167]
	v_pk_add_f32 v[170:171], v[74:75], v[170:171]
	v_pk_add_f32 v[172:173], v[76:77], v[172:173]
	ds_read_b32 v98, v0 offset:236
	ds_read_b32 v99, v0 offset:232
	ds_read_b32 v100, v0 offset:228
	ds_read_b32 v101, v0 offset:224
	ds_read_b32 v102, v0 offset:204
	ds_read_b32 v103, v0 offset:200
	s_waitcnt lgkmcnt(6)
	v_pk_add_f32 v[174:175], v[78:79], v[174:175]
	v_add_f32_e32 v161, v80, v161
	v_add_f32_e32 v163, v81, v163
	ds_read_b32 v104, v0 offset:196
	ds_read_b32 v105, v0 offset:192
	ds_read_b32 v106, v0 offset:172
	ds_read_b32 v107, v0 offset:168
	ds_read_b32 v108, v0 offset:164
	ds_read_b32 v109, v0 offset:160
	s_waitcnt lgkmcnt(6)
	v_pk_add_f32 v[98:99], v[82:83], v[98:99]
	v_pk_add_f32 v[100:101], v[84:85], v[100:101]
	v_pk_add_f32 v[102:103], v[86:87], v[102:103]
	ds_read_b32 v110, v0 offset:140
	ds_read_b32 v111, v0 offset:136
	ds_read_b32 v112, v0 offset:132
	ds_read_b32 v113, v0 offset:128
	s_waitcnt lgkmcnt(4)
	v_pk_add_f32 v[104:105], v[88:89], v[104:105]
	v_pk_add_f32 v[106:107], v[90:91], v[106:107]
	v_pk_add_f32 v[108:109], v[92:93], v[108:109]
	s_waitcnt lgkmcnt(0)
	v_pk_add_f32 v[110:111], v[94:95], v[110:111]
	v_pk_add_f32 v[112:113], v[96:97], v[112:113]

; template <int KIND>
; __device__ __forceinline__ void softmax_tile(f32x16& s0, f32x16& s1, float& l, int t, int k0, int h, int qlo, const LAS float* lut, const LAS float* cb, int W, int dmask, float rowshift) {
;     ...
; #pragma unroll
;             for (int i = 0; i < 16; ++i) {
;                 const int j0 = k0 + (i & 3) + 8 * (i >> 2) + 4 * h, n0 = t - j0, n1 = n0 - 32;
;                 const float b0 = lut[min(max(n0, 0), 128)], b1 = lut[min(max(n1, 0), 128)];
;                 s0[i] = (n0 >= 0) ? s0[i] + b0 : NINF; s1[i] = (n1 >= 0) ? s1[i] + b1 : NINF;
;             }
.LBB0_686:
	s_andn2_saveexec_b64 s[56:57], s[56:57]
	s_cbranch_execz .LBB0_688
	v_lshlrev_b32_e32 v0, 2, v177
	v_add_u32_e32 v0, 0x12998, v0
	ds_read_b32 v164, v0 offset:108
	ds_read_b32 v165, v0 offset:104
	ds_read_b32 v154, v0 offset:100
	ds_read_b32 v155, v0 offset:96
	ds_read_b32 v168, v0 offset:76
	ds_read_b32 v169, v0 offset:72
	ds_read_b32 v166, v0 offset:68
	ds_read_b32 v167, v0 offset:64
	ds_read_b32 v170, v0 offset:44
	ds_read_b32 v171, v0 offset:40
	ds_read_b32 v172, v0 offset:36
	ds_read_b32 v173, v0 offset:32
	s_waitcnt lgkmcnt(6)
	v_pk_add_f32 v[164:165], v[66:67], v[164:165]
	v_pk_add_f32 v[154:155], v[68:69], v[154:155]
	v_pk_add_f32 v[168:169], v[70:71], v[168:169]
	ds_read_b32 v174, v0 offset:12
	ds_read_b32 v175, v0 offset:8
	ds_read_b32 v161, v0 offset:4
	ds_read_b32 v163, v0 offset:0
	s_waitcnt lgkmcnt(4)
	v_pk_add_f32 v[166:167], v[72:73], v[166:167]
	v_pk_add_f32 v[170:171], v[74:75], v[170:171]
	v_pk_add_f32 v[172:173], v[76:77], v[172:173]
	ds_read_b32 v98, v0 offset:236
	ds_read_b32 v99, v0 offset:232
	ds_read_b32 v100, v0 offset:228
	ds_read_b32 v101, v0 offset:224
	ds_read_b32 v102, v0 offset:204
	ds_read_b32 v103, v0 offset:200
	s_waitcnt lgkmcnt(6)
	v_pk_add_f32 v[174:175], v[78:79], v[174:175]
	v_add_f32_e32 v161, v80, v161
	v_add_f32_e32 v163, v81, v163
	ds_read_b32 v104, v0 offset:196
	ds_read_b32 v105, v0 offset:192
	ds_read_b32 v106, v0 offset:172
	ds_read_b32 v107, v0 offset:168
	ds_read_b32 v108, v0 offset:164
	ds_read_b32 v109, v0 offset:160
	s_waitcnt lgkmcnt(6)
	v_pk_add_f32 v[98:99], v[82:83], v[98:99]
	v_pk_add_f32 v[100:101], v[84:85], v[100:101]
	v_pk_add_f32 v[102:103], v[86:87], v[102:103]
	ds_read_b32 v110, v0 offset:140
	ds_read_b32 v111, v0 offset:136
	ds_read_b32 v112, v0 offset:132
	ds_read_b32 v113, v0 offset:128
	s_waitcnt lgkmcnt(4)
	v_pk_add_f32 v[104:105], v[88:89], v[104:105]
	v_pk_add_f32 v[106:107], v[90:91], v[106:107]
	v_pk_add_f32 v[108:109], v[92:93], v[108:109]
	s_waitcnt lgkmcnt(0)
	v_pk_add_f32 v[110:111], v[94:95], v[110:111]
	v_pk_add_f32 v[112:113], v[96:97], v[112:113]
